# YIELD-8: one more s_setprio 0/1 yield point in the middle of every 16-MFMA block of the GEMM K-loops (on REL-FIRST)
# speedup vs baseline: 1.0026x; 1.0026x over previous
.LBB0_212:
	s_ashr_i32 s27, s26, 31
	s_lshl_b64 s[30:31], s[26:27], 19
	s_ashr_i32 s25, s24, 31
	v_lshl_add_u64 v[148:149], v[130:131], 0, s[30:31]
	s_lshl_b64 s[30:31], s[24:25], 19
	v_lshl_add_u64 v[150:151], v[132:133], 0, s[30:31]
	v_cndmask_b32_e64 v152, v2, v150, s[4:5]
	v_lshl_add_u64 v[156:157], v[2:3], 0, s[20:21]
	v_mov_b32_e32 v2, 0
	v_cndmask_b32_e64 v1, v5, v149, s[4:5]
	v_cndmask_b32_e64 v138, v4, v148, s[4:5]
	v_cndmask_b32_e64 v153, v3, v151, s[4:5]
	v_lshl_add_u64 v[154:155], v[4:5], 0, s[16:17]
	s_mov_b32 s7, -2
	ds_read_b128 v[168:171], v160
	ds_read_b128 v[172:175], v160 offset:1024
	ds_read_b128 v[176:179], v160 offset:2048
	ds_read_b128 v[180:183], v160 offset:3072
	ds_read_b128 v[184:187], v161
	ds_read_b128 v[188:191], v161 offset:1024
	ds_read_b128 v[192:195], v161 offset:2048
	ds_read_b128 v[196:199], v161 offset:3072
	s_cmp_eq_u32 s7, 12
	v_lshl_add_u64 v[200:201], v[154:155], 0, s[22:23]
	s_cselect_b64 vcc, -1, 0
	v_cndmask_b32_e32 v233, v201, v1, vcc
	v_cndmask_b32_e32 v232, v200, v138, vcc
	v_cndmask_b32_e32 v235, v157, v153, vcc
	v_cndmask_b32_e32 v234, v156, v152, vcc
	s_mov_b32 m0, s42
	v_lshl_add_u64 v[236:237], v[154:155], 0, v[140:141]
	ds_read_b128 v[200:203], v162
	ds_read_b128 v[204:207], v162 offset:1024
	ds_read_b128 v[208:211], v162 offset:2048
	ds_read_b128 v[212:215], v162 offset:3072
	ds_read_b128 v[216:219], v162 offset:4096
	ds_read_b128 v[220:223], v162 offset:5120
	ds_read_b128 v[224:227], v162 offset:6144
	ds_read_b128 v[228:231], v162 offset:7168
	global_load_lds_dwordx4 v[236:237], off
	v_lshl_add_u64 v[236:237], v[154:155], 0, v[142:143]
	s_mov_b32 m0, s43
	s_nop 0
	global_load_lds_dwordx4 v[236:237], off
	s_waitcnt vmcnt(8)
	s_waitcnt lgkmcnt(0)
	s_barrier
	s_setprio 1
	s_waitcnt lgkmcnt(0)
	v_mfma_f32_16x16x32_bf16 v[126:129], v[168:171], v[200:203], 0
	v_mfma_f32_16x16x32_bf16 v[122:125], v[176:179], v[200:203], 0
	v_mfma_f32_16x16x32_bf16 v[110:113], v[168:171], v[208:211], 0
	v_mfma_f32_16x16x32_bf16 v[106:109], v[176:179], v[208:211], 0
	v_mfma_f32_16x16x32_bf16 v[94:97], v[168:171], v[216:219], 0
	v_mfma_f32_16x16x32_bf16 v[90:93], v[176:179], v[216:219], 0
	v_mfma_f32_16x16x32_bf16 v[78:81], v[168:171], v[224:227], 0
	v_mfma_f32_16x16x32_bf16 v[74:77], v[176:179], v[224:227], 0
	s_setprio 0
	s_setprio 1
	v_mfma_f32_16x16x32_bf16 v[126:129], v[172:175], v[204:207], v[126:129]
	v_mfma_f32_16x16x32_bf16 v[122:125], v[180:183], v[204:207], v[122:125]
	v_mfma_f32_16x16x32_bf16 v[110:113], v[172:175], v[212:215], v[110:113]
	v_mfma_f32_16x16x32_bf16 v[106:109], v[180:183], v[212:215], v[106:109]
	v_mfma_f32_16x16x32_bf16 v[94:97], v[172:175], v[220:223], v[94:97]
	v_mfma_f32_16x16x32_bf16 v[90:93], v[180:183], v[220:223], v[90:93]
	v_mfma_f32_16x16x32_bf16 v[78:81], v[172:175], v[228:231], v[78:81]
	v_mfma_f32_16x16x32_bf16 v[74:77], v[180:183], v[228:231], v[74:77]
	s_setprio 0
	s_setprio 1
	v_mfma_f32_16x16x32_bf16 v[118:121], v[184:187], v[200:203], 0
	v_mfma_f32_16x16x32_bf16 v[114:117], v[192:195], v[200:203], 0
	v_mfma_f32_16x16x32_bf16 v[102:105], v[184:187], v[208:211], 0
	v_mfma_f32_16x16x32_bf16 v[98:101], v[192:195], v[208:211], 0
	v_mfma_f32_16x16x32_bf16 v[86:89], v[184:187], v[216:219], 0
	v_mfma_f32_16x16x32_bf16 v[82:85], v[192:195], v[216:219], 0
	v_mfma_f32_16x16x32_bf16 v[70:73], v[184:187], v[224:227], 0
	v_mfma_f32_16x16x32_bf16 v[66:69], v[192:195], v[224:227], 0
	s_setprio 0
	s_setprio 1
	v_mfma_f32_16x16x32_bf16 v[118:121], v[188:191], v[204:207], v[118:121]
	v_mfma_f32_16x16x32_bf16 v[114:117], v[196:199], v[204:207], v[114:117]
	v_mfma_f32_16x16x32_bf16 v[102:105], v[188:191], v[212:215], v[102:105]
	v_mfma_f32_16x16x32_bf16 v[98:101], v[196:199], v[212:215], v[98:101]
	v_mfma_f32_16x16x32_bf16 v[86:89], v[188:191], v[220:223], v[86:89]
	v_mfma_f32_16x16x32_bf16 v[82:85], v[196:199], v[220:223], v[82:85]
	v_mfma_f32_16x16x32_bf16 v[70:73], v[188:191], v[228:231], v[70:73]
	v_mfma_f32_16x16x32_bf16 v[66:69], v[196:199], v[228:231], v[66:69]
	s_setprio 0
	s_barrier
	s_mov_b32 m0, s44
	v_lshl_add_u64 v[236:237], v[234:235], 0, v[134:135]
	ds_read_b128 v[200:203], v162 offset:16384
	ds_read_b128 v[204:207], v162 offset:17408
	ds_read_b128 v[208:211], v162 offset:18432
	ds_read_b128 v[212:215], v162 offset:19456
	ds_read_b128 v[216:219], v162 offset:20480
	ds_read_b128 v[220:223], v162 offset:21504
	ds_read_b128 v[224:227], v162 offset:22528
	ds_read_b128 v[228:231], v162 offset:23552
	global_load_lds_dwordx4 v[236:237], off
	v_lshl_add_u64 v[238:239], v[234:235], 0, v[136:137]
	s_mov_b32 m0, s45
	v_lshl_add_u64 v[240:241], v[234:235], 0, s[10:11]
	global_load_lds_dwordx4 v[238:239], off
	v_lshl_add_u64 v[242:243], v[240:241], 0, v[134:135]
	s_mov_b32 m0, s46
	v_lshl_add_u64 v[240:241], v[240:241], 0, v[136:137]
	global_load_lds_dwordx4 v[242:243], off
	s_mov_b32 m0, s47
	v_lshl_add_u64 v[242:243], v[232:233], 0, v[136:137]
	global_load_lds_dwordx4 v[240:241], off
	v_lshl_add_u64 v[240:241], v[232:233], 0, v[134:135]
	s_mov_b32 m0, s0
	s_nop 0
	global_load_lds_dwordx4 v[240:241], off
	s_mov_b32 m0, s1
	s_nop 0
	global_load_lds_dwordx4 v[242:243], off
	s_waitcnt vmcnt(8)
	s_waitcnt lgkmcnt(0)
	s_barrier
	s_setprio 1
	s_waitcnt lgkmcnt(0)
	v_mfma_f32_16x16x32_bf16 v[62:65], v[168:171], v[200:203], 0
	v_mfma_f32_16x16x32_bf16 v[58:61], v[176:179], v[200:203], 0
	v_mfma_f32_16x16x32_bf16 v[46:49], v[168:171], v[208:211], 0
	v_mfma_f32_16x16x32_bf16 v[42:45], v[176:179], v[208:211], 0
	v_mfma_f32_16x16x32_bf16 v[30:33], v[168:171], v[216:219], 0
	v_mfma_f32_16x16x32_bf16 v[26:29], v[176:179], v[216:219], 0
	v_mfma_f32_16x16x32_bf16 v[14:17], v[168:171], v[224:227], 0
	v_mfma_f32_16x16x32_bf16 v[10:13], v[176:179], v[224:227], 0
	s_setprio 0
	s_setprio 1
	v_mfma_f32_16x16x32_bf16 v[62:65], v[172:175], v[204:207], v[62:65]
	v_mfma_f32_16x16x32_bf16 v[58:61], v[180:183], v[204:207], v[58:61]
	v_mfma_f32_16x16x32_bf16 v[46:49], v[172:175], v[212:215], v[46:49]
	v_mfma_f32_16x16x32_bf16 v[42:45], v[180:183], v[212:215], v[42:45]
	v_mfma_f32_16x16x32_bf16 v[30:33], v[172:175], v[220:223], v[30:33]
	v_mfma_f32_16x16x32_bf16 v[26:29], v[180:183], v[220:223], v[26:29]
	v_mfma_f32_16x16x32_bf16 v[14:17], v[172:175], v[228:231], v[14:17]
	v_mfma_f32_16x16x32_bf16 v[10:13], v[180:183], v[228:231], v[10:13]
	s_setprio 0
	s_setprio 1
	v_mfma_f32_16x16x32_bf16 v[54:57], v[184:187], v[200:203], 0
	v_mfma_f32_16x16x32_bf16 v[50:53], v[192:195], v[200:203], 0
	v_mfma_f32_16x16x32_bf16 v[38:41], v[184:187], v[208:211], 0
	v_mfma_f32_16x16x32_bf16 v[34:37], v[192:195], v[208:211], 0
	v_mfma_f32_16x16x32_bf16 v[22:25], v[184:187], v[216:219], 0
	v_mfma_f32_16x16x32_bf16 v[18:21], v[192:195], v[216:219], 0
	v_mfma_f32_16x16x32_bf16 v[6:9], v[184:187], v[224:227], 0
	v_mfma_f32_16x16x32_bf16 v[2:5], v[192:195], v[224:227], 0
	s_setprio 0
	s_setprio 1
	v_mfma_f32_16x16x32_bf16 v[54:57], v[188:191], v[204:207], v[54:57]
	v_mfma_f32_16x16x32_bf16 v[50:53], v[196:199], v[204:207], v[50:53]
	v_mfma_f32_16x16x32_bf16 v[38:41], v[188:191], v[212:215], v[38:41]
	v_mfma_f32_16x16x32_bf16 v[34:37], v[196:199], v[212:215], v[34:37]
	v_mfma_f32_16x16x32_bf16 v[22:25], v[188:191], v[220:223], v[22:25]
	v_mfma_f32_16x16x32_bf16 v[18:21], v[196:199], v[220:223], v[18:21]
	v_mfma_f32_16x16x32_bf16 v[6:9], v[188:191], v[228:231], v[6:9]
	v_mfma_f32_16x16x32_bf16 v[2:5], v[196:199], v[228:231], v[2:5]
	s_setprio 0
	s_barrier
	ds_read_b128 v[168:171], v163
	ds_read_b128 v[172:175], v163 offset:1024
	ds_read_b128 v[176:179], v163 offset:2048
	ds_read_b128 v[180:183], v163 offset:3072
	ds_read_b128 v[184:187], v164
	ds_read_b128 v[188:191], v164 offset:1024
	ds_read_b128 v[192:195], v164 offset:2048
	ds_read_b128 v[196:199], v164 offset:3072
	v_lshl_add_u64 v[232:233], v[232:233], 0, s[10:11]
	s_mov_b32 m0, s2
	v_lshl_add_u64 v[244:245], v[232:233], 0, v[134:135]
	ds_read_b128 v[200:203], v162 offset:32768
	ds_read_b128 v[204:207], v162 offset:33792
	ds_read_b128 v[208:211], v162 offset:34816
	ds_read_b128 v[212:215], v162 offset:35840
	ds_read_b128 v[216:219], v162 offset:36864
	ds_read_b128 v[220:223], v162 offset:37888
	ds_read_b128 v[224:227], v162 offset:38912
	ds_read_b128 v[228:231], v162 offset:39936
	global_load_lds_dwordx4 v[244:245], off
	v_lshl_add_u64 v[232:233], v[232:233], 0, v[136:137]
	s_mov_b32 m0, s3
	s_nop 0
	global_load_lds_dwordx4 v[232:233], off
	s_waitcnt vmcnt(8)
	s_waitcnt lgkmcnt(0)
	s_barrier
	s_setprio 1
	s_waitcnt lgkmcnt(0)
	v_mfma_f32_16x16x32_bf16 v[126:129], v[168:171], v[200:203], v[126:129]
	v_mfma_f32_16x16x32_bf16 v[122:125], v[176:179], v[200:203], v[122:125]
	v_mfma_f32_16x16x32_bf16 v[110:113], v[168:171], v[208:211], v[110:113]
	v_mfma_f32_16x16x32_bf16 v[106:109], v[176:179], v[208:211], v[106:109]
	v_mfma_f32_16x16x32_bf16 v[94:97], v[168:171], v[216:219], v[94:97]
	v_mfma_f32_16x16x32_bf16 v[90:93], v[176:179], v[216:219], v[90:93]
	v_mfma_f32_16x16x32_bf16 v[78:81], v[168:171], v[224:227], v[78:81]
	v_mfma_f32_16x16x32_bf16 v[74:77], v[176:179], v[224:227], v[74:77]
	s_setprio 0
	s_setprio 1
	v_mfma_f32_16x16x32_bf16 v[126:129], v[172:175], v[204:207], v[126:129]
	v_mfma_f32_16x16x32_bf16 v[122:125], v[180:183], v[204:207], v[122:125]
	v_mfma_f32_16x16x32_bf16 v[110:113], v[172:175], v[212:215], v[110:113]
	v_mfma_f32_16x16x32_bf16 v[106:109], v[180:183], v[212:215], v[106:109]
	v_mfma_f32_16x16x32_bf16 v[94:97], v[172:175], v[220:223], v[94:97]
	v_mfma_f32_16x16x32_bf16 v[90:93], v[180:183], v[220:223], v[90:93]
	v_mfma_f32_16x16x32_bf16 v[78:81], v[172:175], v[228:231], v[78:81]
	v_mfma_f32_16x16x32_bf16 v[74:77], v[180:183], v[228:231], v[74:77]
	s_setprio 0
	s_setprio 1
	v_mfma_f32_16x16x32_bf16 v[118:121], v[184:187], v[200:203], v[118:121]
	v_mfma_f32_16x16x32_bf16 v[114:117], v[192:195], v[200:203], v[114:117]
	v_mfma_f32_16x16x32_bf16 v[102:105], v[184:187], v[208:211], v[102:105]
	v_mfma_f32_16x16x32_bf16 v[98:101], v[192:195], v[208:211], v[98:101]
	v_mfma_f32_16x16x32_bf16 v[86:89], v[184:187], v[216:219], v[86:89]
	v_mfma_f32_16x16x32_bf16 v[82:85], v[192:195], v[216:219], v[82:85]
	v_mfma_f32_16x16x32_bf16 v[70:73], v[184:187], v[224:227], v[70:73]
	v_mfma_f32_16x16x32_bf16 v[66:69], v[192:195], v[224:227], v[66:69]
	s_setprio 0
	s_setprio 1
	v_mfma_f32_16x16x32_bf16 v[118:121], v[188:191], v[204:207], v[118:121]
	v_mfma_f32_16x16x32_bf16 v[114:117], v[196:199], v[204:207], v[114:117]
	v_mfma_f32_16x16x32_bf16 v[102:105], v[188:191], v[212:215], v[102:105]
	v_mfma_f32_16x16x32_bf16 v[98:101], v[196:199], v[212:215], v[98:101]
	v_mfma_f32_16x16x32_bf16 v[86:89], v[188:191], v[220:223], v[86:89]
	v_mfma_f32_16x16x32_bf16 v[82:85], v[196:199], v[220:223], v[82:85]
	v_mfma_f32_16x16x32_bf16 v[70:73], v[188:191], v[228:231], v[70:73]
	v_mfma_f32_16x16x32_bf16 v[66:69], v[196:199], v[228:231], v[66:69]
	s_setprio 0
	s_barrier
	s_mov_b32 m0, s48
	v_lshl_add_u64 v[232:233], v[236:237], 0, s[14:15]
	ds_read_b128 v[200:203], v162 offset:49152
	ds_read_b128 v[204:207], v162 offset:50176
	ds_read_b128 v[208:211], v162 offset:51200
	ds_read_b128 v[212:215], v162 offset:52224
	ds_read_b128 v[216:219], v162 offset:53248
	ds_read_b128 v[220:223], v162 offset:54272
	ds_read_b128 v[224:227], v162 offset:55296
	ds_read_b128 v[228:231], v162 offset:56320
	global_load_lds_dwordx4 v[232:233], off
	v_lshl_add_u64 v[232:233], v[238:239], 0, s[14:15]
	s_mov_b32 m0, s51
	s_nop 0
	global_load_lds_dwordx4 v[232:233], off
	v_lshl_add_u64 v[232:233], v[234:235], 0, s[16:17]
	v_lshl_add_u64 v[234:235], v[232:233], 0, v[134:135]
	s_mov_b32 m0, s52
	v_lshl_add_u64 v[232:233], v[232:233], 0, v[136:137]
	global_load_lds_dwordx4 v[234:235], off
	s_add_i32 m0, s52, 0x2000
	s_nop 0
	global_load_lds_dwordx4 v[232:233], off
	v_lshl_add_u64 v[232:233], v[240:241], 0, s[14:15]
	s_mov_b32 m0, s34
	s_nop 0
	global_load_lds_dwordx4 v[232:233], off
	v_lshl_add_u64 v[232:233], v[242:243], 0, s[14:15]
	s_mov_b32 m0, s35
	s_nop 0
	global_load_lds_dwordx4 v[232:233], off
	s_waitcnt vmcnt(8)
	s_waitcnt lgkmcnt(0)
	s_barrier
	s_setprio 1
	s_waitcnt lgkmcnt(0)
	v_mfma_f32_16x16x32_bf16 v[62:65], v[168:171], v[200:203], v[62:65]
	v_mfma_f32_16x16x32_bf16 v[58:61], v[176:179], v[200:203], v[58:61]
	v_mfma_f32_16x16x32_bf16 v[46:49], v[168:171], v[208:211], v[46:49]
	v_mfma_f32_16x16x32_bf16 v[42:45], v[176:179], v[208:211], v[42:45]
	v_mfma_f32_16x16x32_bf16 v[30:33], v[168:171], v[216:219], v[30:33]
	v_mfma_f32_16x16x32_bf16 v[26:29], v[176:179], v[216:219], v[26:29]
	v_mfma_f32_16x16x32_bf16 v[14:17], v[168:171], v[224:227], v[14:17]
	v_mfma_f32_16x16x32_bf16 v[10:13], v[176:179], v[224:227], v[10:13]
	s_setprio 0
	s_setprio 1
	v_mfma_f32_16x16x32_bf16 v[62:65], v[172:175], v[204:207], v[62:65]
	v_mfma_f32_16x16x32_bf16 v[58:61], v[180:183], v[204:207], v[58:61]
	v_mfma_f32_16x16x32_bf16 v[46:49], v[172:175], v[212:215], v[46:49]
	v_mfma_f32_16x16x32_bf16 v[42:45], v[180:183], v[212:215], v[42:45]
	v_mfma_f32_16x16x32_bf16 v[30:33], v[172:175], v[220:223], v[30:33]
	v_mfma_f32_16x16x32_bf16 v[26:29], v[180:183], v[220:223], v[26:29]
	v_mfma_f32_16x16x32_bf16 v[14:17], v[172:175], v[228:231], v[14:17]
	v_mfma_f32_16x16x32_bf16 v[10:13], v[180:183], v[228:231], v[10:13]
	s_setprio 0
	s_setprio 1
	v_mfma_f32_16x16x32_bf16 v[54:57], v[184:187], v[200:203], v[54:57]
	v_mfma_f32_16x16x32_bf16 v[50:53], v[192:195], v[200:203], v[50:53]
	v_mfma_f32_16x16x32_bf16 v[38:41], v[184:187], v[208:211], v[38:41]
	v_mfma_f32_16x16x32_bf16 v[34:37], v[192:195], v[208:211], v[34:37]
	v_mfma_f32_16x16x32_bf16 v[22:25], v[184:187], v[216:219], v[22:25]
	v_mfma_f32_16x16x32_bf16 v[18:21], v[192:195], v[216:219], v[18:21]
	v_mfma_f32_16x16x32_bf16 v[6:9], v[184:187], v[224:227], v[6:9]
	v_mfma_f32_16x16x32_bf16 v[2:5], v[192:195], v[224:227], v[2:5]
	s_setprio 0
	s_setprio 1
	v_mfma_f32_16x16x32_bf16 v[54:57], v[188:191], v[204:207], v[54:57]
	v_mfma_f32_16x16x32_bf16 v[50:53], v[196:199], v[204:207], v[50:53]
	v_mfma_f32_16x16x32_bf16 v[38:41], v[188:191], v[212:215], v[38:41]
	v_mfma_f32_16x16x32_bf16 v[34:37], v[196:199], v[212:215], v[34:37]
	v_mfma_f32_16x16x32_bf16 v[22:25], v[188:191], v[220:223], v[22:25]
	v_mfma_f32_16x16x32_bf16 v[18:21], v[196:199], v[220:223], v[18:21]
	v_mfma_f32_16x16x32_bf16 v[6:9], v[188:191], v[228:231], v[6:9]
	v_mfma_f32_16x16x32_bf16 v[2:5], v[196:199], v[228:231], v[2:5]
	s_setprio 0
	s_barrier
	s_add_i32 s7, s7, 2
	v_lshl_add_u64 v[154:155], v[154:155], 0, s[20:21]
	s_cmp_gt_u32 s7, 13
	v_lshl_add_u64 v[156:157], v[156:157], 0, s[20:21]
	s_cbranch_scc0 .LBB0_213
	s_branch .Lpeel_exit_1
.LBB0_213:
	ds_read_b128 v[168:171], v160
	ds_read_b128 v[172:175], v160 offset:1024
	ds_read_b128 v[176:179], v160 offset:2048
	ds_read_b128 v[180:183], v160 offset:3072
	ds_read_b128 v[184:187], v161
	ds_read_b128 v[188:191], v161 offset:1024
	ds_read_b128 v[192:195], v161 offset:2048
	ds_read_b128 v[196:199], v161 offset:3072
	s_cmp_eq_u32 s7, 12
	v_lshl_add_u64 v[200:201], v[154:155], 0, s[22:23]
	s_cselect_b64 vcc, -1, 0
	v_cndmask_b32_e32 v233, v201, v1, vcc
	v_cndmask_b32_e32 v232, v200, v138, vcc
	v_cndmask_b32_e32 v235, v157, v153, vcc
	v_cndmask_b32_e32 v234, v156, v152, vcc
	s_mov_b32 m0, s42
	v_lshl_add_u64 v[236:237], v[154:155], 0, v[140:141]
	ds_read_b128 v[200:203], v162
	ds_read_b128 v[204:207], v162 offset:1024
	ds_read_b128 v[208:211], v162 offset:2048
	ds_read_b128 v[212:215], v162 offset:3072
	ds_read_b128 v[216:219], v162 offset:4096
	ds_read_b128 v[220:223], v162 offset:5120
	ds_read_b128 v[224:227], v162 offset:6144
	ds_read_b128 v[228:231], v162 offset:7168
	global_load_lds_dwordx4 v[236:237], off
	v_lshl_add_u64 v[236:237], v[154:155], 0, v[142:143]
	s_mov_b32 m0, s43
	s_nop 0
	global_load_lds_dwordx4 v[236:237], off
	s_waitcnt vmcnt(8)
	s_waitcnt lgkmcnt(0)
	s_barrier
	s_setprio 1
	s_waitcnt lgkmcnt(0)
	v_mfma_f32_16x16x32_bf16 v[126:129], v[168:171], v[200:203], v[126:129]
	v_mfma_f32_16x16x32_bf16 v[122:125], v[176:179], v[200:203], v[122:125]
	v_mfma_f32_16x16x32_bf16 v[110:113], v[168:171], v[208:211], v[110:113]
	v_mfma_f32_16x16x32_bf16 v[106:109], v[176:179], v[208:211], v[106:109]
	v_mfma_f32_16x16x32_bf16 v[94:97], v[168:171], v[216:219], v[94:97]
	v_mfma_f32_16x16x32_bf16 v[90:93], v[176:179], v[216:219], v[90:93]
	v_mfma_f32_16x16x32_bf16 v[78:81], v[168:171], v[224:227], v[78:81]
	v_mfma_f32_16x16x32_bf16 v[74:77], v[176:179], v[224:227], v[74:77]
	s_setprio 0
	s_setprio 1
	v_mfma_f32_16x16x32_bf16 v[126:129], v[172:175], v[204:207], v[126:129]
	v_mfma_f32_16x16x32_bf16 v[122:125], v[180:183], v[204:207], v[122:125]
	v_mfma_f32_16x16x32_bf16 v[110:113], v[172:175], v[212:215], v[110:113]
	v_mfma_f32_16x16x32_bf16 v[106:109], v[180:183], v[212:215], v[106:109]
	v_mfma_f32_16x16x32_bf16 v[94:97], v[172:175], v[220:223], v[94:97]
	v_mfma_f32_16x16x32_bf16 v[90:93], v[180:183], v[220:223], v[90:93]
	v_mfma_f32_16x16x32_bf16 v[78:81], v[172:175], v[228:231], v[78:81]
	v_mfma_f32_16x16x32_bf16 v[74:77], v[180:183], v[228:231], v[74:77]
	s_setprio 0
	s_setprio 1
	v_mfma_f32_16x16x32_bf16 v[118:121], v[184:187], v[200:203], v[118:121]
	v_mfma_f32_16x16x32_bf16 v[114:117], v[192:195], v[200:203], v[114:117]
	v_mfma_f32_16x16x32_bf16 v[102:105], v[184:187], v[208:211], v[102:105]
	v_mfma_f32_16x16x32_bf16 v[98:101], v[192:195], v[208:211], v[98:101]
	v_mfma_f32_16x16x32_bf16 v[86:89], v[184:187], v[216:219], v[86:89]
	v_mfma_f32_16x16x32_bf16 v[82:85], v[192:195], v[216:219], v[82:85]
	v_mfma_f32_16x16x32_bf16 v[70:73], v[184:187], v[224:227], v[70:73]
	v_mfma_f32_16x16x32_bf16 v[66:69], v[192:195], v[224:227], v[66:69]
	s_setprio 0
	s_setprio 1
	v_mfma_f32_16x16x32_bf16 v[118:121], v[188:191], v[204:207], v[118:121]
	v_mfma_f32_16x16x32_bf16 v[114:117], v[196:199], v[204:207], v[114:117]
	v_mfma_f32_16x16x32_bf16 v[102:105], v[188:191], v[212:215], v[102:105]
	v_mfma_f32_16x16x32_bf16 v[98:101], v[196:199], v[212:215], v[98:101]
	v_mfma_f32_16x16x32_bf16 v[86:89], v[188:191], v[220:223], v[86:89]
	v_mfma_f32_16x16x32_bf16 v[82:85], v[196:199], v[220:223], v[82:85]
	v_mfma_f32_16x16x32_bf16 v[70:73], v[188:191], v[228:231], v[70:73]
	v_mfma_f32_16x16x32_bf16 v[66:69], v[196:199], v[228:231], v[66:69]
	s_setprio 0
	s_barrier
	s_mov_b32 m0, s44
	v_lshl_add_u64 v[236:237], v[234:235], 0, v[134:135]
	ds_read_b128 v[200:203], v162 offset:16384
	ds_read_b128 v[204:207], v162 offset:17408
	ds_read_b128 v[208:211], v162 offset:18432
	ds_read_b128 v[212:215], v162 offset:19456
	ds_read_b128 v[216:219], v162 offset:20480
	ds_read_b128 v[220:223], v162 offset:21504
	ds_read_b128 v[224:227], v162 offset:22528
	ds_read_b128 v[228:231], v162 offset:23552
	global_load_lds_dwordx4 v[236:237], off
	v_lshl_add_u64 v[238:239], v[234:235], 0, v[136:137]
	s_mov_b32 m0, s45
	v_lshl_add_u64 v[240:241], v[234:235], 0, s[10:11]
	global_load_lds_dwordx4 v[238:239], off
	v_lshl_add_u64 v[242:243], v[240:241], 0, v[134:135]
	s_mov_b32 m0, s46
	v_lshl_add_u64 v[240:241], v[240:241], 0, v[136:137]
	global_load_lds_dwordx4 v[242:243], off
	s_mov_b32 m0, s47
	v_lshl_add_u64 v[242:243], v[232:233], 0, v[136:137]
	global_load_lds_dwordx4 v[240:241], off
	v_lshl_add_u64 v[240:241], v[232:233], 0, v[134:135]
	s_mov_b32 m0, s0
	s_nop 0
	global_load_lds_dwordx4 v[240:241], off
	s_mov_b32 m0, s1
	s_nop 0
	global_load_lds_dwordx4 v[242:243], off
	s_waitcnt vmcnt(8)
	s_waitcnt lgkmcnt(0)
	s_barrier
	s_setprio 1
	s_waitcnt lgkmcnt(0)
	v_mfma_f32_16x16x32_bf16 v[62:65], v[168:171], v[200:203], v[62:65]
	v_mfma_f32_16x16x32_bf16 v[58:61], v[176:179], v[200:203], v[58:61]
	v_mfma_f32_16x16x32_bf16 v[46:49], v[168:171], v[208:211], v[46:49]
	v_mfma_f32_16x16x32_bf16 v[42:45], v[176:179], v[208:211], v[42:45]
	v_mfma_f32_16x16x32_bf16 v[30:33], v[168:171], v[216:219], v[30:33]
	v_mfma_f32_16x16x32_bf16 v[26:29], v[176:179], v[216:219], v[26:29]
	v_mfma_f32_16x16x32_bf16 v[14:17], v[168:171], v[224:227], v[14:17]
	v_mfma_f32_16x16x32_bf16 v[10:13], v[176:179], v[224:227], v[10:13]
	s_setprio 0
	s_setprio 1
	v_mfma_f32_16x16x32_bf16 v[62:65], v[172:175], v[204:207], v[62:65]
	v_mfma_f32_16x16x32_bf16 v[58:61], v[180:183], v[204:207], v[58:61]
	v_mfma_f32_16x16x32_bf16 v[46:49], v[172:175], v[212:215], v[46:49]
	v_mfma_f32_16x16x32_bf16 v[42:45], v[180:183], v[212:215], v[42:45]
	v_mfma_f32_16x16x32_bf16 v[30:33], v[172:175], v[220:223], v[30:33]
	v_mfma_f32_16x16x32_bf16 v[26:29], v[180:183], v[220:223], v[26:29]
	v_mfma_f32_16x16x32_bf16 v[14:17], v[172:175], v[228:231], v[14:17]
	v_mfma_f32_16x16x32_bf16 v[10:13], v[180:183], v[228:231], v[10:13]
	s_setprio 0
	s_setprio 1
	v_mfma_f32_16x16x32_bf16 v[54:57], v[184:187], v[200:203], v[54:57]
	v_mfma_f32_16x16x32_bf16 v[50:53], v[192:195], v[200:203], v[50:53]
	v_mfma_f32_16x16x32_bf16 v[38:41], v[184:187], v[208:211], v[38:41]
	v_mfma_f32_16x16x32_bf16 v[34:37], v[192:195], v[208:211], v[34:37]
	v_mfma_f32_16x16x32_bf16 v[22:25], v[184:187], v[216:219], v[22:25]
	v_mfma_f32_16x16x32_bf16 v[18:21], v[192:195], v[216:219], v[18:21]
	v_mfma_f32_16x16x32_bf16 v[6:9], v[184:187], v[224:227], v[6:9]
	v_mfma_f32_16x16x32_bf16 v[2:5], v[192:195], v[224:227], v[2:5]
	s_setprio 0
	s_setprio 1
	v_mfma_f32_16x16x32_bf16 v[54:57], v[188:191], v[204:207], v[54:57]
	v_mfma_f32_16x16x32_bf16 v[50:53], v[196:199], v[204:207], v[50:53]
	v_mfma_f32_16x16x32_bf16 v[38:41], v[188:191], v[212:215], v[38:41]
	v_mfma_f32_16x16x32_bf16 v[34:37], v[196:199], v[212:215], v[34:37]
	v_mfma_f32_16x16x32_bf16 v[22:25], v[188:191], v[220:223], v[22:25]
	v_mfma_f32_16x16x32_bf16 v[18:21], v[196:199], v[220:223], v[18:21]
	v_mfma_f32_16x16x32_bf16 v[6:9], v[188:191], v[228:231], v[6:9]
	v_mfma_f32_16x16x32_bf16 v[2:5], v[196:199], v[228:231], v[2:5]
	s_setprio 0
	s_barrier
	ds_read_b128 v[168:171], v163
	ds_read_b128 v[172:175], v163 offset:1024
	ds_read_b128 v[176:179], v163 offset:2048
	ds_read_b128 v[180:183], v163 offset:3072
	ds_read_b128 v[184:187], v164
	ds_read_b128 v[188:191], v164 offset:1024
	ds_read_b128 v[192:195], v164 offset:2048
	ds_read_b128 v[196:199], v164 offset:3072
	v_lshl_add_u64 v[232:233], v[232:233], 0, s[10:11]
	s_mov_b32 m0, s2
	v_lshl_add_u64 v[244:245], v[232:233], 0, v[134:135]
	ds_read_b128 v[200:203], v162 offset:32768
	ds_read_b128 v[204:207], v162 offset:33792
	ds_read_b128 v[208:211], v162 offset:34816
	ds_read_b128 v[212:215], v162 offset:35840
	ds_read_b128 v[216:219], v162 offset:36864
	ds_read_b128 v[220:223], v162 offset:37888
	ds_read_b128 v[224:227], v162 offset:38912
	ds_read_b128 v[228:231], v162 offset:39936
	global_load_lds_dwordx4 v[244:245], off
	v_lshl_add_u64 v[232:233], v[232:233], 0, v[136:137]
	s_mov_b32 m0, s3
	s_nop 0
	global_load_lds_dwordx4 v[232:233], off
	s_waitcnt vmcnt(8)
	s_waitcnt lgkmcnt(0)
	s_barrier
	s_setprio 1
	s_waitcnt lgkmcnt(0)
	v_mfma_f32_16x16x32_bf16 v[126:129], v[168:171], v[200:203], v[126:129]
	v_mfma_f32_16x16x32_bf16 v[122:125], v[176:179], v[200:203], v[122:125]
	v_mfma_f32_16x16x32_bf16 v[110:113], v[168:171], v[208:211], v[110:113]
	v_mfma_f32_16x16x32_bf16 v[106:109], v[176:179], v[208:211], v[106:109]
	v_mfma_f32_16x16x32_bf16 v[94:97], v[168:171], v[216:219], v[94:97]
	v_mfma_f32_16x16x32_bf16 v[90:93], v[176:179], v[216:219], v[90:93]
	v_mfma_f32_16x16x32_bf16 v[78:81], v[168:171], v[224:227], v[78:81]
	v_mfma_f32_16x16x32_bf16 v[74:77], v[176:179], v[224:227], v[74:77]
	s_setprio 0
	s_setprio 1
	v_mfma_f32_16x16x32_bf16 v[126:129], v[172:175], v[204:207], v[126:129]
	v_mfma_f32_16x16x32_bf16 v[122:125], v[180:183], v[204:207], v[122:125]
	v_mfma_f32_16x16x32_bf16 v[110:113], v[172:175], v[212:215], v[110:113]
	v_mfma_f32_16x16x32_bf16 v[106:109], v[180:183], v[212:215], v[106:109]
	v_mfma_f32_16x16x32_bf16 v[94:97], v[172:175], v[220:223], v[94:97]
	v_mfma_f32_16x16x32_bf16 v[90:93], v[180:183], v[220:223], v[90:93]
	v_mfma_f32_16x16x32_bf16 v[78:81], v[172:175], v[228:231], v[78:81]
	v_mfma_f32_16x16x32_bf16 v[74:77], v[180:183], v[228:231], v[74:77]
	s_setprio 0
	s_setprio 1
	v_mfma_f32_16x16x32_bf16 v[118:121], v[184:187], v[200:203], v[118:121]
	v_mfma_f32_16x16x32_bf16 v[114:117], v[192:195], v[200:203], v[114:117]
	v_mfma_f32_16x16x32_bf16 v[102:105], v[184:187], v[208:211], v[102:105]
	v_mfma_f32_16x16x32_bf16 v[98:101], v[192:195], v[208:211], v[98:101]
	v_mfma_f32_16x16x32_bf16 v[86:89], v[184:187], v[216:219], v[86:89]
	v_mfma_f32_16x16x32_bf16 v[82:85], v[192:195], v[216:219], v[82:85]
	v_mfma_f32_16x16x32_bf16 v[70:73], v[184:187], v[224:227], v[70:73]
	v_mfma_f32_16x16x32_bf16 v[66:69], v[192:195], v[224:227], v[66:69]
	s_setprio 0
	s_setprio 1
	v_mfma_f32_16x16x32_bf16 v[118:121], v[188:191], v[204:207], v[118:121]
	v_mfma_f32_16x16x32_bf16 v[114:117], v[196:199], v[204:207], v[114:117]
	v_mfma_f32_16x16x32_bf16 v[102:105], v[188:191], v[212:215], v[102:105]
	v_mfma_f32_16x16x32_bf16 v[98:101], v[196:199], v[212:215], v[98:101]
	v_mfma_f32_16x16x32_bf16 v[86:89], v[188:191], v[220:223], v[86:89]
	v_mfma_f32_16x16x32_bf16 v[82:85], v[196:199], v[220:223], v[82:85]
	v_mfma_f32_16x16x32_bf16 v[70:73], v[188:191], v[228:231], v[70:73]
	v_mfma_f32_16x16x32_bf16 v[66:69], v[196:199], v[228:231], v[66:69]
	s_setprio 0
	s_barrier
	s_mov_b32 m0, s48
	v_lshl_add_u64 v[232:233], v[236:237], 0, s[14:15]
	ds_read_b128 v[200:203], v162 offset:49152
	ds_read_b128 v[204:207], v162 offset:50176
	ds_read_b128 v[208:211], v162 offset:51200
	ds_read_b128 v[212:215], v162 offset:52224
	ds_read_b128 v[216:219], v162 offset:53248
	ds_read_b128 v[220:223], v162 offset:54272
	ds_read_b128 v[224:227], v162 offset:55296
	ds_read_b128 v[228:231], v162 offset:56320
	global_load_lds_dwordx4 v[232:233], off
	v_lshl_add_u64 v[232:233], v[238:239], 0, s[14:15]
	s_mov_b32 m0, s51
	s_nop 0
	global_load_lds_dwordx4 v[232:233], off
	v_lshl_add_u64 v[232:233], v[234:235], 0, s[16:17]
	v_lshl_add_u64 v[234:235], v[232:233], 0, v[134:135]
	s_mov_b32 m0, s52
	v_lshl_add_u64 v[232:233], v[232:233], 0, v[136:137]
	global_load_lds_dwordx4 v[234:235], off
	s_add_i32 m0, s52, 0x2000
	s_nop 0
	global_load_lds_dwordx4 v[232:233], off
	v_lshl_add_u64 v[232:233], v[240:241], 0, s[14:15]
	s_mov_b32 m0, s34
	s_nop 0
	global_load_lds_dwordx4 v[232:233], off
	v_lshl_add_u64 v[232:233], v[242:243], 0, s[14:15]
	s_mov_b32 m0, s35
	s_nop 0
	global_load_lds_dwordx4 v[232:233], off
	s_waitcnt vmcnt(8)
	s_waitcnt lgkmcnt(0)
	s_barrier
	s_setprio 1
	s_waitcnt lgkmcnt(0)
	v_mfma_f32_16x16x32_bf16 v[62:65], v[168:171], v[200:203], v[62:65]
	v_mfma_f32_16x16x32_bf16 v[58:61], v[176:179], v[200:203], v[58:61]
	v_mfma_f32_16x16x32_bf16 v[46:49], v[168:171], v[208:211], v[46:49]
	v_mfma_f32_16x16x32_bf16 v[42:45], v[176:179], v[208:211], v[42:45]
	v_mfma_f32_16x16x32_bf16 v[30:33], v[168:171], v[216:219], v[30:33]
	v_mfma_f32_16x16x32_bf16 v[26:29], v[176:179], v[216:219], v[26:29]
	v_mfma_f32_16x16x32_bf16 v[14:17], v[168:171], v[224:227], v[14:17]
	v_mfma_f32_16x16x32_bf16 v[10:13], v[176:179], v[224:227], v[10:13]
	s_setprio 0
	s_setprio 1
	v_mfma_f32_16x16x32_bf16 v[62:65], v[172:175], v[204:207], v[62:65]
	v_mfma_f32_16x16x32_bf16 v[58:61], v[180:183], v[204:207], v[58:61]
	v_mfma_f32_16x16x32_bf16 v[46:49], v[172:175], v[212:215], v[46:49]
	v_mfma_f32_16x16x32_bf16 v[42:45], v[180:183], v[212:215], v[42:45]
	v_mfma_f32_16x16x32_bf16 v[30:33], v[172:175], v[220:223], v[30:33]
	v_mfma_f32_16x16x32_bf16 v[26:29], v[180:183], v[220:223], v[26:29]
	v_mfma_f32_16x16x32_bf16 v[14:17], v[172:175], v[228:231], v[14:17]
	v_mfma_f32_16x16x32_bf16 v[10:13], v[180:183], v[228:231], v[10:13]
	s_setprio 0
	s_setprio 1
	v_mfma_f32_16x16x32_bf16 v[54:57], v[184:187], v[200:203], v[54:57]
	v_mfma_f32_16x16x32_bf16 v[50:53], v[192:195], v[200:203], v[50:53]
	v_mfma_f32_16x16x32_bf16 v[38:41], v[184:187], v[208:211], v[38:41]
	v_mfma_f32_16x16x32_bf16 v[34:37], v[192:195], v[208:211], v[34:37]
	v_mfma_f32_16x16x32_bf16 v[22:25], v[184:187], v[216:219], v[22:25]
	v_mfma_f32_16x16x32_bf16 v[18:21], v[192:195], v[216:219], v[18:21]
	v_mfma_f32_16x16x32_bf16 v[6:9], v[184:187], v[224:227], v[6:9]
	v_mfma_f32_16x16x32_bf16 v[2:5], v[192:195], v[224:227], v[2:5]
	s_setprio 0
	s_setprio 1
	v_mfma_f32_16x16x32_bf16 v[54:57], v[188:191], v[204:207], v[54:57]
	v_mfma_f32_16x16x32_bf16 v[50:53], v[196:199], v[204:207], v[50:53]
	v_mfma_f32_16x16x32_bf16 v[38:41], v[188:191], v[212:215], v[38:41]
	v_mfma_f32_16x16x32_bf16 v[34:37], v[196:199], v[212:215], v[34:37]
	v_mfma_f32_16x16x32_bf16 v[22:25], v[188:191], v[220:223], v[22:25]
	v_mfma_f32_16x16x32_bf16 v[18:21], v[196:199], v[220:223], v[18:21]
	v_mfma_f32_16x16x32_bf16 v[6:9], v[188:191], v[228:231], v[6:9]
	v_mfma_f32_16x16x32_bf16 v[2:5], v[196:199], v[228:231], v[2:5]
	s_setprio 0
	s_barrier
	s_add_i32 s7, s7, 2
	v_lshl_add_u64 v[154:155], v[154:155], 0, s[20:21]
	s_cmp_gt_u32 s7, 13
	v_lshl_add_u64 v[156:157], v[156:157], 0, s[20:21]
	s_cbranch_scc0 .LBB0_213

.LBB0_675:
	s_ashr_i32 s45, s44, 31
	s_lshl_b64 s[8:9], s[44:45], 19
	s_ashr_i32 s43, s42, 31
	v_lshl_add_u64 v[162:163], v[146:147], 0, s[8:9]
	s_lshl_b64 s[8:9], s[42:43], 19
	v_lshl_add_u64 v[164:165], v[140:141], 0, s[8:9]
	v_cndmask_b32_e64 v132, v2, v164, s[4:5]
	v_lshl_add_u64 v[136:137], v[2:3], 0, s[36:37]
	v_mov_b32_e32 v2, 0
	v_cndmask_b32_e64 v1, v5, v163, s[4:5]
	v_cndmask_b32_e64 v130, v4, v162, s[4:5]
	v_cndmask_b32_e64 v131, v3, v165, s[4:5]
	v_lshl_add_u64 v[134:135], v[4:5], 0, s[26:27]
	s_mov_b32 s3, -2
	ds_read_b128 v[168:171], v180
	ds_read_b128 v[172:175], v180 offset:1024
	ds_read_b128 v[184:187], v180 offset:2048
	ds_read_b128 v[188:191], v180 offset:3072
	ds_read_b128 v[192:195], v181
	ds_read_b128 v[200:203], v181 offset:1024
	ds_read_b128 v[204:207], v181 offset:2048
	ds_read_b128 v[208:211], v181 offset:3072
	s_cmp_eq_u32 s3, 12
	v_lshl_add_u64 v[196:197], v[134:135], 0, s[38:39]
	s_cselect_b64 vcc, -1, 0
	v_cndmask_b32_e32 v197, v197, v1, vcc
	v_cndmask_b32_e32 v196, v196, v130, vcc
	v_cndmask_b32_e32 v245, v137, v131, vcc
	v_cndmask_b32_e32 v244, v136, v132, vcc
	s_mov_b32 m0, s56
	v_lshl_add_u64 v[246:247], v[134:135], 0, v[156:157]
	ds_read_b128 v[212:215], v178
	ds_read_b128 v[216:219], v178 offset:1024
	ds_read_b128 v[220:223], v178 offset:2048
	ds_read_b128 v[224:227], v178 offset:3072
	ds_read_b128 v[228:231], v178 offset:4096
	ds_read_b128 v[232:235], v178 offset:5120
	ds_read_b128 v[236:239], v178 offset:6144
	ds_read_b128 v[240:243], v178 offset:7168
	global_load_lds_dwordx4 v[246:247], off
	v_lshl_add_u64 v[246:247], v[134:135], 0, v[158:159]
	s_mov_b32 m0, s57
	s_nop 0
	global_load_lds_dwordx4 v[246:247], off
	s_waitcnt vmcnt(8)
	s_waitcnt lgkmcnt(0)
	s_barrier
	s_setprio 1
	s_waitcnt lgkmcnt(0)
	v_mfma_f32_16x16x32_bf16 v[126:129], v[168:171], v[212:215], 0
	v_mfma_f32_16x16x32_bf16 v[122:125], v[184:187], v[212:215], 0
	v_mfma_f32_16x16x32_bf16 v[110:113], v[168:171], v[220:223], 0
	v_mfma_f32_16x16x32_bf16 v[106:109], v[184:187], v[220:223], 0
	v_mfma_f32_16x16x32_bf16 v[94:97], v[168:171], v[228:231], 0
	v_mfma_f32_16x16x32_bf16 v[90:93], v[184:187], v[228:231], 0
	v_mfma_f32_16x16x32_bf16 v[78:81], v[168:171], v[236:239], 0
	v_mfma_f32_16x16x32_bf16 v[74:77], v[184:187], v[236:239], 0
	s_setprio 0
	s_setprio 1
	v_mfma_f32_16x16x32_bf16 v[126:129], v[172:175], v[216:219], v[126:129]
	v_mfma_f32_16x16x32_bf16 v[122:125], v[188:191], v[216:219], v[122:125]
	v_mfma_f32_16x16x32_bf16 v[110:113], v[172:175], v[224:227], v[110:113]
	v_mfma_f32_16x16x32_bf16 v[106:109], v[188:191], v[224:227], v[106:109]
	v_mfma_f32_16x16x32_bf16 v[94:97], v[172:175], v[232:235], v[94:97]
	v_mfma_f32_16x16x32_bf16 v[90:93], v[188:191], v[232:235], v[90:93]
	v_mfma_f32_16x16x32_bf16 v[78:81], v[172:175], v[240:243], v[78:81]
	v_mfma_f32_16x16x32_bf16 v[74:77], v[188:191], v[240:243], v[74:77]
	s_setprio 0
	s_setprio 1
	v_mfma_f32_16x16x32_bf16 v[118:121], v[192:195], v[212:215], 0
	v_mfma_f32_16x16x32_bf16 v[114:117], v[204:207], v[212:215], 0
	v_mfma_f32_16x16x32_bf16 v[102:105], v[192:195], v[220:223], 0
	v_mfma_f32_16x16x32_bf16 v[98:101], v[204:207], v[220:223], 0
	v_mfma_f32_16x16x32_bf16 v[86:89], v[192:195], v[228:231], 0
	v_mfma_f32_16x16x32_bf16 v[82:85], v[204:207], v[228:231], 0
	v_mfma_f32_16x16x32_bf16 v[70:73], v[192:195], v[236:239], 0
	v_mfma_f32_16x16x32_bf16 v[66:69], v[204:207], v[236:239], 0
	s_setprio 0
	s_setprio 1
	v_mfma_f32_16x16x32_bf16 v[118:121], v[200:203], v[216:219], v[118:121]
	v_mfma_f32_16x16x32_bf16 v[114:117], v[208:211], v[216:219], v[114:117]
	v_mfma_f32_16x16x32_bf16 v[102:105], v[200:203], v[224:227], v[102:105]
	v_mfma_f32_16x16x32_bf16 v[98:101], v[208:211], v[224:227], v[98:101]
	v_mfma_f32_16x16x32_bf16 v[86:89], v[200:203], v[232:235], v[86:89]
	v_mfma_f32_16x16x32_bf16 v[82:85], v[208:211], v[232:235], v[82:85]
	v_mfma_f32_16x16x32_bf16 v[70:73], v[200:203], v[240:243], v[70:73]
	v_mfma_f32_16x16x32_bf16 v[66:69], v[208:211], v[240:243], v[66:69]
	s_setprio 0
	s_barrier
	s_mov_b32 m0, s58
	v_lshl_add_u64 v[246:247], v[244:245], 0, v[142:143]
	ds_read_b128 v[212:215], v178 offset:16384
	ds_read_b128 v[216:219], v178 offset:17408
	ds_read_b128 v[220:223], v178 offset:18432
	ds_read_b128 v[224:227], v178 offset:19456
	ds_read_b128 v[228:231], v178 offset:20480
	ds_read_b128 v[232:235], v178 offset:21504
	ds_read_b128 v[236:239], v178 offset:22528
	ds_read_b128 v[240:243], v178 offset:23552
	global_load_lds_dwordx4 v[246:247], off
	v_lshl_add_u64 v[248:249], v[244:245], 0, v[144:145]
	s_add_i32 m0, s58, 0x2000
	v_lshl_add_u64 v[250:251], v[244:245], 0, s[16:17]
	s_add_i32 s7, s55, s0
	global_load_lds_dwordx4 v[248:249], off
	v_lshl_add_u64 v[252:253], v[250:251], 0, v[142:143]
	s_mov_b32 m0, s7
	v_lshl_add_u64 v[250:251], v[250:251], 0, v[144:145]
	global_load_lds_dwordx4 v[252:253], off
	s_add_i32 m0, s7, 0x2000
	v_lshl_add_u64 v[252:253], v[196:197], 0, v[144:145]
	global_load_lds_dwordx4 v[250:251], off
	v_lshl_add_u64 v[250:251], v[196:197], 0, v[142:143]
	s_mov_b32 m0, s1
	s_nop 0
	global_load_lds_dwordx4 v[250:251], off
	s_mov_b32 m0, s2
	s_nop 0
	global_load_lds_dwordx4 v[252:253], off
	s_waitcnt vmcnt(8)
	s_waitcnt lgkmcnt(0)
	s_barrier
	s_setprio 1
	s_waitcnt lgkmcnt(0)
	v_mfma_f32_16x16x32_bf16 v[62:65], v[168:171], v[212:215], 0
	v_mfma_f32_16x16x32_bf16 v[58:61], v[184:187], v[212:215], 0
	v_mfma_f32_16x16x32_bf16 v[46:49], v[168:171], v[220:223], 0
	v_mfma_f32_16x16x32_bf16 v[42:45], v[184:187], v[220:223], 0
	v_mfma_f32_16x16x32_bf16 v[30:33], v[168:171], v[228:231], 0
	v_mfma_f32_16x16x32_bf16 v[26:29], v[184:187], v[228:231], 0
	v_mfma_f32_16x16x32_bf16 v[14:17], v[168:171], v[236:239], 0
	v_mfma_f32_16x16x32_bf16 v[10:13], v[184:187], v[236:239], 0
	s_setprio 0
	s_setprio 1
	v_mfma_f32_16x16x32_bf16 v[62:65], v[172:175], v[216:219], v[62:65]
	v_mfma_f32_16x16x32_bf16 v[58:61], v[188:191], v[216:219], v[58:61]
	v_mfma_f32_16x16x32_bf16 v[46:49], v[172:175], v[224:227], v[46:49]
	v_mfma_f32_16x16x32_bf16 v[42:45], v[188:191], v[224:227], v[42:45]
	v_mfma_f32_16x16x32_bf16 v[30:33], v[172:175], v[232:235], v[30:33]
	v_mfma_f32_16x16x32_bf16 v[26:29], v[188:191], v[232:235], v[26:29]
	v_mfma_f32_16x16x32_bf16 v[14:17], v[172:175], v[240:243], v[14:17]
	v_mfma_f32_16x16x32_bf16 v[10:13], v[188:191], v[240:243], v[10:13]
	s_setprio 0
	s_setprio 1
	v_mfma_f32_16x16x32_bf16 v[54:57], v[192:195], v[212:215], 0
	v_mfma_f32_16x16x32_bf16 v[50:53], v[204:207], v[212:215], 0
	v_mfma_f32_16x16x32_bf16 v[38:41], v[192:195], v[220:223], 0
	v_mfma_f32_16x16x32_bf16 v[34:37], v[204:207], v[220:223], 0
	v_mfma_f32_16x16x32_bf16 v[22:25], v[192:195], v[228:231], 0
	v_mfma_f32_16x16x32_bf16 v[18:21], v[204:207], v[228:231], 0
	v_mfma_f32_16x16x32_bf16 v[6:9], v[192:195], v[236:239], 0
	v_mfma_f32_16x16x32_bf16 v[2:5], v[204:207], v[236:239], 0
	s_setprio 0
	s_setprio 1
	v_mfma_f32_16x16x32_bf16 v[54:57], v[200:203], v[216:219], v[54:57]
	v_mfma_f32_16x16x32_bf16 v[50:53], v[208:211], v[216:219], v[50:53]
	v_mfma_f32_16x16x32_bf16 v[38:41], v[200:203], v[224:227], v[38:41]
	v_mfma_f32_16x16x32_bf16 v[34:37], v[208:211], v[224:227], v[34:37]
	v_mfma_f32_16x16x32_bf16 v[22:25], v[200:203], v[232:235], v[22:25]
	v_mfma_f32_16x16x32_bf16 v[18:21], v[208:211], v[232:235], v[18:21]
	v_mfma_f32_16x16x32_bf16 v[6:9], v[200:203], v[240:243], v[6:9]
	v_mfma_f32_16x16x32_bf16 v[2:5], v[208:211], v[240:243], v[2:5]
	s_setprio 0
	s_barrier
	s_add_i32 s7, 0, 0x18000
	v_add_u32_e32 v133, s7, v177
	s_add_i32 s8, 0, 0x1c000
	ds_read_b128 v[168:171], v133
	ds_read_b128 v[172:175], v133 offset:1024
	ds_read_b128 v[184:187], v133 offset:2048
	ds_read_b128 v[188:191], v133 offset:3072
	v_add_u32_e32 v133, s8, v177
	ds_read_b128 v[192:195], v133
	ds_read_b128 v[200:203], v133 offset:1024
	ds_read_b128 v[204:207], v133 offset:2048
	ds_read_b128 v[208:211], v133 offset:3072
	v_lshl_add_u64 v[196:197], v[196:197], 0, s[16:17]
	s_mov_b32 m0, s33
	v_lshl_add_u64 v[198:199], v[196:197], 0, v[142:143]
	ds_read_b128 v[212:215], v178 offset:32768
	ds_read_b128 v[216:219], v178 offset:33792
	ds_read_b128 v[220:223], v178 offset:34816
	ds_read_b128 v[224:227], v178 offset:35840
	ds_read_b128 v[228:231], v178 offset:36864
	ds_read_b128 v[232:235], v178 offset:37888
	ds_read_b128 v[236:239], v178 offset:38912
	ds_read_b128 v[240:243], v178 offset:39936
	global_load_lds_dwordx4 v[198:199], off
	v_lshl_add_u64 v[196:197], v[196:197], 0, v[144:145]
	s_mov_b32 m0, s34
	s_nop 0
	global_load_lds_dwordx4 v[196:197], off
	s_waitcnt vmcnt(8)
	s_waitcnt lgkmcnt(0)
	s_barrier
	s_setprio 1
	s_waitcnt lgkmcnt(0)
	v_mfma_f32_16x16x32_bf16 v[126:129], v[168:171], v[212:215], v[126:129]
	v_mfma_f32_16x16x32_bf16 v[122:125], v[184:187], v[212:215], v[122:125]
	v_mfma_f32_16x16x32_bf16 v[110:113], v[168:171], v[220:223], v[110:113]
	v_mfma_f32_16x16x32_bf16 v[106:109], v[184:187], v[220:223], v[106:109]
	v_mfma_f32_16x16x32_bf16 v[94:97], v[168:171], v[228:231], v[94:97]
	v_mfma_f32_16x16x32_bf16 v[90:93], v[184:187], v[228:231], v[90:93]
	v_mfma_f32_16x16x32_bf16 v[78:81], v[168:171], v[236:239], v[78:81]
	v_mfma_f32_16x16x32_bf16 v[74:77], v[184:187], v[236:239], v[74:77]
	s_setprio 0
	s_setprio 1
	v_mfma_f32_16x16x32_bf16 v[126:129], v[172:175], v[216:219], v[126:129]
	v_mfma_f32_16x16x32_bf16 v[122:125], v[188:191], v[216:219], v[122:125]
	v_mfma_f32_16x16x32_bf16 v[110:113], v[172:175], v[224:227], v[110:113]
	v_mfma_f32_16x16x32_bf16 v[106:109], v[188:191], v[224:227], v[106:109]
	v_mfma_f32_16x16x32_bf16 v[94:97], v[172:175], v[232:235], v[94:97]
	v_mfma_f32_16x16x32_bf16 v[90:93], v[188:191], v[232:235], v[90:93]
	v_mfma_f32_16x16x32_bf16 v[78:81], v[172:175], v[240:243], v[78:81]
	v_mfma_f32_16x16x32_bf16 v[74:77], v[188:191], v[240:243], v[74:77]
	s_setprio 0
	s_setprio 1
	v_mfma_f32_16x16x32_bf16 v[118:121], v[192:195], v[212:215], v[118:121]
	v_mfma_f32_16x16x32_bf16 v[114:117], v[204:207], v[212:215], v[114:117]
	v_mfma_f32_16x16x32_bf16 v[102:105], v[192:195], v[220:223], v[102:105]
	v_mfma_f32_16x16x32_bf16 v[98:101], v[204:207], v[220:223], v[98:101]
	v_mfma_f32_16x16x32_bf16 v[86:89], v[192:195], v[228:231], v[86:89]
	v_mfma_f32_16x16x32_bf16 v[82:85], v[204:207], v[228:231], v[82:85]
	v_mfma_f32_16x16x32_bf16 v[70:73], v[192:195], v[236:239], v[70:73]
	v_mfma_f32_16x16x32_bf16 v[66:69], v[204:207], v[236:239], v[66:69]
	s_setprio 0
	s_setprio 1
	v_mfma_f32_16x16x32_bf16 v[118:121], v[200:203], v[216:219], v[118:121]
	v_mfma_f32_16x16x32_bf16 v[114:117], v[208:211], v[216:219], v[114:117]
	v_mfma_f32_16x16x32_bf16 v[102:105], v[200:203], v[224:227], v[102:105]
	v_mfma_f32_16x16x32_bf16 v[98:101], v[208:211], v[224:227], v[98:101]
	v_mfma_f32_16x16x32_bf16 v[86:89], v[200:203], v[232:235], v[86:89]
	v_mfma_f32_16x16x32_bf16 v[82:85], v[208:211], v[232:235], v[82:85]
	v_mfma_f32_16x16x32_bf16 v[70:73], v[200:203], v[240:243], v[70:73]
	v_mfma_f32_16x16x32_bf16 v[66:69], v[208:211], v[240:243], v[66:69]
	s_setprio 0
	s_barrier
	s_add_i32 s7, s7, s0
	v_lshl_add_u64 v[196:197], v[246:247], 0, s[24:25]
	s_mov_b32 m0, s7
	ds_read_b128 v[212:215], v178 offset:49152
	ds_read_b128 v[216:219], v178 offset:50176
	ds_read_b128 v[220:223], v178 offset:51200
	ds_read_b128 v[224:227], v178 offset:52224
	ds_read_b128 v[228:231], v178 offset:53248
	ds_read_b128 v[232:235], v178 offset:54272
	ds_read_b128 v[236:239], v178 offset:55296
	ds_read_b128 v[240:243], v178 offset:56320
	global_load_lds_dwordx4 v[196:197], off
	v_lshl_add_u64 v[196:197], v[248:249], 0, s[24:25]
	s_add_i32 m0, s7, 0x2000
	s_add_i32 s7, s8, s0
	global_load_lds_dwordx4 v[196:197], off
	v_lshl_add_u64 v[196:197], v[244:245], 0, s[26:27]
	v_lshl_add_u64 v[198:199], v[196:197], 0, v[142:143]
	s_mov_b32 m0, s7
	v_lshl_add_u64 v[196:197], v[196:197], 0, v[144:145]
	global_load_lds_dwordx4 v[198:199], off
	s_add_i32 m0, s7, 0x2000
	s_nop 0
	global_load_lds_dwordx4 v[196:197], off
	v_lshl_add_u64 v[196:197], v[250:251], 0, s[24:25]
	s_mov_b32 m0, s49
	s_nop 0
	global_load_lds_dwordx4 v[196:197], off
	v_lshl_add_u64 v[196:197], v[252:253], 0, s[24:25]
	s_mov_b32 m0, s50
	s_nop 0
	global_load_lds_dwordx4 v[196:197], off
	s_waitcnt vmcnt(8)
	s_waitcnt lgkmcnt(0)
	s_barrier
	s_setprio 1
	s_waitcnt lgkmcnt(0)
	v_mfma_f32_16x16x32_bf16 v[62:65], v[168:171], v[212:215], v[62:65]
	v_mfma_f32_16x16x32_bf16 v[58:61], v[184:187], v[212:215], v[58:61]
	v_mfma_f32_16x16x32_bf16 v[46:49], v[168:171], v[220:223], v[46:49]
	v_mfma_f32_16x16x32_bf16 v[42:45], v[184:187], v[220:223], v[42:45]
	v_mfma_f32_16x16x32_bf16 v[30:33], v[168:171], v[228:231], v[30:33]
	v_mfma_f32_16x16x32_bf16 v[26:29], v[184:187], v[228:231], v[26:29]
	v_mfma_f32_16x16x32_bf16 v[14:17], v[168:171], v[236:239], v[14:17]
	v_mfma_f32_16x16x32_bf16 v[10:13], v[184:187], v[236:239], v[10:13]
	s_setprio 0
	s_setprio 1
	v_mfma_f32_16x16x32_bf16 v[62:65], v[172:175], v[216:219], v[62:65]
	v_mfma_f32_16x16x32_bf16 v[58:61], v[188:191], v[216:219], v[58:61]
	v_mfma_f32_16x16x32_bf16 v[46:49], v[172:175], v[224:227], v[46:49]
	v_mfma_f32_16x16x32_bf16 v[42:45], v[188:191], v[224:227], v[42:45]
	v_mfma_f32_16x16x32_bf16 v[30:33], v[172:175], v[232:235], v[30:33]
	v_mfma_f32_16x16x32_bf16 v[26:29], v[188:191], v[232:235], v[26:29]
	v_mfma_f32_16x16x32_bf16 v[14:17], v[172:175], v[240:243], v[14:17]
	v_mfma_f32_16x16x32_bf16 v[10:13], v[188:191], v[240:243], v[10:13]
	s_setprio 0
	s_setprio 1
	v_mfma_f32_16x16x32_bf16 v[54:57], v[192:195], v[212:215], v[54:57]
	v_mfma_f32_16x16x32_bf16 v[50:53], v[204:207], v[212:215], v[50:53]
	v_mfma_f32_16x16x32_bf16 v[38:41], v[192:195], v[220:223], v[38:41]
	v_mfma_f32_16x16x32_bf16 v[34:37], v[204:207], v[220:223], v[34:37]
	v_mfma_f32_16x16x32_bf16 v[22:25], v[192:195], v[228:231], v[22:25]
	v_mfma_f32_16x16x32_bf16 v[18:21], v[204:207], v[228:231], v[18:21]
	v_mfma_f32_16x16x32_bf16 v[6:9], v[192:195], v[236:239], v[6:9]
	v_mfma_f32_16x16x32_bf16 v[2:5], v[204:207], v[236:239], v[2:5]
	s_setprio 0
	s_setprio 1
	v_mfma_f32_16x16x32_bf16 v[54:57], v[200:203], v[216:219], v[54:57]
	v_mfma_f32_16x16x32_bf16 v[50:53], v[208:211], v[216:219], v[50:53]
	v_mfma_f32_16x16x32_bf16 v[38:41], v[200:203], v[224:227], v[38:41]
	v_mfma_f32_16x16x32_bf16 v[34:37], v[208:211], v[224:227], v[34:37]
	v_mfma_f32_16x16x32_bf16 v[22:25], v[200:203], v[232:235], v[22:25]
	v_mfma_f32_16x16x32_bf16 v[18:21], v[208:211], v[232:235], v[18:21]
	v_mfma_f32_16x16x32_bf16 v[6:9], v[200:203], v[240:243], v[6:9]
	v_mfma_f32_16x16x32_bf16 v[2:5], v[208:211], v[240:243], v[2:5]
	s_setprio 0
	s_barrier
	s_add_i32 s3, s3, 2
	v_lshl_add_u64 v[134:135], v[134:135], 0, s[36:37]
	s_cmp_gt_u32 s3, 13
	v_lshl_add_u64 v[136:137], v[136:137], 0, s[36:37]
	s_cbranch_scc0 .LBB0_676
	s_branch .Lpeel_exit_2
.LBB0_676:
	ds_read_b128 v[168:171], v180
	ds_read_b128 v[172:175], v180 offset:1024
	ds_read_b128 v[184:187], v180 offset:2048
	ds_read_b128 v[188:191], v180 offset:3072
	ds_read_b128 v[192:195], v181
	ds_read_b128 v[200:203], v181 offset:1024
	ds_read_b128 v[204:207], v181 offset:2048
	ds_read_b128 v[208:211], v181 offset:3072
	s_cmp_eq_u32 s3, 12
	v_lshl_add_u64 v[196:197], v[134:135], 0, s[38:39]
	s_cselect_b64 vcc, -1, 0
	v_cndmask_b32_e32 v197, v197, v1, vcc
	v_cndmask_b32_e32 v196, v196, v130, vcc
	v_cndmask_b32_e32 v245, v137, v131, vcc
	v_cndmask_b32_e32 v244, v136, v132, vcc
	s_mov_b32 m0, s56
	v_lshl_add_u64 v[246:247], v[134:135], 0, v[156:157]
	ds_read_b128 v[212:215], v178
	ds_read_b128 v[216:219], v178 offset:1024
	ds_read_b128 v[220:223], v178 offset:2048
	ds_read_b128 v[224:227], v178 offset:3072
	ds_read_b128 v[228:231], v178 offset:4096
	ds_read_b128 v[232:235], v178 offset:5120
	ds_read_b128 v[236:239], v178 offset:6144
	ds_read_b128 v[240:243], v178 offset:7168
	global_load_lds_dwordx4 v[246:247], off
	v_lshl_add_u64 v[246:247], v[134:135], 0, v[158:159]
	s_mov_b32 m0, s57
	s_nop 0
	global_load_lds_dwordx4 v[246:247], off
	s_waitcnt vmcnt(8)
	s_waitcnt lgkmcnt(0)
	s_barrier
	s_setprio 1
	s_waitcnt lgkmcnt(0)
	v_mfma_f32_16x16x32_bf16 v[126:129], v[168:171], v[212:215], v[126:129]
	v_mfma_f32_16x16x32_bf16 v[122:125], v[184:187], v[212:215], v[122:125]
	v_mfma_f32_16x16x32_bf16 v[110:113], v[168:171], v[220:223], v[110:113]
	v_mfma_f32_16x16x32_bf16 v[106:109], v[184:187], v[220:223], v[106:109]
	v_mfma_f32_16x16x32_bf16 v[94:97], v[168:171], v[228:231], v[94:97]
	v_mfma_f32_16x16x32_bf16 v[90:93], v[184:187], v[228:231], v[90:93]
	v_mfma_f32_16x16x32_bf16 v[78:81], v[168:171], v[236:239], v[78:81]
	v_mfma_f32_16x16x32_bf16 v[74:77], v[184:187], v[236:239], v[74:77]
	s_setprio 0
	s_setprio 1
	v_mfma_f32_16x16x32_bf16 v[126:129], v[172:175], v[216:219], v[126:129]
	v_mfma_f32_16x16x32_bf16 v[122:125], v[188:191], v[216:219], v[122:125]
	v_mfma_f32_16x16x32_bf16 v[110:113], v[172:175], v[224:227], v[110:113]
	v_mfma_f32_16x16x32_bf16 v[106:109], v[188:191], v[224:227], v[106:109]
	v_mfma_f32_16x16x32_bf16 v[94:97], v[172:175], v[232:235], v[94:97]
	v_mfma_f32_16x16x32_bf16 v[90:93], v[188:191], v[232:235], v[90:93]
	v_mfma_f32_16x16x32_bf16 v[78:81], v[172:175], v[240:243], v[78:81]
	v_mfma_f32_16x16x32_bf16 v[74:77], v[188:191], v[240:243], v[74:77]
	s_setprio 0
	s_setprio 1
	v_mfma_f32_16x16x32_bf16 v[118:121], v[192:195], v[212:215], v[118:121]
	v_mfma_f32_16x16x32_bf16 v[114:117], v[204:207], v[212:215], v[114:117]
	v_mfma_f32_16x16x32_bf16 v[102:105], v[192:195], v[220:223], v[102:105]
	v_mfma_f32_16x16x32_bf16 v[98:101], v[204:207], v[220:223], v[98:101]
	v_mfma_f32_16x16x32_bf16 v[86:89], v[192:195], v[228:231], v[86:89]
	v_mfma_f32_16x16x32_bf16 v[82:85], v[204:207], v[228:231], v[82:85]
	v_mfma_f32_16x16x32_bf16 v[70:73], v[192:195], v[236:239], v[70:73]
	v_mfma_f32_16x16x32_bf16 v[66:69], v[204:207], v[236:239], v[66:69]
	s_setprio 0
	s_setprio 1
	v_mfma_f32_16x16x32_bf16 v[118:121], v[200:203], v[216:219], v[118:121]
	v_mfma_f32_16x16x32_bf16 v[114:117], v[208:211], v[216:219], v[114:117]
	v_mfma_f32_16x16x32_bf16 v[102:105], v[200:203], v[224:227], v[102:105]
	v_mfma_f32_16x16x32_bf16 v[98:101], v[208:211], v[224:227], v[98:101]
	v_mfma_f32_16x16x32_bf16 v[86:89], v[200:203], v[232:235], v[86:89]
	v_mfma_f32_16x16x32_bf16 v[82:85], v[208:211], v[232:235], v[82:85]
	v_mfma_f32_16x16x32_bf16 v[70:73], v[200:203], v[240:243], v[70:73]
	v_mfma_f32_16x16x32_bf16 v[66:69], v[208:211], v[240:243], v[66:69]
	s_setprio 0
	s_barrier
	s_mov_b32 m0, s58
	v_lshl_add_u64 v[246:247], v[244:245], 0, v[142:143]
	ds_read_b128 v[212:215], v178 offset:16384
	ds_read_b128 v[216:219], v178 offset:17408
	ds_read_b128 v[220:223], v178 offset:18432
	ds_read_b128 v[224:227], v178 offset:19456
	ds_read_b128 v[228:231], v178 offset:20480
	ds_read_b128 v[232:235], v178 offset:21504
	ds_read_b128 v[236:239], v178 offset:22528
	ds_read_b128 v[240:243], v178 offset:23552
	global_load_lds_dwordx4 v[246:247], off
	v_lshl_add_u64 v[248:249], v[244:245], 0, v[144:145]
	s_add_i32 m0, s58, 0x2000
	v_lshl_add_u64 v[250:251], v[244:245], 0, s[16:17]
	s_add_i32 s7, s55, s0
	global_load_lds_dwordx4 v[248:249], off
	v_lshl_add_u64 v[252:253], v[250:251], 0, v[142:143]
	s_mov_b32 m0, s7
	v_lshl_add_u64 v[250:251], v[250:251], 0, v[144:145]
	global_load_lds_dwordx4 v[252:253], off
	s_add_i32 m0, s7, 0x2000
	v_lshl_add_u64 v[252:253], v[196:197], 0, v[144:145]
	global_load_lds_dwordx4 v[250:251], off
	v_lshl_add_u64 v[250:251], v[196:197], 0, v[142:143]
	s_mov_b32 m0, s1
	s_nop 0
	global_load_lds_dwordx4 v[250:251], off
	s_mov_b32 m0, s2
	s_nop 0
	global_load_lds_dwordx4 v[252:253], off
	s_waitcnt vmcnt(8)
	s_waitcnt lgkmcnt(0)
	s_barrier
	s_setprio 1
	s_waitcnt lgkmcnt(0)
	v_mfma_f32_16x16x32_bf16 v[62:65], v[168:171], v[212:215], v[62:65]
	v_mfma_f32_16x16x32_bf16 v[58:61], v[184:187], v[212:215], v[58:61]
	v_mfma_f32_16x16x32_bf16 v[46:49], v[168:171], v[220:223], v[46:49]
	v_mfma_f32_16x16x32_bf16 v[42:45], v[184:187], v[220:223], v[42:45]
	v_mfma_f32_16x16x32_bf16 v[30:33], v[168:171], v[228:231], v[30:33]
	v_mfma_f32_16x16x32_bf16 v[26:29], v[184:187], v[228:231], v[26:29]
	v_mfma_f32_16x16x32_bf16 v[14:17], v[168:171], v[236:239], v[14:17]
	v_mfma_f32_16x16x32_bf16 v[10:13], v[184:187], v[236:239], v[10:13]
	s_setprio 0
	s_setprio 1
	v_mfma_f32_16x16x32_bf16 v[62:65], v[172:175], v[216:219], v[62:65]
	v_mfma_f32_16x16x32_bf16 v[58:61], v[188:191], v[216:219], v[58:61]
	v_mfma_f32_16x16x32_bf16 v[46:49], v[172:175], v[224:227], v[46:49]
	v_mfma_f32_16x16x32_bf16 v[42:45], v[188:191], v[224:227], v[42:45]
	v_mfma_f32_16x16x32_bf16 v[30:33], v[172:175], v[232:235], v[30:33]
	v_mfma_f32_16x16x32_bf16 v[26:29], v[188:191], v[232:235], v[26:29]
	v_mfma_f32_16x16x32_bf16 v[14:17], v[172:175], v[240:243], v[14:17]
	v_mfma_f32_16x16x32_bf16 v[10:13], v[188:191], v[240:243], v[10:13]
	s_setprio 0
	s_setprio 1
	v_mfma_f32_16x16x32_bf16 v[54:57], v[192:195], v[212:215], v[54:57]
	v_mfma_f32_16x16x32_bf16 v[50:53], v[204:207], v[212:215], v[50:53]
	v_mfma_f32_16x16x32_bf16 v[38:41], v[192:195], v[220:223], v[38:41]
	v_mfma_f32_16x16x32_bf16 v[34:37], v[204:207], v[220:223], v[34:37]
	v_mfma_f32_16x16x32_bf16 v[22:25], v[192:195], v[228:231], v[22:25]
	v_mfma_f32_16x16x32_bf16 v[18:21], v[204:207], v[228:231], v[18:21]
	v_mfma_f32_16x16x32_bf16 v[6:9], v[192:195], v[236:239], v[6:9]
	v_mfma_f32_16x16x32_bf16 v[2:5], v[204:207], v[236:239], v[2:5]
	s_setprio 0
	s_setprio 1
	v_mfma_f32_16x16x32_bf16 v[54:57], v[200:203], v[216:219], v[54:57]
	v_mfma_f32_16x16x32_bf16 v[50:53], v[208:211], v[216:219], v[50:53]
	v_mfma_f32_16x16x32_bf16 v[38:41], v[200:203], v[224:227], v[38:41]
	v_mfma_f32_16x16x32_bf16 v[34:37], v[208:211], v[224:227], v[34:37]
	v_mfma_f32_16x16x32_bf16 v[22:25], v[200:203], v[232:235], v[22:25]
	v_mfma_f32_16x16x32_bf16 v[18:21], v[208:211], v[232:235], v[18:21]
	v_mfma_f32_16x16x32_bf16 v[6:9], v[200:203], v[240:243], v[6:9]
	v_mfma_f32_16x16x32_bf16 v[2:5], v[208:211], v[240:243], v[2:5]
	s_setprio 0
	s_barrier
	s_add_i32 s7, 0, 0x18000
	v_add_u32_e32 v133, s7, v177
	s_add_i32 s8, 0, 0x1c000
	ds_read_b128 v[168:171], v133
	ds_read_b128 v[172:175], v133 offset:1024
	ds_read_b128 v[184:187], v133 offset:2048
	ds_read_b128 v[188:191], v133 offset:3072
	v_add_u32_e32 v133, s8, v177
	ds_read_b128 v[192:195], v133
	ds_read_b128 v[200:203], v133 offset:1024
	ds_read_b128 v[204:207], v133 offset:2048
	ds_read_b128 v[208:211], v133 offset:3072
	v_lshl_add_u64 v[196:197], v[196:197], 0, s[16:17]
	s_mov_b32 m0, s33
	v_lshl_add_u64 v[198:199], v[196:197], 0, v[142:143]
	ds_read_b128 v[212:215], v178 offset:32768
	ds_read_b128 v[216:219], v178 offset:33792
	ds_read_b128 v[220:223], v178 offset:34816
	ds_read_b128 v[224:227], v178 offset:35840
	ds_read_b128 v[228:231], v178 offset:36864
	ds_read_b128 v[232:235], v178 offset:37888
	ds_read_b128 v[236:239], v178 offset:38912
	ds_read_b128 v[240:243], v178 offset:39936
	global_load_lds_dwordx4 v[198:199], off
	v_lshl_add_u64 v[196:197], v[196:197], 0, v[144:145]
	s_mov_b32 m0, s34
	s_nop 0
	global_load_lds_dwordx4 v[196:197], off
	s_waitcnt vmcnt(8)
	s_waitcnt lgkmcnt(0)
	s_barrier
	s_setprio 1
	s_waitcnt lgkmcnt(0)
	v_mfma_f32_16x16x32_bf16 v[126:129], v[168:171], v[212:215], v[126:129]
	v_mfma_f32_16x16x32_bf16 v[122:125], v[184:187], v[212:215], v[122:125]
	v_mfma_f32_16x16x32_bf16 v[110:113], v[168:171], v[220:223], v[110:113]
	v_mfma_f32_16x16x32_bf16 v[106:109], v[184:187], v[220:223], v[106:109]
	v_mfma_f32_16x16x32_bf16 v[94:97], v[168:171], v[228:231], v[94:97]
	v_mfma_f32_16x16x32_bf16 v[90:93], v[184:187], v[228:231], v[90:93]
	v_mfma_f32_16x16x32_bf16 v[78:81], v[168:171], v[236:239], v[78:81]
	v_mfma_f32_16x16x32_bf16 v[74:77], v[184:187], v[236:239], v[74:77]
	s_setprio 0
	s_setprio 1
	v_mfma_f32_16x16x32_bf16 v[126:129], v[172:175], v[216:219], v[126:129]
	v_mfma_f32_16x16x32_bf16 v[122:125], v[188:191], v[216:219], v[122:125]
	v_mfma_f32_16x16x32_bf16 v[110:113], v[172:175], v[224:227], v[110:113]
	v_mfma_f32_16x16x32_bf16 v[106:109], v[188:191], v[224:227], v[106:109]
	v_mfma_f32_16x16x32_bf16 v[94:97], v[172:175], v[232:235], v[94:97]
	v_mfma_f32_16x16x32_bf16 v[90:93], v[188:191], v[232:235], v[90:93]
	v_mfma_f32_16x16x32_bf16 v[78:81], v[172:175], v[240:243], v[78:81]
	v_mfma_f32_16x16x32_bf16 v[74:77], v[188:191], v[240:243], v[74:77]
	s_setprio 0
	s_setprio 1
	v_mfma_f32_16x16x32_bf16 v[118:121], v[192:195], v[212:215], v[118:121]
	v_mfma_f32_16x16x32_bf16 v[114:117], v[204:207], v[212:215], v[114:117]
	v_mfma_f32_16x16x32_bf16 v[102:105], v[192:195], v[220:223], v[102:105]
	v_mfma_f32_16x16x32_bf16 v[98:101], v[204:207], v[220:223], v[98:101]
	v_mfma_f32_16x16x32_bf16 v[86:89], v[192:195], v[228:231], v[86:89]
	v_mfma_f32_16x16x32_bf16 v[82:85], v[204:207], v[228:231], v[82:85]
	v_mfma_f32_16x16x32_bf16 v[70:73], v[192:195], v[236:239], v[70:73]
	v_mfma_f32_16x16x32_bf16 v[66:69], v[204:207], v[236:239], v[66:69]
	s_setprio 0
	s_setprio 1
	v_mfma_f32_16x16x32_bf16 v[118:121], v[200:203], v[216:219], v[118:121]
	v_mfma_f32_16x16x32_bf16 v[114:117], v[208:211], v[216:219], v[114:117]
	v_mfma_f32_16x16x32_bf16 v[102:105], v[200:203], v[224:227], v[102:105]
	v_mfma_f32_16x16x32_bf16 v[98:101], v[208:211], v[224:227], v[98:101]
	v_mfma_f32_16x16x32_bf16 v[86:89], v[200:203], v[232:235], v[86:89]
	v_mfma_f32_16x16x32_bf16 v[82:85], v[208:211], v[232:235], v[82:85]
	v_mfma_f32_16x16x32_bf16 v[70:73], v[200:203], v[240:243], v[70:73]
	v_mfma_f32_16x16x32_bf16 v[66:69], v[208:211], v[240:243], v[66:69]
	s_setprio 0
	s_barrier
	s_add_i32 s7, s7, s0
	v_lshl_add_u64 v[196:197], v[246:247], 0, s[24:25]
	s_mov_b32 m0, s7
	ds_read_b128 v[212:215], v178 offset:49152
	ds_read_b128 v[216:219], v178 offset:50176
	ds_read_b128 v[220:223], v178 offset:51200
	ds_read_b128 v[224:227], v178 offset:52224
	ds_read_b128 v[228:231], v178 offset:53248
	ds_read_b128 v[232:235], v178 offset:54272
	ds_read_b128 v[236:239], v178 offset:55296
	ds_read_b128 v[240:243], v178 offset:56320
	global_load_lds_dwordx4 v[196:197], off
	v_lshl_add_u64 v[196:197], v[248:249], 0, s[24:25]
	s_add_i32 m0, s7, 0x2000
	s_add_i32 s7, s8, s0
	global_load_lds_dwordx4 v[196:197], off
	v_lshl_add_u64 v[196:197], v[244:245], 0, s[26:27]
	v_lshl_add_u64 v[198:199], v[196:197], 0, v[142:143]
	s_mov_b32 m0, s7
	v_lshl_add_u64 v[196:197], v[196:197], 0, v[144:145]
	global_load_lds_dwordx4 v[198:199], off
	s_add_i32 m0, s7, 0x2000
	s_nop 0
	global_load_lds_dwordx4 v[196:197], off
	v_lshl_add_u64 v[196:197], v[250:251], 0, s[24:25]
	s_mov_b32 m0, s49
	s_nop 0
	global_load_lds_dwordx4 v[196:197], off
	v_lshl_add_u64 v[196:197], v[252:253], 0, s[24:25]
	s_mov_b32 m0, s50
	s_nop 0
	global_load_lds_dwordx4 v[196:197], off
	s_waitcnt vmcnt(8)
	s_waitcnt lgkmcnt(0)
	s_barrier
	s_setprio 1
	s_waitcnt lgkmcnt(0)
	v_mfma_f32_16x16x32_bf16 v[62:65], v[168:171], v[212:215], v[62:65]
	v_mfma_f32_16x16x32_bf16 v[58:61], v[184:187], v[212:215], v[58:61]
	v_mfma_f32_16x16x32_bf16 v[46:49], v[168:171], v[220:223], v[46:49]
	v_mfma_f32_16x16x32_bf16 v[42:45], v[184:187], v[220:223], v[42:45]
	v_mfma_f32_16x16x32_bf16 v[30:33], v[168:171], v[228:231], v[30:33]
	v_mfma_f32_16x16x32_bf16 v[26:29], v[184:187], v[228:231], v[26:29]
	v_mfma_f32_16x16x32_bf16 v[14:17], v[168:171], v[236:239], v[14:17]
	v_mfma_f32_16x16x32_bf16 v[10:13], v[184:187], v[236:239], v[10:13]
	s_setprio 0
	s_setprio 1
	v_mfma_f32_16x16x32_bf16 v[62:65], v[172:175], v[216:219], v[62:65]
	v_mfma_f32_16x16x32_bf16 v[58:61], v[188:191], v[216:219], v[58:61]
	v_mfma_f32_16x16x32_bf16 v[46:49], v[172:175], v[224:227], v[46:49]
	v_mfma_f32_16x16x32_bf16 v[42:45], v[188:191], v[224:227], v[42:45]
	v_mfma_f32_16x16x32_bf16 v[30:33], v[172:175], v[232:235], v[30:33]
	v_mfma_f32_16x16x32_bf16 v[26:29], v[188:191], v[232:235], v[26:29]
	v_mfma_f32_16x16x32_bf16 v[14:17], v[172:175], v[240:243], v[14:17]
	v_mfma_f32_16x16x32_bf16 v[10:13], v[188:191], v[240:243], v[10:13]
	s_setprio 0
	s_setprio 1
	v_mfma_f32_16x16x32_bf16 v[54:57], v[192:195], v[212:215], v[54:57]
	v_mfma_f32_16x16x32_bf16 v[50:53], v[204:207], v[212:215], v[50:53]
	v_mfma_f32_16x16x32_bf16 v[38:41], v[192:195], v[220:223], v[38:41]
	v_mfma_f32_16x16x32_bf16 v[34:37], v[204:207], v[220:223], v[34:37]
	v_mfma_f32_16x16x32_bf16 v[22:25], v[192:195], v[228:231], v[22:25]
	v_mfma_f32_16x16x32_bf16 v[18:21], v[204:207], v[228:231], v[18:21]
	v_mfma_f32_16x16x32_bf16 v[6:9], v[192:195], v[236:239], v[6:9]
	v_mfma_f32_16x16x32_bf16 v[2:5], v[204:207], v[236:239], v[2:5]
	s_setprio 0
	s_setprio 1
	v_mfma_f32_16x16x32_bf16 v[54:57], v[200:203], v[216:219], v[54:57]
	v_mfma_f32_16x16x32_bf16 v[50:53], v[208:211], v[216:219], v[50:53]
	v_mfma_f32_16x16x32_bf16 v[38:41], v[200:203], v[224:227], v[38:41]
	v_mfma_f32_16x16x32_bf16 v[34:37], v[208:211], v[224:227], v[34:37]
	v_mfma_f32_16x16x32_bf16 v[22:25], v[200:203], v[232:235], v[22:25]
	v_mfma_f32_16x16x32_bf16 v[18:21], v[208:211], v[232:235], v[18:21]
	v_mfma_f32_16x16x32_bf16 v[6:9], v[200:203], v[240:243], v[6:9]
	v_mfma_f32_16x16x32_bf16 v[2:5], v[208:211], v[240:243], v[2:5]
	s_setprio 0
	s_barrier
	s_add_i32 s3, s3, 2
	v_lshl_add_u64 v[134:135], v[134:135], 0, s[36:37]
	s_cmp_gt_u32 s3, 13
	v_lshl_add_u64 v[136:137], v[136:137], 0, s[36:37]
	s_cbranch_scc0 .LBB0_676

.LBB0_1064:
	s_ashr_i32 s47, s46, 31
	s_lshl_b64 s[12:13], s[46:47], 20
	s_ashr_i32 s49, s48, 31
	s_ashr_i32 s45, s44, 31
	v_lshl_add_u64 v[6:7], v[168:169], 0, s[12:13]
	s_lshl_b64 s[12:13], s[48:49], 7
	s_lshl_b64 s[52:53], s[44:45], 20
	v_lshl_add_u64 v[188:189], v[6:7], 0, s[12:13]
	v_lshl_add_u64 v[6:7], v[170:171], 0, s[52:53]
	v_lshl_add_u64 v[190:191], v[6:7], 0, s[12:13]
	s_waitcnt vmcnt(0)
	v_mov_b32_e32 v66, 0
	v_cndmask_b32_e64 v1, v5, v189, s[50:51]
	v_cndmask_b32_e64 v130, v4, v188, s[50:51]
	v_cndmask_b32_e64 v131, v3, v191, s[50:51]
	v_cndmask_b32_e64 v132, v2, v190, s[50:51]
	s_add_i32 s12, s9, -2
	v_lshl_add_u64 v[134:135], v[4:5], 0, s[24:25]
	v_lshl_add_u64 v[136:137], v[2:3], 0, s[38:39]
	s_mov_b32 s13, 0
	v_add_u32_e32 v133, s65, v204
	ds_read_b128 v[138:141], v207
	ds_read_b128 v[142:145], v207 offset:1024
	ds_read_b128 v[146:149], v207 offset:2048
	ds_read_b128 v[150:153], v207 offset:3072
	ds_read_b128 v[154:157], v133
	ds_read_b128 v[158:161], v133 offset:1024
	ds_read_b128 v[162:165], v133 offset:2048
	ds_read_b128 v[192:195], v133 offset:3072
	s_cmp_eq_u32 s12, s13
	v_lshl_add_u64 v[196:197], v[134:135], 0, s[40:41]
	s_cselect_b64 vcc, -1, 0
	s_add_i32 s13, s13, 2
	v_cndmask_b32_e32 v197, v197, v1, vcc
	v_cndmask_b32_e32 v196, v196, v130, vcc
	v_cndmask_b32_e32 v199, v137, v131, vcc
	v_cndmask_b32_e32 v198, v136, v132, vcc
	v_lshl_add_u64 v[240:241], v[134:135], 0, v[184:185]
	s_add_i32 m0, s1, 0xc000
	ds_read_b128 v[208:211], v205
	ds_read_b128 v[212:215], v205 offset:1024
	ds_read_b128 v[216:219], v205 offset:2048
	ds_read_b128 v[220:223], v205 offset:3072
	ds_read_b128 v[224:227], v205 offset:4096
	ds_read_b128 v[228:231], v205 offset:5120
	ds_read_b128 v[232:235], v205 offset:6144
	ds_read_b128 v[236:239], v205 offset:7168
	global_load_lds_dwordx4 v[240:241], off
	v_lshl_add_u64 v[240:241], v[134:135], 0, v[186:187]
	s_add_i32 m0, s1, 0xe000
	s_nop 0
	global_load_lds_dwordx4 v[240:241], off
	s_waitcnt vmcnt(8)
	s_waitcnt lgkmcnt(0)
	s_barrier
	s_setprio 1
	s_waitcnt lgkmcnt(0)
	v_mfma_f32_16x16x32_bf16 v[62:65], v[138:141], v[208:211], 0
	v_mfma_f32_16x16x32_bf16 v[58:61], v[146:149], v[208:211], 0
	v_mfma_f32_16x16x32_bf16 v[54:57], v[138:141], v[216:219], 0
	v_mfma_f32_16x16x32_bf16 v[50:53], v[146:149], v[216:219], 0
	v_mfma_f32_16x16x32_bf16 v[46:49], v[138:141], v[224:227], 0
	v_mfma_f32_16x16x32_bf16 v[42:45], v[146:149], v[224:227], 0
	v_mfma_f32_16x16x32_bf16 v[38:41], v[138:141], v[232:235], 0
	v_mfma_f32_16x16x32_bf16 v[34:37], v[146:149], v[232:235], 0
	s_setprio 0
	s_setprio 1
	v_mfma_f32_16x16x32_bf16 v[62:65], v[142:145], v[212:215], v[62:65]
	v_mfma_f32_16x16x32_bf16 v[58:61], v[150:153], v[212:215], v[58:61]
	v_mfma_f32_16x16x32_bf16 v[54:57], v[142:145], v[220:223], v[54:57]
	v_mfma_f32_16x16x32_bf16 v[50:53], v[150:153], v[220:223], v[50:53]
	v_mfma_f32_16x16x32_bf16 v[46:49], v[142:145], v[228:231], v[46:49]
	v_mfma_f32_16x16x32_bf16 v[42:45], v[150:153], v[228:231], v[42:45]
	v_mfma_f32_16x16x32_bf16 v[38:41], v[142:145], v[236:239], v[38:41]
	v_mfma_f32_16x16x32_bf16 v[34:37], v[150:153], v[236:239], v[34:37]
	s_setprio 0
	s_setprio 1
	v_mfma_f32_16x16x32_bf16 v[30:33], v[154:157], v[208:211], 0
	v_mfma_f32_16x16x32_bf16 v[26:29], v[162:165], v[208:211], 0
	v_mfma_f32_16x16x32_bf16 v[22:25], v[154:157], v[216:219], 0
	v_mfma_f32_16x16x32_bf16 v[18:21], v[162:165], v[216:219], 0
	v_mfma_f32_16x16x32_bf16 v[14:17], v[154:157], v[224:227], 0
	v_mfma_f32_16x16x32_bf16 v[10:13], v[162:165], v[224:227], 0
	v_mfma_f32_16x16x32_bf16 v[6:9], v[154:157], v[232:235], 0
	v_mfma_f32_16x16x32_bf16 v[2:5], v[162:165], v[232:235], 0
	s_setprio 0
	s_setprio 1
	v_mfma_f32_16x16x32_bf16 v[30:33], v[158:161], v[212:215], v[30:33]
	v_mfma_f32_16x16x32_bf16 v[26:29], v[192:195], v[212:215], v[26:29]
	v_mfma_f32_16x16x32_bf16 v[22:25], v[158:161], v[220:223], v[22:25]
	v_mfma_f32_16x16x32_bf16 v[18:21], v[192:195], v[220:223], v[18:21]
	v_mfma_f32_16x16x32_bf16 v[14:17], v[158:161], v[228:231], v[14:17]
	v_mfma_f32_16x16x32_bf16 v[10:13], v[192:195], v[228:231], v[10:13]
	v_mfma_f32_16x16x32_bf16 v[6:9], v[158:161], v[236:239], v[6:9]
	v_mfma_f32_16x16x32_bf16 v[2:5], v[192:195], v[236:239], v[2:5]
	s_setprio 0
	s_barrier
	s_add_i32 s31, s64, s0
	v_lshl_add_u64 v[240:241], v[198:199], 0, v[172:173]
	s_mov_b32 m0, s31
	ds_read_b128 v[208:211], v205 offset:16384
	ds_read_b128 v[212:215], v205 offset:17408
	ds_read_b128 v[216:219], v205 offset:18432
	ds_read_b128 v[220:223], v205 offset:19456
	ds_read_b128 v[224:227], v205 offset:20480
	ds_read_b128 v[228:231], v205 offset:21504
	ds_read_b128 v[232:235], v205 offset:22528
	ds_read_b128 v[236:239], v205 offset:23552
	global_load_lds_dwordx4 v[240:241], off
	v_lshl_add_u64 v[242:243], v[198:199], 0, v[174:175]
	s_add_i32 m0, s31, 0x2000
	v_lshl_add_u64 v[244:245], v[198:199], 0, s[18:19]
	s_add_i32 s31, s65, s0
	global_load_lds_dwordx4 v[242:243], off
	v_lshl_add_u64 v[246:247], v[244:245], 0, v[172:173]
	s_mov_b32 m0, s31
	v_lshl_add_u64 v[244:245], v[244:245], 0, v[174:175]
	global_load_lds_dwordx4 v[246:247], off
	s_add_i32 m0, s31, 0x2000
	v_lshl_add_u64 v[246:247], v[196:197], 0, v[174:175]
	global_load_lds_dwordx4 v[244:245], off
	v_lshl_add_u64 v[244:245], v[196:197], 0, v[172:173]
	s_mov_b32 m0, s1
	s_nop 0
	global_load_lds_dwordx4 v[244:245], off
	s_mov_b32 m0, s2
	s_nop 0
	global_load_lds_dwordx4 v[246:247], off
	s_waitcnt vmcnt(8)
	s_waitcnt lgkmcnt(0)
	s_barrier
	s_setprio 1
	s_waitcnt lgkmcnt(0)
	v_mfma_f32_16x16x32_bf16 v[126:129], v[138:141], v[208:211], 0
	v_mfma_f32_16x16x32_bf16 v[122:125], v[146:149], v[208:211], 0
	v_mfma_f32_16x16x32_bf16 v[118:121], v[138:141], v[216:219], 0
	v_mfma_f32_16x16x32_bf16 v[114:117], v[146:149], v[216:219], 0
	v_mfma_f32_16x16x32_bf16 v[110:113], v[138:141], v[224:227], 0
	v_mfma_f32_16x16x32_bf16 v[106:109], v[146:149], v[224:227], 0
	v_mfma_f32_16x16x32_bf16 v[102:105], v[138:141], v[232:235], 0
	v_mfma_f32_16x16x32_bf16 v[98:101], v[146:149], v[232:235], 0
	s_setprio 0
	s_setprio 1
	v_mfma_f32_16x16x32_bf16 v[126:129], v[142:145], v[212:215], v[126:129]
	v_mfma_f32_16x16x32_bf16 v[122:125], v[150:153], v[212:215], v[122:125]
	v_mfma_f32_16x16x32_bf16 v[118:121], v[142:145], v[220:223], v[118:121]
	v_mfma_f32_16x16x32_bf16 v[114:117], v[150:153], v[220:223], v[114:117]
	v_mfma_f32_16x16x32_bf16 v[110:113], v[142:145], v[228:231], v[110:113]
	v_mfma_f32_16x16x32_bf16 v[106:109], v[150:153], v[228:231], v[106:109]
	v_mfma_f32_16x16x32_bf16 v[102:105], v[142:145], v[236:239], v[102:105]
	v_mfma_f32_16x16x32_bf16 v[98:101], v[150:153], v[236:239], v[98:101]
	s_setprio 0
	s_setprio 1
	v_mfma_f32_16x16x32_bf16 v[94:97], v[154:157], v[208:211], 0
	v_mfma_f32_16x16x32_bf16 v[90:93], v[162:165], v[208:211], 0
	v_mfma_f32_16x16x32_bf16 v[86:89], v[154:157], v[216:219], 0
	v_mfma_f32_16x16x32_bf16 v[82:85], v[162:165], v[216:219], 0
	v_mfma_f32_16x16x32_bf16 v[78:81], v[154:157], v[224:227], 0
	v_mfma_f32_16x16x32_bf16 v[74:77], v[162:165], v[224:227], 0
	v_mfma_f32_16x16x32_bf16 v[70:73], v[154:157], v[232:235], 0
	v_mfma_f32_16x16x32_bf16 v[66:69], v[162:165], v[232:235], 0
	s_setprio 0
	s_setprio 1
	v_mfma_f32_16x16x32_bf16 v[94:97], v[158:161], v[212:215], v[94:97]
	v_mfma_f32_16x16x32_bf16 v[90:93], v[192:195], v[212:215], v[90:93]
	v_mfma_f32_16x16x32_bf16 v[86:89], v[158:161], v[220:223], v[86:89]
	v_mfma_f32_16x16x32_bf16 v[82:85], v[192:195], v[220:223], v[82:85]
	v_mfma_f32_16x16x32_bf16 v[78:81], v[158:161], v[228:231], v[78:81]
	v_mfma_f32_16x16x32_bf16 v[74:77], v[192:195], v[228:231], v[74:77]
	v_mfma_f32_16x16x32_bf16 v[70:73], v[158:161], v[236:239], v[70:73]
	v_mfma_f32_16x16x32_bf16 v[66:69], v[192:195], v[236:239], v[66:69]
	s_setprio 0
	s_barrier
	s_add_i32 s31, 0, 0x18000
	v_add_u32_e32 v133, s31, v204
	s_add_i32 s45, 0, 0x1c000
	ds_read_b128 v[138:141], v133
	ds_read_b128 v[142:145], v133 offset:1024
	ds_read_b128 v[146:149], v133 offset:2048
	ds_read_b128 v[150:153], v133 offset:3072
	v_add_u32_e32 v133, s45, v204
	ds_read_b128 v[154:157], v133
	ds_read_b128 v[158:161], v133 offset:1024
	ds_read_b128 v[162:165], v133 offset:2048
	ds_read_b128 v[192:195], v133 offset:3072
	v_lshl_add_u64 v[196:197], v[196:197], 0, s[18:19]
	s_mov_b32 m0, s33
	v_lshl_add_u64 v[248:249], v[196:197], 0, v[172:173]
	ds_read_b128 v[208:211], v205 offset:32768
	ds_read_b128 v[212:215], v205 offset:33792
	ds_read_b128 v[216:219], v205 offset:34816
	ds_read_b128 v[220:223], v205 offset:35840
	ds_read_b128 v[224:227], v205 offset:36864
	ds_read_b128 v[228:231], v205 offset:37888
	ds_read_b128 v[232:235], v205 offset:38912
	ds_read_b128 v[236:239], v205 offset:39936
	global_load_lds_dwordx4 v[248:249], off
	v_lshl_add_u64 v[196:197], v[196:197], 0, v[174:175]
	s_mov_b32 m0, s34
	s_nop 0
	global_load_lds_dwordx4 v[196:197], off
	s_waitcnt vmcnt(8)
	s_waitcnt lgkmcnt(0)
	s_barrier
	s_setprio 1
	s_waitcnt lgkmcnt(0)
	v_mfma_f32_16x16x32_bf16 v[62:65], v[138:141], v[208:211], v[62:65]
	v_mfma_f32_16x16x32_bf16 v[58:61], v[146:149], v[208:211], v[58:61]
	v_mfma_f32_16x16x32_bf16 v[54:57], v[138:141], v[216:219], v[54:57]
	v_mfma_f32_16x16x32_bf16 v[50:53], v[146:149], v[216:219], v[50:53]
	v_mfma_f32_16x16x32_bf16 v[46:49], v[138:141], v[224:227], v[46:49]
	v_mfma_f32_16x16x32_bf16 v[42:45], v[146:149], v[224:227], v[42:45]
	v_mfma_f32_16x16x32_bf16 v[38:41], v[138:141], v[232:235], v[38:41]
	v_mfma_f32_16x16x32_bf16 v[34:37], v[146:149], v[232:235], v[34:37]
	s_setprio 0
	s_setprio 1
	v_mfma_f32_16x16x32_bf16 v[62:65], v[142:145], v[212:215], v[62:65]
	v_mfma_f32_16x16x32_bf16 v[58:61], v[150:153], v[212:215], v[58:61]
	v_mfma_f32_16x16x32_bf16 v[54:57], v[142:145], v[220:223], v[54:57]
	v_mfma_f32_16x16x32_bf16 v[50:53], v[150:153], v[220:223], v[50:53]
	v_mfma_f32_16x16x32_bf16 v[46:49], v[142:145], v[228:231], v[46:49]
	v_mfma_f32_16x16x32_bf16 v[42:45], v[150:153], v[228:231], v[42:45]
	v_mfma_f32_16x16x32_bf16 v[38:41], v[142:145], v[236:239], v[38:41]
	v_mfma_f32_16x16x32_bf16 v[34:37], v[150:153], v[236:239], v[34:37]
	s_setprio 0
	s_setprio 1
	v_mfma_f32_16x16x32_bf16 v[30:33], v[154:157], v[208:211], v[30:33]
	v_mfma_f32_16x16x32_bf16 v[26:29], v[162:165], v[208:211], v[26:29]
	v_mfma_f32_16x16x32_bf16 v[22:25], v[154:157], v[216:219], v[22:25]
	v_mfma_f32_16x16x32_bf16 v[18:21], v[162:165], v[216:219], v[18:21]
	v_mfma_f32_16x16x32_bf16 v[14:17], v[154:157], v[224:227], v[14:17]
	v_mfma_f32_16x16x32_bf16 v[10:13], v[162:165], v[224:227], v[10:13]
	v_mfma_f32_16x16x32_bf16 v[6:9], v[154:157], v[232:235], v[6:9]
	v_mfma_f32_16x16x32_bf16 v[2:5], v[162:165], v[232:235], v[2:5]
	s_setprio 0
	s_setprio 1
	v_mfma_f32_16x16x32_bf16 v[30:33], v[158:161], v[212:215], v[30:33]
	v_mfma_f32_16x16x32_bf16 v[26:29], v[192:195], v[212:215], v[26:29]
	v_mfma_f32_16x16x32_bf16 v[22:25], v[158:161], v[220:223], v[22:25]
	v_mfma_f32_16x16x32_bf16 v[18:21], v[192:195], v[220:223], v[18:21]
	v_mfma_f32_16x16x32_bf16 v[14:17], v[158:161], v[228:231], v[14:17]
	v_mfma_f32_16x16x32_bf16 v[10:13], v[192:195], v[228:231], v[10:13]
	v_mfma_f32_16x16x32_bf16 v[6:9], v[158:161], v[236:239], v[6:9]
	v_mfma_f32_16x16x32_bf16 v[2:5], v[192:195], v[236:239], v[2:5]
	s_setprio 0
	s_barrier
	s_add_i32 s31, s31, s0
	v_lshl_add_u64 v[196:197], v[240:241], 0, s[22:23]
	s_mov_b32 m0, s31
	ds_read_b128 v[208:211], v205 offset:49152
	ds_read_b128 v[212:215], v205 offset:50176
	ds_read_b128 v[216:219], v205 offset:51200
	ds_read_b128 v[220:223], v205 offset:52224
	ds_read_b128 v[224:227], v205 offset:53248
	ds_read_b128 v[228:231], v205 offset:54272
	ds_read_b128 v[232:235], v205 offset:55296
	ds_read_b128 v[236:239], v205 offset:56320
	global_load_lds_dwordx4 v[196:197], off
	v_lshl_add_u64 v[196:197], v[242:243], 0, s[22:23]
	s_add_i32 m0, s31, 0x2000
	s_add_i32 s31, s45, s0
	global_load_lds_dwordx4 v[196:197], off
	v_lshl_add_u64 v[196:197], v[198:199], 0, s[24:25]
	v_lshl_add_u64 v[198:199], v[196:197], 0, v[172:173]
	s_mov_b32 m0, s31
	v_lshl_add_u64 v[196:197], v[196:197], 0, v[174:175]
	global_load_lds_dwordx4 v[198:199], off
	s_add_i32 m0, s31, 0x2000
	s_nop 0
	global_load_lds_dwordx4 v[196:197], off
	v_lshl_add_u64 v[196:197], v[244:245], 0, s[22:23]
	s_mov_b32 m0, s56
	s_nop 0
	global_load_lds_dwordx4 v[196:197], off
	v_lshl_add_u64 v[196:197], v[246:247], 0, s[22:23]
	s_mov_b32 m0, s57
	s_nop 0
	global_load_lds_dwordx4 v[196:197], off
	s_waitcnt vmcnt(8)
	s_waitcnt lgkmcnt(0)
	s_barrier
	s_setprio 1
	s_waitcnt lgkmcnt(0)
	v_mfma_f32_16x16x32_bf16 v[126:129], v[138:141], v[208:211], v[126:129]
	v_mfma_f32_16x16x32_bf16 v[122:125], v[146:149], v[208:211], v[122:125]
	v_mfma_f32_16x16x32_bf16 v[118:121], v[138:141], v[216:219], v[118:121]
	v_mfma_f32_16x16x32_bf16 v[114:117], v[146:149], v[216:219], v[114:117]
	v_mfma_f32_16x16x32_bf16 v[110:113], v[138:141], v[224:227], v[110:113]
	v_mfma_f32_16x16x32_bf16 v[106:109], v[146:149], v[224:227], v[106:109]
	v_mfma_f32_16x16x32_bf16 v[102:105], v[138:141], v[232:235], v[102:105]
	v_mfma_f32_16x16x32_bf16 v[98:101], v[146:149], v[232:235], v[98:101]
	s_setprio 0
	s_setprio 1
	v_mfma_f32_16x16x32_bf16 v[126:129], v[142:145], v[212:215], v[126:129]
	v_mfma_f32_16x16x32_bf16 v[122:125], v[150:153], v[212:215], v[122:125]
	v_mfma_f32_16x16x32_bf16 v[118:121], v[142:145], v[220:223], v[118:121]
	v_mfma_f32_16x16x32_bf16 v[114:117], v[150:153], v[220:223], v[114:117]
	v_mfma_f32_16x16x32_bf16 v[110:113], v[142:145], v[228:231], v[110:113]
	v_mfma_f32_16x16x32_bf16 v[106:109], v[150:153], v[228:231], v[106:109]
	v_mfma_f32_16x16x32_bf16 v[102:105], v[142:145], v[236:239], v[102:105]
	v_mfma_f32_16x16x32_bf16 v[98:101], v[150:153], v[236:239], v[98:101]
	s_setprio 0
	s_setprio 1
	v_mfma_f32_16x16x32_bf16 v[94:97], v[154:157], v[208:211], v[94:97]
	v_mfma_f32_16x16x32_bf16 v[90:93], v[162:165], v[208:211], v[90:93]
	v_mfma_f32_16x16x32_bf16 v[86:89], v[154:157], v[216:219], v[86:89]
	v_mfma_f32_16x16x32_bf16 v[82:85], v[162:165], v[216:219], v[82:85]
	v_mfma_f32_16x16x32_bf16 v[78:81], v[154:157], v[224:227], v[78:81]
	v_mfma_f32_16x16x32_bf16 v[74:77], v[162:165], v[224:227], v[74:77]
	v_mfma_f32_16x16x32_bf16 v[70:73], v[154:157], v[232:235], v[70:73]
	v_mfma_f32_16x16x32_bf16 v[66:69], v[162:165], v[232:235], v[66:69]
	s_setprio 0
	s_setprio 1
	v_mfma_f32_16x16x32_bf16 v[94:97], v[158:161], v[212:215], v[94:97]
	v_mfma_f32_16x16x32_bf16 v[90:93], v[192:195], v[212:215], v[90:93]
	v_mfma_f32_16x16x32_bf16 v[86:89], v[158:161], v[220:223], v[86:89]
	v_mfma_f32_16x16x32_bf16 v[82:85], v[192:195], v[220:223], v[82:85]
	v_mfma_f32_16x16x32_bf16 v[78:81], v[158:161], v[228:231], v[78:81]
	v_mfma_f32_16x16x32_bf16 v[74:77], v[192:195], v[228:231], v[74:77]
	v_mfma_f32_16x16x32_bf16 v[70:73], v[158:161], v[236:239], v[70:73]
	v_mfma_f32_16x16x32_bf16 v[66:69], v[192:195], v[236:239], v[66:69]
	s_setprio 0
	s_barrier
	v_lshl_add_u64 v[134:135], v[134:135], 0, s[38:39]
	s_cmp_ge_i32 s13, s9
	v_lshl_add_u64 v[136:137], v[136:137], 0, s[38:39]
	s_cbranch_scc0 .LBB0_1065
	s_branch .Lpeel_exit_3
.LBB0_1065:
	v_add_u32_e32 v133, s65, v204
	ds_read_b128 v[138:141], v207
	ds_read_b128 v[142:145], v207 offset:1024
	ds_read_b128 v[146:149], v207 offset:2048
	ds_read_b128 v[150:153], v207 offset:3072
	ds_read_b128 v[154:157], v133
	ds_read_b128 v[158:161], v133 offset:1024
	ds_read_b128 v[162:165], v133 offset:2048
	ds_read_b128 v[192:195], v133 offset:3072
	s_cmp_eq_u32 s12, s13
	v_lshl_add_u64 v[196:197], v[134:135], 0, s[40:41]
	s_cselect_b64 vcc, -1, 0
	s_add_i32 s13, s13, 2
	v_cndmask_b32_e32 v197, v197, v1, vcc
	v_cndmask_b32_e32 v196, v196, v130, vcc
	v_cndmask_b32_e32 v199, v137, v131, vcc
	v_cndmask_b32_e32 v198, v136, v132, vcc
	v_lshl_add_u64 v[240:241], v[134:135], 0, v[184:185]
	s_add_i32 m0, s1, 0xc000
	ds_read_b128 v[208:211], v205
	ds_read_b128 v[212:215], v205 offset:1024
	ds_read_b128 v[216:219], v205 offset:2048
	ds_read_b128 v[220:223], v205 offset:3072
	ds_read_b128 v[224:227], v205 offset:4096
	ds_read_b128 v[228:231], v205 offset:5120
	ds_read_b128 v[232:235], v205 offset:6144
	ds_read_b128 v[236:239], v205 offset:7168
	global_load_lds_dwordx4 v[240:241], off
	v_lshl_add_u64 v[240:241], v[134:135], 0, v[186:187]
	s_add_i32 m0, s1, 0xe000
	s_nop 0
	global_load_lds_dwordx4 v[240:241], off
	s_waitcnt vmcnt(8)
	s_waitcnt lgkmcnt(0)
	s_barrier
	s_setprio 1
	s_waitcnt lgkmcnt(0)
	v_mfma_f32_16x16x32_bf16 v[62:65], v[138:141], v[208:211], v[62:65]
	v_mfma_f32_16x16x32_bf16 v[58:61], v[146:149], v[208:211], v[58:61]
	v_mfma_f32_16x16x32_bf16 v[54:57], v[138:141], v[216:219], v[54:57]
	v_mfma_f32_16x16x32_bf16 v[50:53], v[146:149], v[216:219], v[50:53]
	v_mfma_f32_16x16x32_bf16 v[46:49], v[138:141], v[224:227], v[46:49]
	v_mfma_f32_16x16x32_bf16 v[42:45], v[146:149], v[224:227], v[42:45]
	v_mfma_f32_16x16x32_bf16 v[38:41], v[138:141], v[232:235], v[38:41]
	v_mfma_f32_16x16x32_bf16 v[34:37], v[146:149], v[232:235], v[34:37]
	s_setprio 0
	s_setprio 1
	v_mfma_f32_16x16x32_bf16 v[62:65], v[142:145], v[212:215], v[62:65]
	v_mfma_f32_16x16x32_bf16 v[58:61], v[150:153], v[212:215], v[58:61]
	v_mfma_f32_16x16x32_bf16 v[54:57], v[142:145], v[220:223], v[54:57]
	v_mfma_f32_16x16x32_bf16 v[50:53], v[150:153], v[220:223], v[50:53]
	v_mfma_f32_16x16x32_bf16 v[46:49], v[142:145], v[228:231], v[46:49]
	v_mfma_f32_16x16x32_bf16 v[42:45], v[150:153], v[228:231], v[42:45]
	v_mfma_f32_16x16x32_bf16 v[38:41], v[142:145], v[236:239], v[38:41]
	v_mfma_f32_16x16x32_bf16 v[34:37], v[150:153], v[236:239], v[34:37]
	s_setprio 0
	s_setprio 1
	v_mfma_f32_16x16x32_bf16 v[30:33], v[154:157], v[208:211], v[30:33]
	v_mfma_f32_16x16x32_bf16 v[26:29], v[162:165], v[208:211], v[26:29]
	v_mfma_f32_16x16x32_bf16 v[22:25], v[154:157], v[216:219], v[22:25]
	v_mfma_f32_16x16x32_bf16 v[18:21], v[162:165], v[216:219], v[18:21]
	v_mfma_f32_16x16x32_bf16 v[14:17], v[154:157], v[224:227], v[14:17]
	v_mfma_f32_16x16x32_bf16 v[10:13], v[162:165], v[224:227], v[10:13]
	v_mfma_f32_16x16x32_bf16 v[6:9], v[154:157], v[232:235], v[6:9]
	v_mfma_f32_16x16x32_bf16 v[2:5], v[162:165], v[232:235], v[2:5]
	s_setprio 0
	s_setprio 1
	v_mfma_f32_16x16x32_bf16 v[30:33], v[158:161], v[212:215], v[30:33]
	v_mfma_f32_16x16x32_bf16 v[26:29], v[192:195], v[212:215], v[26:29]
	v_mfma_f32_16x16x32_bf16 v[22:25], v[158:161], v[220:223], v[22:25]
	v_mfma_f32_16x16x32_bf16 v[18:21], v[192:195], v[220:223], v[18:21]
	v_mfma_f32_16x16x32_bf16 v[14:17], v[158:161], v[228:231], v[14:17]
	v_mfma_f32_16x16x32_bf16 v[10:13], v[192:195], v[228:231], v[10:13]
	v_mfma_f32_16x16x32_bf16 v[6:9], v[158:161], v[236:239], v[6:9]
	v_mfma_f32_16x16x32_bf16 v[2:5], v[192:195], v[236:239], v[2:5]
	s_setprio 0
	s_barrier
	s_add_i32 s31, s64, s0
	v_lshl_add_u64 v[240:241], v[198:199], 0, v[172:173]
	s_mov_b32 m0, s31
	ds_read_b128 v[208:211], v205 offset:16384
	ds_read_b128 v[212:215], v205 offset:17408
	ds_read_b128 v[216:219], v205 offset:18432
	ds_read_b128 v[220:223], v205 offset:19456
	ds_read_b128 v[224:227], v205 offset:20480
	ds_read_b128 v[228:231], v205 offset:21504
	ds_read_b128 v[232:235], v205 offset:22528
	ds_read_b128 v[236:239], v205 offset:23552
	global_load_lds_dwordx4 v[240:241], off
	v_lshl_add_u64 v[242:243], v[198:199], 0, v[174:175]
	s_add_i32 m0, s31, 0x2000
	v_lshl_add_u64 v[244:245], v[198:199], 0, s[18:19]
	s_add_i32 s31, s65, s0
	global_load_lds_dwordx4 v[242:243], off
	v_lshl_add_u64 v[246:247], v[244:245], 0, v[172:173]
	s_mov_b32 m0, s31
	v_lshl_add_u64 v[244:245], v[244:245], 0, v[174:175]
	global_load_lds_dwordx4 v[246:247], off
	s_add_i32 m0, s31, 0x2000
	v_lshl_add_u64 v[246:247], v[196:197], 0, v[174:175]
	global_load_lds_dwordx4 v[244:245], off
	v_lshl_add_u64 v[244:245], v[196:197], 0, v[172:173]
	s_mov_b32 m0, s1
	s_nop 0
	global_load_lds_dwordx4 v[244:245], off
	s_mov_b32 m0, s2
	s_nop 0
	global_load_lds_dwordx4 v[246:247], off
	s_waitcnt vmcnt(8)
	s_waitcnt lgkmcnt(0)
	s_barrier
	s_setprio 1
	s_waitcnt lgkmcnt(0)
	v_mfma_f32_16x16x32_bf16 v[126:129], v[138:141], v[208:211], v[126:129]
	v_mfma_f32_16x16x32_bf16 v[122:125], v[146:149], v[208:211], v[122:125]
	v_mfma_f32_16x16x32_bf16 v[118:121], v[138:141], v[216:219], v[118:121]
	v_mfma_f32_16x16x32_bf16 v[114:117], v[146:149], v[216:219], v[114:117]
	v_mfma_f32_16x16x32_bf16 v[110:113], v[138:141], v[224:227], v[110:113]
	v_mfma_f32_16x16x32_bf16 v[106:109], v[146:149], v[224:227], v[106:109]
	v_mfma_f32_16x16x32_bf16 v[102:105], v[138:141], v[232:235], v[102:105]
	v_mfma_f32_16x16x32_bf16 v[98:101], v[146:149], v[232:235], v[98:101]
	s_setprio 0
	s_setprio 1
	v_mfma_f32_16x16x32_bf16 v[126:129], v[142:145], v[212:215], v[126:129]
	v_mfma_f32_16x16x32_bf16 v[122:125], v[150:153], v[212:215], v[122:125]
	v_mfma_f32_16x16x32_bf16 v[118:121], v[142:145], v[220:223], v[118:121]
	v_mfma_f32_16x16x32_bf16 v[114:117], v[150:153], v[220:223], v[114:117]
	v_mfma_f32_16x16x32_bf16 v[110:113], v[142:145], v[228:231], v[110:113]
	v_mfma_f32_16x16x32_bf16 v[106:109], v[150:153], v[228:231], v[106:109]
	v_mfma_f32_16x16x32_bf16 v[102:105], v[142:145], v[236:239], v[102:105]
	v_mfma_f32_16x16x32_bf16 v[98:101], v[150:153], v[236:239], v[98:101]
	s_setprio 0
	s_setprio 1
	v_mfma_f32_16x16x32_bf16 v[94:97], v[154:157], v[208:211], v[94:97]
	v_mfma_f32_16x16x32_bf16 v[90:93], v[162:165], v[208:211], v[90:93]
	v_mfma_f32_16x16x32_bf16 v[86:89], v[154:157], v[216:219], v[86:89]
	v_mfma_f32_16x16x32_bf16 v[82:85], v[162:165], v[216:219], v[82:85]
	v_mfma_f32_16x16x32_bf16 v[78:81], v[154:157], v[224:227], v[78:81]
	v_mfma_f32_16x16x32_bf16 v[74:77], v[162:165], v[224:227], v[74:77]
	v_mfma_f32_16x16x32_bf16 v[70:73], v[154:157], v[232:235], v[70:73]
	v_mfma_f32_16x16x32_bf16 v[66:69], v[162:165], v[232:235], v[66:69]
	s_setprio 0
	s_setprio 1
	v_mfma_f32_16x16x32_bf16 v[94:97], v[158:161], v[212:215], v[94:97]
	v_mfma_f32_16x16x32_bf16 v[90:93], v[192:195], v[212:215], v[90:93]
	v_mfma_f32_16x16x32_bf16 v[86:89], v[158:161], v[220:223], v[86:89]
	v_mfma_f32_16x16x32_bf16 v[82:85], v[192:195], v[220:223], v[82:85]
	v_mfma_f32_16x16x32_bf16 v[78:81], v[158:161], v[228:231], v[78:81]
	v_mfma_f32_16x16x32_bf16 v[74:77], v[192:195], v[228:231], v[74:77]
	v_mfma_f32_16x16x32_bf16 v[70:73], v[158:161], v[236:239], v[70:73]
	v_mfma_f32_16x16x32_bf16 v[66:69], v[192:195], v[236:239], v[66:69]
	s_setprio 0
	s_barrier
	s_add_i32 s31, 0, 0x18000
	v_add_u32_e32 v133, s31, v204
	s_add_i32 s45, 0, 0x1c000
	ds_read_b128 v[138:141], v133
	ds_read_b128 v[142:145], v133 offset:1024
	ds_read_b128 v[146:149], v133 offset:2048
	ds_read_b128 v[150:153], v133 offset:3072
	v_add_u32_e32 v133, s45, v204
	ds_read_b128 v[154:157], v133
	ds_read_b128 v[158:161], v133 offset:1024
	ds_read_b128 v[162:165], v133 offset:2048
	ds_read_b128 v[192:195], v133 offset:3072
	v_lshl_add_u64 v[196:197], v[196:197], 0, s[18:19]
	s_mov_b32 m0, s33
	v_lshl_add_u64 v[248:249], v[196:197], 0, v[172:173]
	ds_read_b128 v[208:211], v205 offset:32768
	ds_read_b128 v[212:215], v205 offset:33792
	ds_read_b128 v[216:219], v205 offset:34816
	ds_read_b128 v[220:223], v205 offset:35840
	ds_read_b128 v[224:227], v205 offset:36864
	ds_read_b128 v[228:231], v205 offset:37888
	ds_read_b128 v[232:235], v205 offset:38912
	ds_read_b128 v[236:239], v205 offset:39936
	global_load_lds_dwordx4 v[248:249], off
	v_lshl_add_u64 v[196:197], v[196:197], 0, v[174:175]
	s_mov_b32 m0, s34
	s_nop 0
	global_load_lds_dwordx4 v[196:197], off
	s_waitcnt vmcnt(8)
	s_waitcnt lgkmcnt(0)
	s_barrier
	s_setprio 1
	s_waitcnt lgkmcnt(0)
	v_mfma_f32_16x16x32_bf16 v[62:65], v[138:141], v[208:211], v[62:65]
	v_mfma_f32_16x16x32_bf16 v[58:61], v[146:149], v[208:211], v[58:61]
	v_mfma_f32_16x16x32_bf16 v[54:57], v[138:141], v[216:219], v[54:57]
	v_mfma_f32_16x16x32_bf16 v[50:53], v[146:149], v[216:219], v[50:53]
	v_mfma_f32_16x16x32_bf16 v[46:49], v[138:141], v[224:227], v[46:49]
	v_mfma_f32_16x16x32_bf16 v[42:45], v[146:149], v[224:227], v[42:45]
	v_mfma_f32_16x16x32_bf16 v[38:41], v[138:141], v[232:235], v[38:41]
	v_mfma_f32_16x16x32_bf16 v[34:37], v[146:149], v[232:235], v[34:37]
	s_setprio 0
	s_setprio 1
	v_mfma_f32_16x16x32_bf16 v[62:65], v[142:145], v[212:215], v[62:65]
	v_mfma_f32_16x16x32_bf16 v[58:61], v[150:153], v[212:215], v[58:61]
	v_mfma_f32_16x16x32_bf16 v[54:57], v[142:145], v[220:223], v[54:57]
	v_mfma_f32_16x16x32_bf16 v[50:53], v[150:153], v[220:223], v[50:53]
	v_mfma_f32_16x16x32_bf16 v[46:49], v[142:145], v[228:231], v[46:49]
	v_mfma_f32_16x16x32_bf16 v[42:45], v[150:153], v[228:231], v[42:45]
	v_mfma_f32_16x16x32_bf16 v[38:41], v[142:145], v[236:239], v[38:41]
	v_mfma_f32_16x16x32_bf16 v[34:37], v[150:153], v[236:239], v[34:37]
	s_setprio 0
	s_setprio 1
	v_mfma_f32_16x16x32_bf16 v[30:33], v[154:157], v[208:211], v[30:33]
	v_mfma_f32_16x16x32_bf16 v[26:29], v[162:165], v[208:211], v[26:29]
	v_mfma_f32_16x16x32_bf16 v[22:25], v[154:157], v[216:219], v[22:25]
	v_mfma_f32_16x16x32_bf16 v[18:21], v[162:165], v[216:219], v[18:21]
	v_mfma_f32_16x16x32_bf16 v[14:17], v[154:157], v[224:227], v[14:17]
	v_mfma_f32_16x16x32_bf16 v[10:13], v[162:165], v[224:227], v[10:13]
	v_mfma_f32_16x16x32_bf16 v[6:9], v[154:157], v[232:235], v[6:9]
	v_mfma_f32_16x16x32_bf16 v[2:5], v[162:165], v[232:235], v[2:5]
	s_setprio 0
	s_setprio 1
	v_mfma_f32_16x16x32_bf16 v[30:33], v[158:161], v[212:215], v[30:33]
	v_mfma_f32_16x16x32_bf16 v[26:29], v[192:195], v[212:215], v[26:29]
	v_mfma_f32_16x16x32_bf16 v[22:25], v[158:161], v[220:223], v[22:25]
	v_mfma_f32_16x16x32_bf16 v[18:21], v[192:195], v[220:223], v[18:21]
	v_mfma_f32_16x16x32_bf16 v[14:17], v[158:161], v[228:231], v[14:17]
	v_mfma_f32_16x16x32_bf16 v[10:13], v[192:195], v[228:231], v[10:13]
	v_mfma_f32_16x16x32_bf16 v[6:9], v[158:161], v[236:239], v[6:9]
	v_mfma_f32_16x16x32_bf16 v[2:5], v[192:195], v[236:239], v[2:5]
	s_setprio 0
	s_barrier
	s_add_i32 s31, s31, s0
	v_lshl_add_u64 v[196:197], v[240:241], 0, s[22:23]
	s_mov_b32 m0, s31
	ds_read_b128 v[208:211], v205 offset:49152
	ds_read_b128 v[212:215], v205 offset:50176
	ds_read_b128 v[216:219], v205 offset:51200
	ds_read_b128 v[220:223], v205 offset:52224
	ds_read_b128 v[224:227], v205 offset:53248
	ds_read_b128 v[228:231], v205 offset:54272
	ds_read_b128 v[232:235], v205 offset:55296
	ds_read_b128 v[236:239], v205 offset:56320
	global_load_lds_dwordx4 v[196:197], off
	v_lshl_add_u64 v[196:197], v[242:243], 0, s[22:23]
	s_add_i32 m0, s31, 0x2000
	s_add_i32 s31, s45, s0
	global_load_lds_dwordx4 v[196:197], off
	v_lshl_add_u64 v[196:197], v[198:199], 0, s[24:25]
	v_lshl_add_u64 v[198:199], v[196:197], 0, v[172:173]
	s_mov_b32 m0, s31
	v_lshl_add_u64 v[196:197], v[196:197], 0, v[174:175]
	global_load_lds_dwordx4 v[198:199], off
	s_add_i32 m0, s31, 0x2000
	s_nop 0
	global_load_lds_dwordx4 v[196:197], off
	v_lshl_add_u64 v[196:197], v[244:245], 0, s[22:23]
	s_mov_b32 m0, s56
	s_nop 0
	global_load_lds_dwordx4 v[196:197], off
	v_lshl_add_u64 v[196:197], v[246:247], 0, s[22:23]
	s_mov_b32 m0, s57
	s_nop 0
	global_load_lds_dwordx4 v[196:197], off
	s_waitcnt vmcnt(8)
	s_waitcnt lgkmcnt(0)
	s_barrier
	s_setprio 1
	s_waitcnt lgkmcnt(0)
	v_mfma_f32_16x16x32_bf16 v[126:129], v[138:141], v[208:211], v[126:129]
	v_mfma_f32_16x16x32_bf16 v[122:125], v[146:149], v[208:211], v[122:125]
	v_mfma_f32_16x16x32_bf16 v[118:121], v[138:141], v[216:219], v[118:121]
	v_mfma_f32_16x16x32_bf16 v[114:117], v[146:149], v[216:219], v[114:117]
	v_mfma_f32_16x16x32_bf16 v[110:113], v[138:141], v[224:227], v[110:113]
	v_mfma_f32_16x16x32_bf16 v[106:109], v[146:149], v[224:227], v[106:109]
	v_mfma_f32_16x16x32_bf16 v[102:105], v[138:141], v[232:235], v[102:105]
	v_mfma_f32_16x16x32_bf16 v[98:101], v[146:149], v[232:235], v[98:101]
	s_setprio 0
	s_setprio 1
	v_mfma_f32_16x16x32_bf16 v[126:129], v[142:145], v[212:215], v[126:129]
	v_mfma_f32_16x16x32_bf16 v[122:125], v[150:153], v[212:215], v[122:125]
	v_mfma_f32_16x16x32_bf16 v[118:121], v[142:145], v[220:223], v[118:121]
	v_mfma_f32_16x16x32_bf16 v[114:117], v[150:153], v[220:223], v[114:117]
	v_mfma_f32_16x16x32_bf16 v[110:113], v[142:145], v[228:231], v[110:113]
	v_mfma_f32_16x16x32_bf16 v[106:109], v[150:153], v[228:231], v[106:109]
	v_mfma_f32_16x16x32_bf16 v[102:105], v[142:145], v[236:239], v[102:105]
	v_mfma_f32_16x16x32_bf16 v[98:101], v[150:153], v[236:239], v[98:101]
	s_setprio 0
	s_setprio 1
	v_mfma_f32_16x16x32_bf16 v[94:97], v[154:157], v[208:211], v[94:97]
	v_mfma_f32_16x16x32_bf16 v[90:93], v[162:165], v[208:211], v[90:93]
	v_mfma_f32_16x16x32_bf16 v[86:89], v[154:157], v[216:219], v[86:89]
	v_mfma_f32_16x16x32_bf16 v[82:85], v[162:165], v[216:219], v[82:85]
	v_mfma_f32_16x16x32_bf16 v[78:81], v[154:157], v[224:227], v[78:81]
	v_mfma_f32_16x16x32_bf16 v[74:77], v[162:165], v[224:227], v[74:77]
	v_mfma_f32_16x16x32_bf16 v[70:73], v[154:157], v[232:235], v[70:73]
	v_mfma_f32_16x16x32_bf16 v[66:69], v[162:165], v[232:235], v[66:69]
	s_setprio 0
	s_setprio 1
	v_mfma_f32_16x16x32_bf16 v[94:97], v[158:161], v[212:215], v[94:97]
	v_mfma_f32_16x16x32_bf16 v[90:93], v[192:195], v[212:215], v[90:93]
	v_mfma_f32_16x16x32_bf16 v[86:89], v[158:161], v[220:223], v[86:89]
	v_mfma_f32_16x16x32_bf16 v[82:85], v[192:195], v[220:223], v[82:85]
	v_mfma_f32_16x16x32_bf16 v[78:81], v[158:161], v[228:231], v[78:81]
	v_mfma_f32_16x16x32_bf16 v[74:77], v[192:195], v[228:231], v[74:77]
	v_mfma_f32_16x16x32_bf16 v[70:73], v[158:161], v[236:239], v[70:73]
	v_mfma_f32_16x16x32_bf16 v[66:69], v[192:195], v[236:239], v[66:69]
	s_setprio 0
	s_barrier
	v_lshl_add_u64 v[134:135], v[134:135], 0, s[38:39]
	s_cmp_ge_i32 s13, s9
	v_lshl_add_u64 v[136:137], v[136:137], 0, s[38:39]
	s_cbranch_scc0 .LBB0_1065

.LBB0_1251:
	s_ashr_i32 s47, s46, 31
	s_lshl_b64 s[8:9], s[46:47], 19
	s_ashr_i32 s45, s44, 31
	v_lshl_add_u64 v[170:171], v[146:147], 0, s[8:9]
	s_lshl_b64 s[8:9], s[44:45], 19
	v_lshl_add_u64 v[172:173], v[148:149], 0, s[8:9]
	s_waitcnt vmcnt(0)
	v_cndmask_b32_e64 v84, v2, v172, s[4:5]
	v_lshl_add_u64 v[88:89], v[2:3], 0, s[40:41]
	v_mov_b32_e32 v2, 0
	v_cndmask_b32_e64 v1, v5, v171, s[4:5]
	v_cndmask_b32_e64 v82, v4, v170, s[4:5]
	v_cndmask_b32_e64 v83, v3, v173, s[4:5]
	v_lshl_add_u64 v[86:87], v[4:5], 0, s[28:29]
	s_mov_b32 s7, -2
	ds_read_b128 v[94:97], v181
	ds_read_b128 v[98:101], v181 offset:1024
	ds_read_b128 v[174:177], v181 offset:2048
	ds_read_b128 v[186:189], v181 offset:3072
	ds_read_b128 v[190:193], v183
	ds_read_b128 v[194:197], v183 offset:1024
	ds_read_b128 v[200:203], v183 offset:2048
	ds_read_b128 v[204:207], v183 offset:3072
	s_cmp_eq_u32 s7, 12
	v_lshl_add_u64 v[198:199], v[86:87], 0, s[42:43]
	s_cselect_b64 vcc, -1, 0
	v_cndmask_b32_e32 v199, v199, v1, vcc
	v_cndmask_b32_e32 v198, v198, v82, vcc
	v_cndmask_b32_e32 v241, v89, v83, vcc
	v_cndmask_b32_e32 v240, v88, v84, vcc
	v_lshl_add_u64 v[242:243], v[86:87], 0, v[160:161]
	s_add_i32 m0, s1, 0xc000
	ds_read_b128 v[208:211], v182
	ds_read_b128 v[212:215], v182 offset:1024
	ds_read_b128 v[216:219], v182 offset:2048
	ds_read_b128 v[220:223], v182 offset:3072
	ds_read_b128 v[224:227], v182 offset:4096
	ds_read_b128 v[228:231], v182 offset:5120
	ds_read_b128 v[232:235], v182 offset:6144
	ds_read_b128 v[236:239], v182 offset:7168
	global_load_lds_dwordx4 v[242:243], off
	v_lshl_add_u64 v[242:243], v[86:87], 0, v[162:163]
	s_add_i32 m0, s1, 0xe000
	s_nop 0
	global_load_lds_dwordx4 v[242:243], off
	s_waitcnt vmcnt(8)
	s_waitcnt lgkmcnt(0)
	s_barrier
	s_setprio 1
	s_waitcnt lgkmcnt(0)
	v_mfma_f32_16x16x32_bf16 v[102:105], v[94:97], v[208:211], 0
	v_mfma_f32_16x16x32_bf16 v[142:145], v[174:177], v[208:211], 0
	v_mfma_f32_16x16x32_bf16 v[62:65], v[94:97], v[216:219], 0
	v_mfma_f32_16x16x32_bf16 v[110:113], v[174:177], v[216:219], 0
	v_mfma_f32_16x16x32_bf16 v[46:49], v[94:97], v[224:227], 0
	v_mfma_f32_16x16x32_bf16 v[78:81], v[174:177], v[224:227], 0
	v_mfma_f32_16x16x32_bf16 v[38:41], v[94:97], v[232:235], 0
	v_mfma_f32_16x16x32_bf16 v[134:137], v[174:177], v[232:235], 0
	s_setprio 0
	s_setprio 1
	v_mfma_f32_16x16x32_bf16 v[102:105], v[98:101], v[212:215], v[102:105]
	v_mfma_f32_16x16x32_bf16 v[142:145], v[186:189], v[212:215], v[142:145]
	v_mfma_f32_16x16x32_bf16 v[62:65], v[98:101], v[220:223], v[62:65]
	v_mfma_f32_16x16x32_bf16 v[110:113], v[186:189], v[220:223], v[110:113]
	v_mfma_f32_16x16x32_bf16 v[46:49], v[98:101], v[228:231], v[46:49]
	v_mfma_f32_16x16x32_bf16 v[78:81], v[186:189], v[228:231], v[78:81]
	v_mfma_f32_16x16x32_bf16 v[38:41], v[98:101], v[236:239], v[38:41]
	v_mfma_f32_16x16x32_bf16 v[134:137], v[186:189], v[236:239], v[134:137]
	s_setprio 0
	s_setprio 1
	v_mfma_f32_16x16x32_bf16 v[138:141], v[190:193], v[208:211], 0
	v_mfma_f32_16x16x32_bf16 v[90:93], v[200:203], v[208:211], 0
	v_mfma_f32_16x16x32_bf16 v[106:109], v[190:193], v[216:219], 0
	v_mfma_f32_16x16x32_bf16 v[50:53], v[200:203], v[216:219], 0
	v_mfma_f32_16x16x32_bf16 v[74:77], v[190:193], v[224:227], 0
	v_mfma_f32_16x16x32_bf16 v[42:45], v[200:203], v[224:227], 0
	v_mfma_f32_16x16x32_bf16 v[130:133], v[190:193], v[232:235], 0
	v_mfma_f32_16x16x32_bf16 v[34:37], v[200:203], v[232:235], 0
	s_setprio 0
	s_setprio 1
	v_mfma_f32_16x16x32_bf16 v[138:141], v[194:197], v[212:215], v[138:141]
	v_mfma_f32_16x16x32_bf16 v[90:93], v[204:207], v[212:215], v[90:93]
	v_mfma_f32_16x16x32_bf16 v[106:109], v[194:197], v[220:223], v[106:109]
	v_mfma_f32_16x16x32_bf16 v[50:53], v[204:207], v[220:223], v[50:53]
	v_mfma_f32_16x16x32_bf16 v[74:77], v[194:197], v[228:231], v[74:77]
	v_mfma_f32_16x16x32_bf16 v[42:45], v[204:207], v[228:231], v[42:45]
	v_mfma_f32_16x16x32_bf16 v[130:133], v[194:197], v[236:239], v[130:133]
	v_mfma_f32_16x16x32_bf16 v[34:37], v[204:207], v[236:239], v[34:37]
	s_setprio 0
	s_barrier
	s_add_i32 s8, s55, s0
	v_lshl_add_u64 v[242:243], v[240:241], 0, v[150:151]
	s_mov_b32 m0, s8
	ds_read_b128 v[208:211], v182 offset:16384
	ds_read_b128 v[212:215], v182 offset:17408
	ds_read_b128 v[216:219], v182 offset:18432
	ds_read_b128 v[220:223], v182 offset:19456
	ds_read_b128 v[224:227], v182 offset:20480
	ds_read_b128 v[228:231], v182 offset:21504
	ds_read_b128 v[232:235], v182 offset:22528
	ds_read_b128 v[236:239], v182 offset:23552
	global_load_lds_dwordx4 v[242:243], off
	v_lshl_add_u64 v[244:245], v[240:241], 0, v[152:153]
	s_add_i32 m0, s8, 0x2000
	v_lshl_add_u64 v[246:247], v[240:241], 0, s[22:23]
	s_add_i32 s8, s56, s0
	global_load_lds_dwordx4 v[244:245], off
	v_lshl_add_u64 v[248:249], v[246:247], 0, v[150:151]
	s_mov_b32 m0, s8
	v_lshl_add_u64 v[246:247], v[246:247], 0, v[152:153]
	global_load_lds_dwordx4 v[248:249], off
	s_add_i32 m0, s8, 0x2000
	v_lshl_add_u64 v[248:249], v[198:199], 0, v[152:153]
	global_load_lds_dwordx4 v[246:247], off
	v_lshl_add_u64 v[246:247], v[198:199], 0, v[150:151]
	s_mov_b32 m0, s1
	s_nop 0
	global_load_lds_dwordx4 v[246:247], off
	s_mov_b32 m0, s2
	s_nop 0
	global_load_lds_dwordx4 v[248:249], off
	s_waitcnt vmcnt(8)
	s_waitcnt lgkmcnt(0)
	s_barrier
	s_setprio 1
	s_waitcnt lgkmcnt(0)
	v_mfma_f32_16x16x32_bf16 v[30:33], v[94:97], v[208:211], 0
	v_mfma_f32_16x16x32_bf16 v[126:129], v[174:177], v[208:211], 0
	v_mfma_f32_16x16x32_bf16 v[22:25], v[94:97], v[216:219], 0
	v_mfma_f32_16x16x32_bf16 v[70:73], v[174:177], v[216:219], 0
	v_mfma_f32_16x16x32_bf16 v[14:17], v[94:97], v[224:227], 0
	v_mfma_f32_16x16x32_bf16 v[66:69], v[174:177], v[224:227], 0
	v_mfma_f32_16x16x32_bf16 v[6:9], v[94:97], v[232:235], 0
	v_mfma_f32_16x16x32_bf16 v[30:33], v[98:101], v[212:215], v[30:33]
	s_setprio 0
	s_setprio 1
	v_mfma_f32_16x16x32_bf16 v[126:129], v[186:189], v[212:215], v[126:129]
	v_mfma_f32_16x16x32_bf16 v[22:25], v[98:101], v[220:223], v[22:25]
	v_mfma_f32_16x16x32_bf16 v[70:73], v[186:189], v[220:223], v[70:73]
	v_mfma_f32_16x16x32_bf16 v[14:17], v[98:101], v[228:231], v[14:17]
	v_mfma_f32_16x16x32_bf16 v[66:69], v[186:189], v[228:231], v[66:69]
	v_mfma_f32_16x16x32_bf16 v[6:9], v[98:101], v[236:239], v[6:9]
	v_mfma_f32_16x16x32_bf16 v[94:97], v[174:177], v[232:235], 0
	v_mfma_f32_16x16x32_bf16 v[94:97], v[186:189], v[236:239], v[94:97]
	s_setprio 0
	s_setprio 1
	v_mfma_f32_16x16x32_bf16 v[26:29], v[200:203], v[208:211], 0
	v_mfma_f32_16x16x32_bf16 v[58:61], v[190:193], v[216:219], 0
	v_mfma_f32_16x16x32_bf16 v[18:21], v[200:203], v[216:219], 0
	v_mfma_f32_16x16x32_bf16 v[54:57], v[190:193], v[224:227], 0
	v_mfma_f32_16x16x32_bf16 v[10:13], v[200:203], v[224:227], 0
	v_mfma_f32_16x16x32_bf16 v[114:117], v[190:193], v[232:235], 0
	v_mfma_f32_16x16x32_bf16 v[2:5], v[200:203], v[232:235], 0
	v_mfma_f32_16x16x32_bf16 v[98:101], v[190:193], v[208:211], 0
	s_setprio 0
	s_setprio 1
	v_mfma_f32_16x16x32_bf16 v[26:29], v[204:207], v[212:215], v[26:29]
	v_mfma_f32_16x16x32_bf16 v[58:61], v[194:197], v[220:223], v[58:61]
	v_mfma_f32_16x16x32_bf16 v[18:21], v[204:207], v[220:223], v[18:21]
	v_mfma_f32_16x16x32_bf16 v[54:57], v[194:197], v[228:231], v[54:57]
	v_mfma_f32_16x16x32_bf16 v[10:13], v[204:207], v[228:231], v[10:13]
	v_mfma_f32_16x16x32_bf16 v[114:117], v[194:197], v[236:239], v[114:117]
	v_mfma_f32_16x16x32_bf16 v[2:5], v[204:207], v[236:239], v[2:5]
	v_mfma_f32_16x16x32_bf16 v[98:101], v[194:197], v[212:215], v[98:101]
	s_setprio 0
	s_barrier
	s_add_i32 s8, 0, 0x18000
	v_add_u32_e32 v85, s8, v180
	s_add_i32 s9, 0, 0x1c000
	ds_read_b128 v[118:121], v85
	ds_read_b128 v[122:125], v85 offset:1024
	ds_read_b128 v[174:177], v85 offset:2048
	ds_read_b128 v[186:189], v85 offset:3072
	v_add_u32_e32 v85, s9, v180
	ds_read_b128 v[190:193], v85
	ds_read_b128 v[194:197], v85 offset:1024
	ds_read_b128 v[200:203], v85 offset:2048
	ds_read_b128 v[204:207], v85 offset:3072
	v_lshl_add_u64 v[198:199], v[198:199], 0, s[22:23]
	s_mov_b32 m0, s3
	v_lshl_add_u64 v[250:251], v[198:199], 0, v[150:151]
	ds_read_b128 v[208:211], v182 offset:32768
	ds_read_b128 v[212:215], v182 offset:33792
	ds_read_b128 v[216:219], v182 offset:34816
	ds_read_b128 v[220:223], v182 offset:35840
	ds_read_b128 v[224:227], v182 offset:36864
	ds_read_b128 v[228:231], v182 offset:37888
	ds_read_b128 v[232:235], v182 offset:38912
	ds_read_b128 v[236:239], v182 offset:39936
	global_load_lds_dwordx4 v[250:251], off
	v_lshl_add_u64 v[198:199], v[198:199], 0, v[152:153]
	s_mov_b32 m0, s21
	s_nop 0
	global_load_lds_dwordx4 v[198:199], off
	s_waitcnt vmcnt(8)
	s_waitcnt lgkmcnt(0)
	s_barrier
	s_setprio 1
	s_waitcnt lgkmcnt(0)
	v_mfma_f32_16x16x32_bf16 v[102:105], v[118:121], v[208:211], v[102:105]
	v_mfma_f32_16x16x32_bf16 v[142:145], v[174:177], v[208:211], v[142:145]
	v_mfma_f32_16x16x32_bf16 v[62:65], v[118:121], v[216:219], v[62:65]
	v_mfma_f32_16x16x32_bf16 v[110:113], v[174:177], v[216:219], v[110:113]
	v_mfma_f32_16x16x32_bf16 v[46:49], v[118:121], v[224:227], v[46:49]
	v_mfma_f32_16x16x32_bf16 v[78:81], v[174:177], v[224:227], v[78:81]
	v_mfma_f32_16x16x32_bf16 v[38:41], v[118:121], v[232:235], v[38:41]
	v_mfma_f32_16x16x32_bf16 v[134:137], v[174:177], v[232:235], v[134:137]
	s_setprio 0
	s_setprio 1
	v_mfma_f32_16x16x32_bf16 v[102:105], v[122:125], v[212:215], v[102:105]
	v_mfma_f32_16x16x32_bf16 v[142:145], v[186:189], v[212:215], v[142:145]
	v_mfma_f32_16x16x32_bf16 v[62:65], v[122:125], v[220:223], v[62:65]
	v_mfma_f32_16x16x32_bf16 v[110:113], v[186:189], v[220:223], v[110:113]
	v_mfma_f32_16x16x32_bf16 v[46:49], v[122:125], v[228:231], v[46:49]
	v_mfma_f32_16x16x32_bf16 v[78:81], v[186:189], v[228:231], v[78:81]
	v_mfma_f32_16x16x32_bf16 v[38:41], v[122:125], v[236:239], v[38:41]
	v_mfma_f32_16x16x32_bf16 v[134:137], v[186:189], v[236:239], v[134:137]
	s_setprio 0
	s_setprio 1
	v_mfma_f32_16x16x32_bf16 v[138:141], v[190:193], v[208:211], v[138:141]
	v_mfma_f32_16x16x32_bf16 v[90:93], v[200:203], v[208:211], v[90:93]
	v_mfma_f32_16x16x32_bf16 v[106:109], v[190:193], v[216:219], v[106:109]
	v_mfma_f32_16x16x32_bf16 v[50:53], v[200:203], v[216:219], v[50:53]
	v_mfma_f32_16x16x32_bf16 v[74:77], v[190:193], v[224:227], v[74:77]
	v_mfma_f32_16x16x32_bf16 v[42:45], v[200:203], v[224:227], v[42:45]
	v_mfma_f32_16x16x32_bf16 v[130:133], v[190:193], v[232:235], v[130:133]
	v_mfma_f32_16x16x32_bf16 v[34:37], v[200:203], v[232:235], v[34:37]
	s_setprio 0
	s_setprio 1
	v_mfma_f32_16x16x32_bf16 v[138:141], v[194:197], v[212:215], v[138:141]
	v_mfma_f32_16x16x32_bf16 v[90:93], v[204:207], v[212:215], v[90:93]
	v_mfma_f32_16x16x32_bf16 v[106:109], v[194:197], v[220:223], v[106:109]
	v_mfma_f32_16x16x32_bf16 v[50:53], v[204:207], v[220:223], v[50:53]
	v_mfma_f32_16x16x32_bf16 v[74:77], v[194:197], v[228:231], v[74:77]
	v_mfma_f32_16x16x32_bf16 v[42:45], v[204:207], v[228:231], v[42:45]
	v_mfma_f32_16x16x32_bf16 v[130:133], v[194:197], v[236:239], v[130:133]
	v_mfma_f32_16x16x32_bf16 v[34:37], v[204:207], v[236:239], v[34:37]
	s_setprio 0
	s_barrier
	s_add_i32 s8, s8, s0
	v_lshl_add_u64 v[198:199], v[242:243], 0, s[26:27]
	s_mov_b32 m0, s8
	ds_read_b128 v[208:211], v182 offset:49152
	ds_read_b128 v[212:215], v182 offset:50176
	ds_read_b128 v[216:219], v182 offset:51200
	ds_read_b128 v[220:223], v182 offset:52224
	ds_read_b128 v[224:227], v182 offset:53248
	ds_read_b128 v[228:231], v182 offset:54272
	ds_read_b128 v[232:235], v182 offset:55296
	ds_read_b128 v[236:239], v182 offset:56320
	global_load_lds_dwordx4 v[198:199], off
	v_lshl_add_u64 v[198:199], v[244:245], 0, s[26:27]
	s_add_i32 m0, s8, 0x2000
	s_add_i32 s8, s9, s0
	global_load_lds_dwordx4 v[198:199], off
	v_lshl_add_u64 v[198:199], v[240:241], 0, s[28:29]
	v_lshl_add_u64 v[240:241], v[198:199], 0, v[150:151]
	s_mov_b32 m0, s8
	v_lshl_add_u64 v[198:199], v[198:199], 0, v[152:153]
	global_load_lds_dwordx4 v[240:241], off
	s_add_i32 m0, s8, 0x2000
	s_nop 0
	global_load_lds_dwordx4 v[198:199], off
	v_lshl_add_u64 v[198:199], v[246:247], 0, s[26:27]
	s_mov_b32 m0, s35
	s_nop 0
	global_load_lds_dwordx4 v[198:199], off
	v_lshl_add_u64 v[198:199], v[248:249], 0, s[26:27]
	s_mov_b32 m0, s50
	s_nop 0
	global_load_lds_dwordx4 v[198:199], off
	s_waitcnt vmcnt(8)
	s_waitcnt lgkmcnt(0)
	s_barrier
	s_setprio 1
	s_waitcnt lgkmcnt(0)
	v_mfma_f32_16x16x32_bf16 v[30:33], v[118:121], v[208:211], v[30:33]
	v_mfma_f32_16x16x32_bf16 v[126:129], v[174:177], v[208:211], v[126:129]
	v_mfma_f32_16x16x32_bf16 v[22:25], v[118:121], v[216:219], v[22:25]
	v_mfma_f32_16x16x32_bf16 v[70:73], v[174:177], v[216:219], v[70:73]
	v_mfma_f32_16x16x32_bf16 v[14:17], v[118:121], v[224:227], v[14:17]
	v_mfma_f32_16x16x32_bf16 v[66:69], v[174:177], v[224:227], v[66:69]
	v_mfma_f32_16x16x32_bf16 v[6:9], v[118:121], v[232:235], v[6:9]
	v_mfma_f32_16x16x32_bf16 v[94:97], v[174:177], v[232:235], v[94:97]
	s_setprio 0
	s_setprio 1
	v_mfma_f32_16x16x32_bf16 v[30:33], v[122:125], v[212:215], v[30:33]
	v_mfma_f32_16x16x32_bf16 v[126:129], v[186:189], v[212:215], v[126:129]
	v_mfma_f32_16x16x32_bf16 v[22:25], v[122:125], v[220:223], v[22:25]
	v_mfma_f32_16x16x32_bf16 v[70:73], v[186:189], v[220:223], v[70:73]
	v_mfma_f32_16x16x32_bf16 v[14:17], v[122:125], v[228:231], v[14:17]
	v_mfma_f32_16x16x32_bf16 v[66:69], v[186:189], v[228:231], v[66:69]
	v_mfma_f32_16x16x32_bf16 v[6:9], v[122:125], v[236:239], v[6:9]
	v_mfma_f32_16x16x32_bf16 v[118:121], v[186:189], v[236:239], v[94:97]
	s_setprio 0
	s_setprio 1
	v_mfma_f32_16x16x32_bf16 v[94:97], v[190:193], v[208:211], v[98:101]
	v_mfma_f32_16x16x32_bf16 v[122:125], v[194:197], v[212:215], v[94:97]
	v_mfma_f32_16x16x32_bf16 v[26:29], v[200:203], v[208:211], v[26:29]
	v_mfma_f32_16x16x32_bf16 v[58:61], v[190:193], v[216:219], v[58:61]
	v_mfma_f32_16x16x32_bf16 v[18:21], v[200:203], v[216:219], v[18:21]
	v_mfma_f32_16x16x32_bf16 v[54:57], v[190:193], v[224:227], v[54:57]
	v_mfma_f32_16x16x32_bf16 v[10:13], v[200:203], v[224:227], v[10:13]
	v_mfma_f32_16x16x32_bf16 v[94:97], v[190:193], v[232:235], v[114:117]
	s_setprio 0
	s_setprio 1
	v_mfma_f32_16x16x32_bf16 v[2:5], v[200:203], v[232:235], v[2:5]
	v_mfma_f32_16x16x32_bf16 v[26:29], v[204:207], v[212:215], v[26:29]
	v_mfma_f32_16x16x32_bf16 v[58:61], v[194:197], v[220:223], v[58:61]
	v_mfma_f32_16x16x32_bf16 v[18:21], v[204:207], v[220:223], v[18:21]
	v_mfma_f32_16x16x32_bf16 v[54:57], v[194:197], v[228:231], v[54:57]
	v_mfma_f32_16x16x32_bf16 v[10:13], v[204:207], v[228:231], v[10:13]
	v_mfma_f32_16x16x32_bf16 v[114:117], v[194:197], v[236:239], v[94:97]
	v_mfma_f32_16x16x32_bf16 v[2:5], v[204:207], v[236:239], v[2:5]
	s_setprio 0
	s_barrier
	s_add_i32 s7, s7, 2
	v_lshl_add_u64 v[86:87], v[86:87], 0, s[40:41]
	s_cmp_gt_u32 s7, 13
	v_lshl_add_u64 v[88:89], v[88:89], 0, s[40:41]
	s_cbranch_scc0 .LBB0_1252
	s_branch .Lpeel_exit_4
.LBB0_1252:
	ds_read_b128 v[94:97], v181
	ds_read_b128 v[98:101], v181 offset:1024
	ds_read_b128 v[174:177], v181 offset:2048
	ds_read_b128 v[186:189], v181 offset:3072
	ds_read_b128 v[190:193], v183
	ds_read_b128 v[194:197], v183 offset:1024
	ds_read_b128 v[200:203], v183 offset:2048
	ds_read_b128 v[204:207], v183 offset:3072
	s_cmp_eq_u32 s7, 12
	v_lshl_add_u64 v[198:199], v[86:87], 0, s[42:43]
	s_cselect_b64 vcc, -1, 0
	v_cndmask_b32_e32 v199, v199, v1, vcc
	v_cndmask_b32_e32 v198, v198, v82, vcc
	v_cndmask_b32_e32 v241, v89, v83, vcc
	v_cndmask_b32_e32 v240, v88, v84, vcc
	v_lshl_add_u64 v[242:243], v[86:87], 0, v[160:161]
	s_add_i32 m0, s1, 0xc000
	ds_read_b128 v[208:211], v182
	ds_read_b128 v[212:215], v182 offset:1024
	ds_read_b128 v[216:219], v182 offset:2048
	ds_read_b128 v[220:223], v182 offset:3072
	ds_read_b128 v[224:227], v182 offset:4096
	ds_read_b128 v[228:231], v182 offset:5120
	ds_read_b128 v[232:235], v182 offset:6144
	ds_read_b128 v[236:239], v182 offset:7168
	global_load_lds_dwordx4 v[242:243], off
	v_lshl_add_u64 v[242:243], v[86:87], 0, v[162:163]
	s_add_i32 m0, s1, 0xe000
	s_nop 0
	global_load_lds_dwordx4 v[242:243], off
	s_waitcnt vmcnt(8)
	s_waitcnt lgkmcnt(0)
	s_barrier
	s_setprio 1
	s_waitcnt lgkmcnt(0)
	v_mfma_f32_16x16x32_bf16 v[102:105], v[94:97], v[208:211], v[102:105]
	v_mfma_f32_16x16x32_bf16 v[142:145], v[174:177], v[208:211], v[142:145]
	v_mfma_f32_16x16x32_bf16 v[62:65], v[94:97], v[216:219], v[62:65]
	v_mfma_f32_16x16x32_bf16 v[110:113], v[174:177], v[216:219], v[110:113]
	v_mfma_f32_16x16x32_bf16 v[46:49], v[94:97], v[224:227], v[46:49]
	v_mfma_f32_16x16x32_bf16 v[78:81], v[174:177], v[224:227], v[78:81]
	v_mfma_f32_16x16x32_bf16 v[38:41], v[94:97], v[232:235], v[38:41]
	v_mfma_f32_16x16x32_bf16 v[134:137], v[174:177], v[232:235], v[134:137]
	s_setprio 0
	s_setprio 1
	v_mfma_f32_16x16x32_bf16 v[102:105], v[98:101], v[212:215], v[102:105]
	v_mfma_f32_16x16x32_bf16 v[142:145], v[186:189], v[212:215], v[142:145]
	v_mfma_f32_16x16x32_bf16 v[62:65], v[98:101], v[220:223], v[62:65]
	v_mfma_f32_16x16x32_bf16 v[110:113], v[186:189], v[220:223], v[110:113]
	v_mfma_f32_16x16x32_bf16 v[46:49], v[98:101], v[228:231], v[46:49]
	v_mfma_f32_16x16x32_bf16 v[78:81], v[186:189], v[228:231], v[78:81]
	v_mfma_f32_16x16x32_bf16 v[38:41], v[98:101], v[236:239], v[38:41]
	v_mfma_f32_16x16x32_bf16 v[134:137], v[186:189], v[236:239], v[134:137]
	s_setprio 0
	s_setprio 1
	v_mfma_f32_16x16x32_bf16 v[138:141], v[190:193], v[208:211], v[138:141]
	v_mfma_f32_16x16x32_bf16 v[90:93], v[200:203], v[208:211], v[90:93]
	v_mfma_f32_16x16x32_bf16 v[106:109], v[190:193], v[216:219], v[106:109]
	v_mfma_f32_16x16x32_bf16 v[50:53], v[200:203], v[216:219], v[50:53]
	v_mfma_f32_16x16x32_bf16 v[74:77], v[190:193], v[224:227], v[74:77]
	v_mfma_f32_16x16x32_bf16 v[42:45], v[200:203], v[224:227], v[42:45]
	v_mfma_f32_16x16x32_bf16 v[130:133], v[190:193], v[232:235], v[130:133]
	v_mfma_f32_16x16x32_bf16 v[34:37], v[200:203], v[232:235], v[34:37]
	s_setprio 0
	s_setprio 1
	v_mfma_f32_16x16x32_bf16 v[138:141], v[194:197], v[212:215], v[138:141]
	v_mfma_f32_16x16x32_bf16 v[90:93], v[204:207], v[212:215], v[90:93]
	v_mfma_f32_16x16x32_bf16 v[106:109], v[194:197], v[220:223], v[106:109]
	v_mfma_f32_16x16x32_bf16 v[50:53], v[204:207], v[220:223], v[50:53]
	v_mfma_f32_16x16x32_bf16 v[74:77], v[194:197], v[228:231], v[74:77]
	v_mfma_f32_16x16x32_bf16 v[42:45], v[204:207], v[228:231], v[42:45]
	v_mfma_f32_16x16x32_bf16 v[130:133], v[194:197], v[236:239], v[130:133]
	v_mfma_f32_16x16x32_bf16 v[34:37], v[204:207], v[236:239], v[34:37]
	s_setprio 0
	s_barrier
	s_add_i32 s8, s55, s0
	v_lshl_add_u64 v[242:243], v[240:241], 0, v[150:151]
	s_mov_b32 m0, s8
	ds_read_b128 v[208:211], v182 offset:16384
	ds_read_b128 v[212:215], v182 offset:17408
	ds_read_b128 v[216:219], v182 offset:18432
	ds_read_b128 v[220:223], v182 offset:19456
	ds_read_b128 v[224:227], v182 offset:20480
	ds_read_b128 v[228:231], v182 offset:21504
	ds_read_b128 v[232:235], v182 offset:22528
	ds_read_b128 v[236:239], v182 offset:23552
	global_load_lds_dwordx4 v[242:243], off
	v_lshl_add_u64 v[244:245], v[240:241], 0, v[152:153]
	s_add_i32 m0, s8, 0x2000
	v_lshl_add_u64 v[246:247], v[240:241], 0, s[22:23]
	s_add_i32 s8, s56, s0
	global_load_lds_dwordx4 v[244:245], off
	v_lshl_add_u64 v[248:249], v[246:247], 0, v[150:151]
	s_mov_b32 m0, s8
	v_lshl_add_u64 v[246:247], v[246:247], 0, v[152:153]
	global_load_lds_dwordx4 v[248:249], off
	s_add_i32 m0, s8, 0x2000
	v_lshl_add_u64 v[248:249], v[198:199], 0, v[152:153]
	global_load_lds_dwordx4 v[246:247], off
	v_lshl_add_u64 v[246:247], v[198:199], 0, v[150:151]
	s_mov_b32 m0, s1
	s_nop 0
	global_load_lds_dwordx4 v[246:247], off
	s_mov_b32 m0, s2
	s_nop 0
	global_load_lds_dwordx4 v[248:249], off
	s_waitcnt vmcnt(8)
	s_waitcnt lgkmcnt(0)
	s_barrier
	s_setprio 1
	s_waitcnt lgkmcnt(0)
	v_mfma_f32_16x16x32_bf16 v[30:33], v[94:97], v[208:211], v[30:33]
	v_mfma_f32_16x16x32_bf16 v[126:129], v[174:177], v[208:211], v[126:129]
	v_mfma_f32_16x16x32_bf16 v[22:25], v[94:97], v[216:219], v[22:25]
	v_mfma_f32_16x16x32_bf16 v[70:73], v[174:177], v[216:219], v[70:73]
	v_mfma_f32_16x16x32_bf16 v[14:17], v[94:97], v[224:227], v[14:17]
	v_mfma_f32_16x16x32_bf16 v[66:69], v[174:177], v[224:227], v[66:69]
	v_mfma_f32_16x16x32_bf16 v[6:9], v[94:97], v[232:235], v[6:9]
	v_mfma_f32_16x16x32_bf16 v[30:33], v[98:101], v[212:215], v[30:33]
	s_setprio 0
	s_setprio 1
	v_mfma_f32_16x16x32_bf16 v[126:129], v[186:189], v[212:215], v[126:129]
	v_mfma_f32_16x16x32_bf16 v[22:25], v[98:101], v[220:223], v[22:25]
	v_mfma_f32_16x16x32_bf16 v[70:73], v[186:189], v[220:223], v[70:73]
	v_mfma_f32_16x16x32_bf16 v[14:17], v[98:101], v[228:231], v[14:17]
	v_mfma_f32_16x16x32_bf16 v[66:69], v[186:189], v[228:231], v[66:69]
	v_mfma_f32_16x16x32_bf16 v[6:9], v[98:101], v[236:239], v[6:9]
	v_mfma_f32_16x16x32_bf16 v[94:97], v[174:177], v[232:235], v[118:121]
	v_mfma_f32_16x16x32_bf16 v[94:97], v[186:189], v[236:239], v[94:97]
	s_setprio 0
	s_setprio 1
	v_mfma_f32_16x16x32_bf16 v[26:29], v[200:203], v[208:211], v[26:29]
	v_mfma_f32_16x16x32_bf16 v[58:61], v[190:193], v[216:219], v[58:61]
	v_mfma_f32_16x16x32_bf16 v[18:21], v[200:203], v[216:219], v[18:21]
	v_mfma_f32_16x16x32_bf16 v[54:57], v[190:193], v[224:227], v[54:57]
	v_mfma_f32_16x16x32_bf16 v[10:13], v[200:203], v[224:227], v[10:13]
	v_mfma_f32_16x16x32_bf16 v[114:117], v[190:193], v[232:235], v[114:117]
	v_mfma_f32_16x16x32_bf16 v[2:5], v[200:203], v[232:235], v[2:5]
	v_mfma_f32_16x16x32_bf16 v[98:101], v[190:193], v[208:211], v[122:125]
	s_setprio 0
	s_setprio 1
	v_mfma_f32_16x16x32_bf16 v[26:29], v[204:207], v[212:215], v[26:29]
	v_mfma_f32_16x16x32_bf16 v[58:61], v[194:197], v[220:223], v[58:61]
	v_mfma_f32_16x16x32_bf16 v[18:21], v[204:207], v[220:223], v[18:21]
	v_mfma_f32_16x16x32_bf16 v[54:57], v[194:197], v[228:231], v[54:57]
	v_mfma_f32_16x16x32_bf16 v[10:13], v[204:207], v[228:231], v[10:13]
	v_mfma_f32_16x16x32_bf16 v[114:117], v[194:197], v[236:239], v[114:117]
	v_mfma_f32_16x16x32_bf16 v[2:5], v[204:207], v[236:239], v[2:5]
	v_mfma_f32_16x16x32_bf16 v[98:101], v[194:197], v[212:215], v[98:101]
	s_setprio 0
	s_barrier
	s_add_i32 s8, 0, 0x18000
	v_add_u32_e32 v85, s8, v180
	s_add_i32 s9, 0, 0x1c000
	ds_read_b128 v[118:121], v85
	ds_read_b128 v[122:125], v85 offset:1024
	ds_read_b128 v[174:177], v85 offset:2048
	ds_read_b128 v[186:189], v85 offset:3072
	v_add_u32_e32 v85, s9, v180
	ds_read_b128 v[190:193], v85
	ds_read_b128 v[194:197], v85 offset:1024
	ds_read_b128 v[200:203], v85 offset:2048
	ds_read_b128 v[204:207], v85 offset:3072
	v_lshl_add_u64 v[198:199], v[198:199], 0, s[22:23]
	s_mov_b32 m0, s3
	v_lshl_add_u64 v[250:251], v[198:199], 0, v[150:151]
	ds_read_b128 v[208:211], v182 offset:32768
	ds_read_b128 v[212:215], v182 offset:33792
	ds_read_b128 v[216:219], v182 offset:34816
	ds_read_b128 v[220:223], v182 offset:35840
	ds_read_b128 v[224:227], v182 offset:36864
	ds_read_b128 v[228:231], v182 offset:37888
	ds_read_b128 v[232:235], v182 offset:38912
	ds_read_b128 v[236:239], v182 offset:39936
	global_load_lds_dwordx4 v[250:251], off
	v_lshl_add_u64 v[198:199], v[198:199], 0, v[152:153]
	s_mov_b32 m0, s21
	s_nop 0
	global_load_lds_dwordx4 v[198:199], off
	s_waitcnt vmcnt(8)
	s_waitcnt lgkmcnt(0)
	s_barrier
	s_setprio 1
	s_waitcnt lgkmcnt(0)
	v_mfma_f32_16x16x32_bf16 v[102:105], v[118:121], v[208:211], v[102:105]
	v_mfma_f32_16x16x32_bf16 v[142:145], v[174:177], v[208:211], v[142:145]
	v_mfma_f32_16x16x32_bf16 v[62:65], v[118:121], v[216:219], v[62:65]
	v_mfma_f32_16x16x32_bf16 v[110:113], v[174:177], v[216:219], v[110:113]
	v_mfma_f32_16x16x32_bf16 v[46:49], v[118:121], v[224:227], v[46:49]
	v_mfma_f32_16x16x32_bf16 v[78:81], v[174:177], v[224:227], v[78:81]
	v_mfma_f32_16x16x32_bf16 v[38:41], v[118:121], v[232:235], v[38:41]
	v_mfma_f32_16x16x32_bf16 v[134:137], v[174:177], v[232:235], v[134:137]
	s_setprio 0
	s_setprio 1
	v_mfma_f32_16x16x32_bf16 v[102:105], v[122:125], v[212:215], v[102:105]
	v_mfma_f32_16x16x32_bf16 v[142:145], v[186:189], v[212:215], v[142:145]
	v_mfma_f32_16x16x32_bf16 v[62:65], v[122:125], v[220:223], v[62:65]
	v_mfma_f32_16x16x32_bf16 v[110:113], v[186:189], v[220:223], v[110:113]
	v_mfma_f32_16x16x32_bf16 v[46:49], v[122:125], v[228:231], v[46:49]
	v_mfma_f32_16x16x32_bf16 v[78:81], v[186:189], v[228:231], v[78:81]
	v_mfma_f32_16x16x32_bf16 v[38:41], v[122:125], v[236:239], v[38:41]
	v_mfma_f32_16x16x32_bf16 v[134:137], v[186:189], v[236:239], v[134:137]
	s_setprio 0
	s_setprio 1
	v_mfma_f32_16x16x32_bf16 v[138:141], v[190:193], v[208:211], v[138:141]
	v_mfma_f32_16x16x32_bf16 v[90:93], v[200:203], v[208:211], v[90:93]
	v_mfma_f32_16x16x32_bf16 v[106:109], v[190:193], v[216:219], v[106:109]
	v_mfma_f32_16x16x32_bf16 v[50:53], v[200:203], v[216:219], v[50:53]
	v_mfma_f32_16x16x32_bf16 v[74:77], v[190:193], v[224:227], v[74:77]
	v_mfma_f32_16x16x32_bf16 v[42:45], v[200:203], v[224:227], v[42:45]
	v_mfma_f32_16x16x32_bf16 v[130:133], v[190:193], v[232:235], v[130:133]
	v_mfma_f32_16x16x32_bf16 v[34:37], v[200:203], v[232:235], v[34:37]
	s_setprio 0
	s_setprio 1
	v_mfma_f32_16x16x32_bf16 v[138:141], v[194:197], v[212:215], v[138:141]
	v_mfma_f32_16x16x32_bf16 v[90:93], v[204:207], v[212:215], v[90:93]
	v_mfma_f32_16x16x32_bf16 v[106:109], v[194:197], v[220:223], v[106:109]
	v_mfma_f32_16x16x32_bf16 v[50:53], v[204:207], v[220:223], v[50:53]
	v_mfma_f32_16x16x32_bf16 v[74:77], v[194:197], v[228:231], v[74:77]
	v_mfma_f32_16x16x32_bf16 v[42:45], v[204:207], v[228:231], v[42:45]
	v_mfma_f32_16x16x32_bf16 v[130:133], v[194:197], v[236:239], v[130:133]
	v_mfma_f32_16x16x32_bf16 v[34:37], v[204:207], v[236:239], v[34:37]
	s_setprio 0
	s_barrier
	s_add_i32 s8, s8, s0
	v_lshl_add_u64 v[198:199], v[242:243], 0, s[26:27]
	s_mov_b32 m0, s8
	ds_read_b128 v[208:211], v182 offset:49152
	ds_read_b128 v[212:215], v182 offset:50176
	ds_read_b128 v[216:219], v182 offset:51200
	ds_read_b128 v[220:223], v182 offset:52224
	ds_read_b128 v[224:227], v182 offset:53248
	ds_read_b128 v[228:231], v182 offset:54272
	ds_read_b128 v[232:235], v182 offset:55296
	ds_read_b128 v[236:239], v182 offset:56320
	global_load_lds_dwordx4 v[198:199], off
	v_lshl_add_u64 v[198:199], v[244:245], 0, s[26:27]
	s_add_i32 m0, s8, 0x2000
	s_add_i32 s8, s9, s0
	global_load_lds_dwordx4 v[198:199], off
	v_lshl_add_u64 v[198:199], v[240:241], 0, s[28:29]
	v_lshl_add_u64 v[240:241], v[198:199], 0, v[150:151]
	s_mov_b32 m0, s8
	v_lshl_add_u64 v[198:199], v[198:199], 0, v[152:153]
	global_load_lds_dwordx4 v[240:241], off
	s_add_i32 m0, s8, 0x2000
	s_nop 0
	global_load_lds_dwordx4 v[198:199], off
	v_lshl_add_u64 v[198:199], v[246:247], 0, s[26:27]
	s_mov_b32 m0, s35
	s_nop 0
	global_load_lds_dwordx4 v[198:199], off
	v_lshl_add_u64 v[198:199], v[248:249], 0, s[26:27]
	s_mov_b32 m0, s50
	s_nop 0
	global_load_lds_dwordx4 v[198:199], off
	s_waitcnt vmcnt(8)
	s_waitcnt lgkmcnt(0)
	s_barrier
	s_setprio 1
	s_waitcnt lgkmcnt(0)
	v_mfma_f32_16x16x32_bf16 v[30:33], v[118:121], v[208:211], v[30:33]
	v_mfma_f32_16x16x32_bf16 v[126:129], v[174:177], v[208:211], v[126:129]
	v_mfma_f32_16x16x32_bf16 v[22:25], v[118:121], v[216:219], v[22:25]
	v_mfma_f32_16x16x32_bf16 v[70:73], v[174:177], v[216:219], v[70:73]
	v_mfma_f32_16x16x32_bf16 v[14:17], v[118:121], v[224:227], v[14:17]
	v_mfma_f32_16x16x32_bf16 v[66:69], v[174:177], v[224:227], v[66:69]
	v_mfma_f32_16x16x32_bf16 v[6:9], v[118:121], v[232:235], v[6:9]
	v_mfma_f32_16x16x32_bf16 v[94:97], v[174:177], v[232:235], v[94:97]
	s_setprio 0
	s_setprio 1
	v_mfma_f32_16x16x32_bf16 v[30:33], v[122:125], v[212:215], v[30:33]
	v_mfma_f32_16x16x32_bf16 v[126:129], v[186:189], v[212:215], v[126:129]
	v_mfma_f32_16x16x32_bf16 v[22:25], v[122:125], v[220:223], v[22:25]
	v_mfma_f32_16x16x32_bf16 v[70:73], v[186:189], v[220:223], v[70:73]
	v_mfma_f32_16x16x32_bf16 v[14:17], v[122:125], v[228:231], v[14:17]
	v_mfma_f32_16x16x32_bf16 v[66:69], v[186:189], v[228:231], v[66:69]
	v_mfma_f32_16x16x32_bf16 v[6:9], v[122:125], v[236:239], v[6:9]
	v_mfma_f32_16x16x32_bf16 v[118:121], v[186:189], v[236:239], v[94:97]
	s_setprio 0
	s_setprio 1
	v_mfma_f32_16x16x32_bf16 v[94:97], v[190:193], v[208:211], v[98:101]
	v_mfma_f32_16x16x32_bf16 v[122:125], v[194:197], v[212:215], v[94:97]
	v_mfma_f32_16x16x32_bf16 v[26:29], v[200:203], v[208:211], v[26:29]
	v_mfma_f32_16x16x32_bf16 v[58:61], v[190:193], v[216:219], v[58:61]
	v_mfma_f32_16x16x32_bf16 v[18:21], v[200:203], v[216:219], v[18:21]
	v_mfma_f32_16x16x32_bf16 v[54:57], v[190:193], v[224:227], v[54:57]
	v_mfma_f32_16x16x32_bf16 v[10:13], v[200:203], v[224:227], v[10:13]
	v_mfma_f32_16x16x32_bf16 v[94:97], v[190:193], v[232:235], v[114:117]
	s_setprio 0
	s_setprio 1
	v_mfma_f32_16x16x32_bf16 v[2:5], v[200:203], v[232:235], v[2:5]
	v_mfma_f32_16x16x32_bf16 v[26:29], v[204:207], v[212:215], v[26:29]
	v_mfma_f32_16x16x32_bf16 v[58:61], v[194:197], v[220:223], v[58:61]
	v_mfma_f32_16x16x32_bf16 v[18:21], v[204:207], v[220:223], v[18:21]
	v_mfma_f32_16x16x32_bf16 v[54:57], v[194:197], v[228:231], v[54:57]
	v_mfma_f32_16x16x32_bf16 v[10:13], v[204:207], v[228:231], v[10:13]
	v_mfma_f32_16x16x32_bf16 v[114:117], v[194:197], v[236:239], v[94:97]
	v_mfma_f32_16x16x32_bf16 v[2:5], v[204:207], v[236:239], v[2:5]
	s_setprio 0
	s_barrier
	s_add_i32 s7, s7, 2
	v_lshl_add_u64 v[86:87], v[86:87], 0, s[40:41]
	s_cmp_gt_u32 s7, 13
	v_lshl_add_u64 v[88:89], v[88:89], 0, s[40:41]
	s_cbranch_scc0 .LBB0_1252

.LBB0_1382:
	s_ashr_i32 s35, s34, 31
	s_lshl_b64 s[42:43], s[34:35], 20
	s_ashr_i32 s37, s36, 31
	s_ashr_i32 s31, s30, 31
	v_lshl_add_u64 v[0:1], v[168:169], 0, s[42:43]
	s_lshl_b64 s[42:43], s[36:37], 7
	s_lshl_b64 s[44:45], s[30:31], 20
	v_lshl_add_u64 v[182:183], v[0:1], 0, s[42:43]
	v_lshl_add_u64 v[0:1], v[160:161], 0, s[44:45]
	v_lshl_add_u64 v[184:185], v[0:1], 0, s[42:43]
	v_mov_b32_e32 v64, 0
	v_cndmask_b32_e64 v129, v5, v183, s[38:39]
	v_cndmask_b32_e64 v128, v4, v182, s[38:39]
	v_cndmask_b32_e64 v131, v3, v185, s[38:39]
	v_cndmask_b32_e64 v130, v2, v184, s[38:39]
	s_add_i32 s31, s5, -2
	v_lshl_add_u64 v[132:133], v[4:5], 0, s[18:19]
	v_lshl_add_u64 v[134:135], v[2:3], 0, s[24:25]
	s_mov_b32 s35, 0
	v_add_u32_e32 v148, s57, v194
	v_add_u32_e32 v197, s58, v194
	ds_read_b128 v[136:139], v148
	ds_read_b128 v[140:143], v148 offset:1024
	ds_read_b128 v[144:147], v148 offset:2048
	ds_read_b128 v[148:151], v148 offset:3072
	ds_read_b128 v[152:155], v197
	ds_read_b128 v[156:159], v197 offset:1024
	ds_read_b128 v[186:189], v197 offset:2048
	ds_read_b128 v[198:201], v197 offset:3072
	s_cmp_eq_u32 s31, s35
	v_lshl_add_u64 v[190:191], v[132:133], 0, s[26:27]
	s_cselect_b64 vcc, -1, 0
	s_add_i32 s35, s35, 2
	v_cndmask_b32_e32 v191, v191, v129, vcc
	v_cndmask_b32_e32 v190, v190, v128, vcc
	v_cndmask_b32_e32 v235, v135, v131, vcc
	v_cndmask_b32_e32 v234, v134, v130, vcc
	v_lshl_add_u64 v[236:237], v[132:133], 0, v[178:179]
	s_add_i32 m0, s47, 0xc000
	ds_read_b128 v[202:205], v195
	ds_read_b128 v[206:209], v195 offset:1024
	ds_read_b128 v[210:213], v195 offset:2048
	ds_read_b128 v[214:217], v195 offset:3072
	ds_read_b128 v[218:221], v195 offset:4096
	ds_read_b128 v[222:225], v195 offset:5120
	ds_read_b128 v[226:229], v195 offset:6144
	ds_read_b128 v[230:233], v195 offset:7168
	global_load_lds_dwordx4 v[236:237], off
	v_lshl_add_u64 v[236:237], v[132:133], 0, v[180:181]
	s_add_i32 m0, s47, 0xe000
	s_nop 0
	global_load_lds_dwordx4 v[236:237], off
	s_waitcnt vmcnt(8)
	s_waitcnt lgkmcnt(0)
	s_barrier
	s_setprio 1
	s_waitcnt lgkmcnt(0)
	v_mfma_f32_16x16x32_bf16 v[60:63], v[136:139], v[202:205], 0
	v_mfma_f32_16x16x32_bf16 v[56:59], v[144:147], v[202:205], 0
	v_mfma_f32_16x16x32_bf16 v[52:55], v[136:139], v[210:213], 0
	v_mfma_f32_16x16x32_bf16 v[48:51], v[144:147], v[210:213], 0
	v_mfma_f32_16x16x32_bf16 v[44:47], v[136:139], v[218:221], 0
	v_mfma_f32_16x16x32_bf16 v[40:43], v[144:147], v[218:221], 0
	v_mfma_f32_16x16x32_bf16 v[36:39], v[136:139], v[226:229], 0
	v_mfma_f32_16x16x32_bf16 v[32:35], v[144:147], v[226:229], 0
	s_setprio 0
	s_setprio 1
	v_mfma_f32_16x16x32_bf16 v[60:63], v[140:143], v[206:209], v[60:63]
	v_mfma_f32_16x16x32_bf16 v[56:59], v[148:151], v[206:209], v[56:59]
	v_mfma_f32_16x16x32_bf16 v[52:55], v[140:143], v[214:217], v[52:55]
	v_mfma_f32_16x16x32_bf16 v[48:51], v[148:151], v[214:217], v[48:51]
	v_mfma_f32_16x16x32_bf16 v[44:47], v[140:143], v[222:225], v[44:47]
	v_mfma_f32_16x16x32_bf16 v[40:43], v[148:151], v[222:225], v[40:43]
	v_mfma_f32_16x16x32_bf16 v[36:39], v[140:143], v[230:233], v[36:39]
	v_mfma_f32_16x16x32_bf16 v[32:35], v[148:151], v[230:233], v[32:35]
	s_setprio 0
	s_setprio 1
	v_mfma_f32_16x16x32_bf16 v[28:31], v[152:155], v[202:205], 0
	v_mfma_f32_16x16x32_bf16 v[24:27], v[186:189], v[202:205], 0
	v_mfma_f32_16x16x32_bf16 v[20:23], v[152:155], v[210:213], 0
	v_mfma_f32_16x16x32_bf16 v[16:19], v[186:189], v[210:213], 0
	v_mfma_f32_16x16x32_bf16 v[12:15], v[152:155], v[218:221], 0
	v_mfma_f32_16x16x32_bf16 v[8:11], v[186:189], v[218:221], 0
	v_mfma_f32_16x16x32_bf16 v[4:7], v[152:155], v[226:229], 0
	v_mfma_f32_16x16x32_bf16 v[0:3], v[186:189], v[226:229], 0
	s_setprio 0
	s_setprio 1
	v_mfma_f32_16x16x32_bf16 v[28:31], v[156:159], v[206:209], v[28:31]
	v_mfma_f32_16x16x32_bf16 v[24:27], v[198:201], v[206:209], v[24:27]
	v_mfma_f32_16x16x32_bf16 v[20:23], v[156:159], v[214:217], v[20:23]
	v_mfma_f32_16x16x32_bf16 v[16:19], v[198:201], v[214:217], v[16:19]
	v_mfma_f32_16x16x32_bf16 v[12:15], v[156:159], v[222:225], v[12:15]
	v_mfma_f32_16x16x32_bf16 v[8:11], v[198:201], v[222:225], v[8:11]
	v_mfma_f32_16x16x32_bf16 v[4:7], v[156:159], v[230:233], v[4:7]
	v_mfma_f32_16x16x32_bf16 v[0:3], v[198:201], v[230:233], v[0:3]
	s_setprio 0
	s_barrier
	s_add_i32 s37, s57, s3
	v_lshl_add_u64 v[236:237], v[234:235], 0, v[162:163]
	s_mov_b32 m0, s37
	ds_read_b128 v[202:205], v195 offset:16384
	ds_read_b128 v[206:209], v195 offset:17408
	ds_read_b128 v[210:213], v195 offset:18432
	ds_read_b128 v[214:217], v195 offset:19456
	ds_read_b128 v[218:221], v195 offset:20480
	ds_read_b128 v[222:225], v195 offset:21504
	ds_read_b128 v[226:229], v195 offset:22528
	ds_read_b128 v[230:233], v195 offset:23552
	global_load_lds_dwordx4 v[236:237], off
	v_lshl_add_u64 v[238:239], v[234:235], 0, v[164:165]
	s_add_i32 m0, s37, 0x2000
	v_lshl_add_u64 v[240:241], v[234:235], 0, s[12:13]
	s_add_i32 s37, s58, s3
	global_load_lds_dwordx4 v[238:239], off
	v_lshl_add_u64 v[242:243], v[240:241], 0, v[162:163]
	s_mov_b32 m0, s37
	v_lshl_add_u64 v[240:241], v[240:241], 0, v[164:165]
	global_load_lds_dwordx4 v[242:243], off
	s_add_i32 m0, s37, 0x2000
	v_lshl_add_u64 v[242:243], v[190:191], 0, v[164:165]
	global_load_lds_dwordx4 v[240:241], off
	v_lshl_add_u64 v[240:241], v[190:191], 0, v[162:163]
	s_mov_b32 m0, s47
	s_nop 0
	global_load_lds_dwordx4 v[240:241], off
	s_mov_b32 m0, s48
	s_nop 0
	global_load_lds_dwordx4 v[242:243], off
	s_waitcnt vmcnt(8)
	s_waitcnt lgkmcnt(0)
	s_barrier
	s_setprio 1
	s_waitcnt lgkmcnt(0)
	v_mfma_f32_16x16x32_bf16 v[124:127], v[136:139], v[202:205], 0
	v_mfma_f32_16x16x32_bf16 v[120:123], v[144:147], v[202:205], 0
	v_mfma_f32_16x16x32_bf16 v[116:119], v[136:139], v[210:213], 0
	v_mfma_f32_16x16x32_bf16 v[112:115], v[144:147], v[210:213], 0
	v_mfma_f32_16x16x32_bf16 v[108:111], v[136:139], v[218:221], 0
	v_mfma_f32_16x16x32_bf16 v[104:107], v[144:147], v[218:221], 0
	v_mfma_f32_16x16x32_bf16 v[100:103], v[136:139], v[226:229], 0
	v_mfma_f32_16x16x32_bf16 v[96:99], v[144:147], v[226:229], 0
	s_setprio 0
	s_setprio 1
	v_mfma_f32_16x16x32_bf16 v[124:127], v[140:143], v[206:209], v[124:127]
	v_mfma_f32_16x16x32_bf16 v[120:123], v[148:151], v[206:209], v[120:123]
	v_mfma_f32_16x16x32_bf16 v[116:119], v[140:143], v[214:217], v[116:119]
	v_mfma_f32_16x16x32_bf16 v[112:115], v[148:151], v[214:217], v[112:115]
	v_mfma_f32_16x16x32_bf16 v[108:111], v[140:143], v[222:225], v[108:111]
	v_mfma_f32_16x16x32_bf16 v[104:107], v[148:151], v[222:225], v[104:107]
	v_mfma_f32_16x16x32_bf16 v[100:103], v[140:143], v[230:233], v[100:103]
	v_mfma_f32_16x16x32_bf16 v[96:99], v[148:151], v[230:233], v[96:99]
	s_setprio 0
	s_setprio 1
	v_mfma_f32_16x16x32_bf16 v[92:95], v[152:155], v[202:205], 0
	v_mfma_f32_16x16x32_bf16 v[88:91], v[186:189], v[202:205], 0
	v_mfma_f32_16x16x32_bf16 v[84:87], v[152:155], v[210:213], 0
	v_mfma_f32_16x16x32_bf16 v[80:83], v[186:189], v[210:213], 0
	v_mfma_f32_16x16x32_bf16 v[76:79], v[152:155], v[218:221], 0
	v_mfma_f32_16x16x32_bf16 v[72:75], v[186:189], v[218:221], 0
	v_mfma_f32_16x16x32_bf16 v[68:71], v[152:155], v[226:229], 0
	v_mfma_f32_16x16x32_bf16 v[64:67], v[186:189], v[226:229], 0
	s_setprio 0
	s_setprio 1
	v_mfma_f32_16x16x32_bf16 v[92:95], v[156:159], v[206:209], v[92:95]
	v_mfma_f32_16x16x32_bf16 v[88:91], v[198:201], v[206:209], v[88:91]
	v_mfma_f32_16x16x32_bf16 v[84:87], v[156:159], v[214:217], v[84:87]
	v_mfma_f32_16x16x32_bf16 v[80:83], v[198:201], v[214:217], v[80:83]
	v_mfma_f32_16x16x32_bf16 v[76:79], v[156:159], v[222:225], v[76:79]
	v_mfma_f32_16x16x32_bf16 v[72:75], v[198:201], v[222:225], v[72:75]
	v_mfma_f32_16x16x32_bf16 v[68:71], v[156:159], v[230:233], v[68:71]
	v_mfma_f32_16x16x32_bf16 v[64:67], v[198:201], v[230:233], v[64:67]
	s_setprio 0
	s_barrier
	s_add_i32 s37, 0, 0x18000
	s_add_i32 s41, 0, 0x1c000
	v_add_u32_e32 v148, s37, v194
	v_add_u32_e32 v197, s41, v194
	ds_read_b128 v[136:139], v148
	ds_read_b128 v[140:143], v148 offset:1024
	ds_read_b128 v[144:147], v148 offset:2048
	ds_read_b128 v[148:151], v148 offset:3072
	ds_read_b128 v[152:155], v197
	ds_read_b128 v[156:159], v197 offset:1024
	ds_read_b128 v[186:189], v197 offset:2048
	ds_read_b128 v[198:201], v197 offset:3072
	v_lshl_add_u64 v[190:191], v[190:191], 0, s[12:13]
	s_mov_b32 m0, s49
	v_lshl_add_u64 v[244:245], v[190:191], 0, v[162:163]
	ds_read_b128 v[202:205], v195 offset:32768
	ds_read_b128 v[206:209], v195 offset:33792
	ds_read_b128 v[210:213], v195 offset:34816
	ds_read_b128 v[214:217], v195 offset:35840
	ds_read_b128 v[218:221], v195 offset:36864
	ds_read_b128 v[222:225], v195 offset:37888
	ds_read_b128 v[226:229], v195 offset:38912
	ds_read_b128 v[230:233], v195 offset:39936
	global_load_lds_dwordx4 v[244:245], off
	v_lshl_add_u64 v[190:191], v[190:191], 0, v[164:165]
	s_mov_b32 m0, s50
	s_nop 0
	global_load_lds_dwordx4 v[190:191], off
	s_waitcnt vmcnt(8)
	s_waitcnt lgkmcnt(0)
	s_barrier
	s_setprio 1
	s_waitcnt lgkmcnt(0)
	v_mfma_f32_16x16x32_bf16 v[60:63], v[136:139], v[202:205], v[60:63]
	v_mfma_f32_16x16x32_bf16 v[56:59], v[144:147], v[202:205], v[56:59]
	v_mfma_f32_16x16x32_bf16 v[52:55], v[136:139], v[210:213], v[52:55]
	v_mfma_f32_16x16x32_bf16 v[48:51], v[144:147], v[210:213], v[48:51]
	v_mfma_f32_16x16x32_bf16 v[44:47], v[136:139], v[218:221], v[44:47]
	v_mfma_f32_16x16x32_bf16 v[40:43], v[144:147], v[218:221], v[40:43]
	v_mfma_f32_16x16x32_bf16 v[36:39], v[136:139], v[226:229], v[36:39]
	v_mfma_f32_16x16x32_bf16 v[32:35], v[144:147], v[226:229], v[32:35]
	s_setprio 0
	s_setprio 1
	v_mfma_f32_16x16x32_bf16 v[60:63], v[140:143], v[206:209], v[60:63]
	v_mfma_f32_16x16x32_bf16 v[56:59], v[148:151], v[206:209], v[56:59]
	v_mfma_f32_16x16x32_bf16 v[52:55], v[140:143], v[214:217], v[52:55]
	v_mfma_f32_16x16x32_bf16 v[48:51], v[148:151], v[214:217], v[48:51]
	v_mfma_f32_16x16x32_bf16 v[44:47], v[140:143], v[222:225], v[44:47]
	v_mfma_f32_16x16x32_bf16 v[40:43], v[148:151], v[222:225], v[40:43]
	v_mfma_f32_16x16x32_bf16 v[36:39], v[140:143], v[230:233], v[36:39]
	v_mfma_f32_16x16x32_bf16 v[32:35], v[148:151], v[230:233], v[32:35]
	s_setprio 0
	s_setprio 1
	v_mfma_f32_16x16x32_bf16 v[28:31], v[152:155], v[202:205], v[28:31]
	v_mfma_f32_16x16x32_bf16 v[24:27], v[186:189], v[202:205], v[24:27]
	v_mfma_f32_16x16x32_bf16 v[20:23], v[152:155], v[210:213], v[20:23]
	v_mfma_f32_16x16x32_bf16 v[16:19], v[186:189], v[210:213], v[16:19]
	v_mfma_f32_16x16x32_bf16 v[12:15], v[152:155], v[218:221], v[12:15]
	v_mfma_f32_16x16x32_bf16 v[8:11], v[186:189], v[218:221], v[8:11]
	v_mfma_f32_16x16x32_bf16 v[4:7], v[152:155], v[226:229], v[4:7]
	v_mfma_f32_16x16x32_bf16 v[0:3], v[186:189], v[226:229], v[0:3]
	s_setprio 0
	s_setprio 1
	v_mfma_f32_16x16x32_bf16 v[28:31], v[156:159], v[206:209], v[28:31]
	v_mfma_f32_16x16x32_bf16 v[24:27], v[198:201], v[206:209], v[24:27]
	v_mfma_f32_16x16x32_bf16 v[20:23], v[156:159], v[214:217], v[20:23]
	v_mfma_f32_16x16x32_bf16 v[16:19], v[198:201], v[214:217], v[16:19]
	v_mfma_f32_16x16x32_bf16 v[12:15], v[156:159], v[222:225], v[12:15]
	v_mfma_f32_16x16x32_bf16 v[8:11], v[198:201], v[222:225], v[8:11]
	v_mfma_f32_16x16x32_bf16 v[4:7], v[156:159], v[230:233], v[4:7]
	v_mfma_f32_16x16x32_bf16 v[0:3], v[198:201], v[230:233], v[0:3]
	s_setprio 0
	s_barrier
	s_add_i32 s37, s37, s3
	v_lshl_add_u64 v[190:191], v[236:237], 0, s[16:17]
	s_mov_b32 m0, s37
	ds_read_b128 v[202:205], v195 offset:49152
	ds_read_b128 v[206:209], v195 offset:50176
	ds_read_b128 v[210:213], v195 offset:51200
	ds_read_b128 v[214:217], v195 offset:52224
	ds_read_b128 v[218:221], v195 offset:53248
	ds_read_b128 v[222:225], v195 offset:54272
	ds_read_b128 v[226:229], v195 offset:55296
	ds_read_b128 v[230:233], v195 offset:56320
	global_load_lds_dwordx4 v[190:191], off
	v_lshl_add_u64 v[190:191], v[238:239], 0, s[16:17]
	s_add_i32 m0, s37, 0x2000
	s_add_i32 s37, s41, s3
	global_load_lds_dwordx4 v[190:191], off
	v_lshl_add_u64 v[190:191], v[234:235], 0, s[18:19]
	v_lshl_add_u64 v[234:235], v[190:191], 0, v[162:163]
	s_mov_b32 m0, s37
	v_lshl_add_u64 v[190:191], v[190:191], 0, v[164:165]
	global_load_lds_dwordx4 v[234:235], off
	s_add_i32 m0, s37, 0x2000
	s_nop 0
	global_load_lds_dwordx4 v[190:191], off
	v_lshl_add_u64 v[190:191], v[240:241], 0, s[16:17]
	s_mov_b32 m0, s52
	s_nop 0
	global_load_lds_dwordx4 v[190:191], off
	v_lshl_add_u64 v[190:191], v[242:243], 0, s[16:17]
	s_mov_b32 m0, s53
	s_nop 0
	global_load_lds_dwordx4 v[190:191], off
	s_waitcnt vmcnt(8)
	s_waitcnt lgkmcnt(0)
	s_barrier
	s_setprio 1
	s_waitcnt lgkmcnt(0)
	v_mfma_f32_16x16x32_bf16 v[124:127], v[136:139], v[202:205], v[124:127]
	v_mfma_f32_16x16x32_bf16 v[120:123], v[144:147], v[202:205], v[120:123]
	v_mfma_f32_16x16x32_bf16 v[116:119], v[136:139], v[210:213], v[116:119]
	v_mfma_f32_16x16x32_bf16 v[112:115], v[144:147], v[210:213], v[112:115]
	v_mfma_f32_16x16x32_bf16 v[108:111], v[136:139], v[218:221], v[108:111]
	v_mfma_f32_16x16x32_bf16 v[104:107], v[144:147], v[218:221], v[104:107]
	v_mfma_f32_16x16x32_bf16 v[100:103], v[136:139], v[226:229], v[100:103]
	v_mfma_f32_16x16x32_bf16 v[96:99], v[144:147], v[226:229], v[96:99]
	s_setprio 0
	s_setprio 1
	v_mfma_f32_16x16x32_bf16 v[124:127], v[140:143], v[206:209], v[124:127]
	v_mfma_f32_16x16x32_bf16 v[120:123], v[148:151], v[206:209], v[120:123]
	v_mfma_f32_16x16x32_bf16 v[116:119], v[140:143], v[214:217], v[116:119]
	v_mfma_f32_16x16x32_bf16 v[112:115], v[148:151], v[214:217], v[112:115]
	v_mfma_f32_16x16x32_bf16 v[108:111], v[140:143], v[222:225], v[108:111]
	v_mfma_f32_16x16x32_bf16 v[104:107], v[148:151], v[222:225], v[104:107]
	v_mfma_f32_16x16x32_bf16 v[100:103], v[140:143], v[230:233], v[100:103]
	v_mfma_f32_16x16x32_bf16 v[96:99], v[148:151], v[230:233], v[96:99]
	s_setprio 0
	s_setprio 1
	v_mfma_f32_16x16x32_bf16 v[92:95], v[152:155], v[202:205], v[92:95]
	v_mfma_f32_16x16x32_bf16 v[88:91], v[186:189], v[202:205], v[88:91]
	v_mfma_f32_16x16x32_bf16 v[84:87], v[152:155], v[210:213], v[84:87]
	v_mfma_f32_16x16x32_bf16 v[80:83], v[186:189], v[210:213], v[80:83]
	v_mfma_f32_16x16x32_bf16 v[76:79], v[152:155], v[218:221], v[76:79]
	v_mfma_f32_16x16x32_bf16 v[72:75], v[186:189], v[218:221], v[72:75]
	v_mfma_f32_16x16x32_bf16 v[68:71], v[152:155], v[226:229], v[68:71]
	v_mfma_f32_16x16x32_bf16 v[64:67], v[186:189], v[226:229], v[64:67]
	s_setprio 0
	s_setprio 1
	v_mfma_f32_16x16x32_bf16 v[92:95], v[156:159], v[206:209], v[92:95]
	v_mfma_f32_16x16x32_bf16 v[88:91], v[198:201], v[206:209], v[88:91]
	v_mfma_f32_16x16x32_bf16 v[84:87], v[156:159], v[214:217], v[84:87]
	v_mfma_f32_16x16x32_bf16 v[80:83], v[198:201], v[214:217], v[80:83]
	v_mfma_f32_16x16x32_bf16 v[76:79], v[156:159], v[222:225], v[76:79]
	v_mfma_f32_16x16x32_bf16 v[72:75], v[198:201], v[222:225], v[72:75]
	v_mfma_f32_16x16x32_bf16 v[68:71], v[156:159], v[230:233], v[68:71]
	v_mfma_f32_16x16x32_bf16 v[64:67], v[198:201], v[230:233], v[64:67]
	s_setprio 0
	s_barrier
	v_lshl_add_u64 v[132:133], v[132:133], 0, s[24:25]
	s_cmp_ge_i32 s35, s5
	v_lshl_add_u64 v[134:135], v[134:135], 0, s[24:25]
	s_cbranch_scc0 .LBB0_1383
	s_branch .Lpeel_exit_5
.LBB0_1383:
	v_add_u32_e32 v148, s57, v194
	v_add_u32_e32 v197, s58, v194
	ds_read_b128 v[136:139], v148
	ds_read_b128 v[140:143], v148 offset:1024
	ds_read_b128 v[144:147], v148 offset:2048
	ds_read_b128 v[148:151], v148 offset:3072
	ds_read_b128 v[152:155], v197
	ds_read_b128 v[156:159], v197 offset:1024
	ds_read_b128 v[186:189], v197 offset:2048
	ds_read_b128 v[198:201], v197 offset:3072
	s_cmp_eq_u32 s31, s35
	v_lshl_add_u64 v[190:191], v[132:133], 0, s[26:27]
	s_cselect_b64 vcc, -1, 0
	s_add_i32 s35, s35, 2
	v_cndmask_b32_e32 v191, v191, v129, vcc
	v_cndmask_b32_e32 v190, v190, v128, vcc
	v_cndmask_b32_e32 v235, v135, v131, vcc
	v_cndmask_b32_e32 v234, v134, v130, vcc
	v_lshl_add_u64 v[236:237], v[132:133], 0, v[178:179]
	s_add_i32 m0, s47, 0xc000
	ds_read_b128 v[202:205], v195
	ds_read_b128 v[206:209], v195 offset:1024
	ds_read_b128 v[210:213], v195 offset:2048
	ds_read_b128 v[214:217], v195 offset:3072
	ds_read_b128 v[218:221], v195 offset:4096
	ds_read_b128 v[222:225], v195 offset:5120
	ds_read_b128 v[226:229], v195 offset:6144
	ds_read_b128 v[230:233], v195 offset:7168
	global_load_lds_dwordx4 v[236:237], off
	v_lshl_add_u64 v[236:237], v[132:133], 0, v[180:181]
	s_add_i32 m0, s47, 0xe000
	s_nop 0
	global_load_lds_dwordx4 v[236:237], off
	s_waitcnt vmcnt(8)
	s_waitcnt lgkmcnt(0)
	s_barrier
	s_setprio 1
	s_waitcnt lgkmcnt(0)
	v_mfma_f32_16x16x32_bf16 v[60:63], v[136:139], v[202:205], v[60:63]
	v_mfma_f32_16x16x32_bf16 v[56:59], v[144:147], v[202:205], v[56:59]
	v_mfma_f32_16x16x32_bf16 v[52:55], v[136:139], v[210:213], v[52:55]
	v_mfma_f32_16x16x32_bf16 v[48:51], v[144:147], v[210:213], v[48:51]
	v_mfma_f32_16x16x32_bf16 v[44:47], v[136:139], v[218:221], v[44:47]
	v_mfma_f32_16x16x32_bf16 v[40:43], v[144:147], v[218:221], v[40:43]
	v_mfma_f32_16x16x32_bf16 v[36:39], v[136:139], v[226:229], v[36:39]
	v_mfma_f32_16x16x32_bf16 v[32:35], v[144:147], v[226:229], v[32:35]
	s_setprio 0
	s_setprio 1
	v_mfma_f32_16x16x32_bf16 v[60:63], v[140:143], v[206:209], v[60:63]
	v_mfma_f32_16x16x32_bf16 v[56:59], v[148:151], v[206:209], v[56:59]
	v_mfma_f32_16x16x32_bf16 v[52:55], v[140:143], v[214:217], v[52:55]
	v_mfma_f32_16x16x32_bf16 v[48:51], v[148:151], v[214:217], v[48:51]
	v_mfma_f32_16x16x32_bf16 v[44:47], v[140:143], v[222:225], v[44:47]
	v_mfma_f32_16x16x32_bf16 v[40:43], v[148:151], v[222:225], v[40:43]
	v_mfma_f32_16x16x32_bf16 v[36:39], v[140:143], v[230:233], v[36:39]
	v_mfma_f32_16x16x32_bf16 v[32:35], v[148:151], v[230:233], v[32:35]
	s_setprio 0
	s_setprio 1
	v_mfma_f32_16x16x32_bf16 v[28:31], v[152:155], v[202:205], v[28:31]
	v_mfma_f32_16x16x32_bf16 v[24:27], v[186:189], v[202:205], v[24:27]
	v_mfma_f32_16x16x32_bf16 v[20:23], v[152:155], v[210:213], v[20:23]
	v_mfma_f32_16x16x32_bf16 v[16:19], v[186:189], v[210:213], v[16:19]
	v_mfma_f32_16x16x32_bf16 v[12:15], v[152:155], v[218:221], v[12:15]
	v_mfma_f32_16x16x32_bf16 v[8:11], v[186:189], v[218:221], v[8:11]
	v_mfma_f32_16x16x32_bf16 v[4:7], v[152:155], v[226:229], v[4:7]
	v_mfma_f32_16x16x32_bf16 v[0:3], v[186:189], v[226:229], v[0:3]
	s_setprio 0
	s_setprio 1
	v_mfma_f32_16x16x32_bf16 v[28:31], v[156:159], v[206:209], v[28:31]
	v_mfma_f32_16x16x32_bf16 v[24:27], v[198:201], v[206:209], v[24:27]
	v_mfma_f32_16x16x32_bf16 v[20:23], v[156:159], v[214:217], v[20:23]
	v_mfma_f32_16x16x32_bf16 v[16:19], v[198:201], v[214:217], v[16:19]
	v_mfma_f32_16x16x32_bf16 v[12:15], v[156:159], v[222:225], v[12:15]
	v_mfma_f32_16x16x32_bf16 v[8:11], v[198:201], v[222:225], v[8:11]
	v_mfma_f32_16x16x32_bf16 v[4:7], v[156:159], v[230:233], v[4:7]
	v_mfma_f32_16x16x32_bf16 v[0:3], v[198:201], v[230:233], v[0:3]
	s_setprio 0
	s_barrier
	s_add_i32 s37, s57, s3
	v_lshl_add_u64 v[236:237], v[234:235], 0, v[162:163]
	s_mov_b32 m0, s37
	ds_read_b128 v[202:205], v195 offset:16384
	ds_read_b128 v[206:209], v195 offset:17408
	ds_read_b128 v[210:213], v195 offset:18432
	ds_read_b128 v[214:217], v195 offset:19456
	ds_read_b128 v[218:221], v195 offset:20480
	ds_read_b128 v[222:225], v195 offset:21504
	ds_read_b128 v[226:229], v195 offset:22528
	ds_read_b128 v[230:233], v195 offset:23552
	global_load_lds_dwordx4 v[236:237], off
	v_lshl_add_u64 v[238:239], v[234:235], 0, v[164:165]
	s_add_i32 m0, s37, 0x2000
	v_lshl_add_u64 v[240:241], v[234:235], 0, s[12:13]
	s_add_i32 s37, s58, s3
	global_load_lds_dwordx4 v[238:239], off
	v_lshl_add_u64 v[242:243], v[240:241], 0, v[162:163]
	s_mov_b32 m0, s37
	v_lshl_add_u64 v[240:241], v[240:241], 0, v[164:165]
	global_load_lds_dwordx4 v[242:243], off
	s_add_i32 m0, s37, 0x2000
	v_lshl_add_u64 v[242:243], v[190:191], 0, v[164:165]
	global_load_lds_dwordx4 v[240:241], off
	v_lshl_add_u64 v[240:241], v[190:191], 0, v[162:163]
	s_mov_b32 m0, s47
	s_nop 0
	global_load_lds_dwordx4 v[240:241], off
	s_mov_b32 m0, s48
	s_nop 0
	global_load_lds_dwordx4 v[242:243], off
	s_waitcnt vmcnt(8)
	s_waitcnt lgkmcnt(0)
	s_barrier
	s_setprio 1
	s_waitcnt lgkmcnt(0)
	v_mfma_f32_16x16x32_bf16 v[124:127], v[136:139], v[202:205], v[124:127]
	v_mfma_f32_16x16x32_bf16 v[120:123], v[144:147], v[202:205], v[120:123]
	v_mfma_f32_16x16x32_bf16 v[116:119], v[136:139], v[210:213], v[116:119]
	v_mfma_f32_16x16x32_bf16 v[112:115], v[144:147], v[210:213], v[112:115]
	v_mfma_f32_16x16x32_bf16 v[108:111], v[136:139], v[218:221], v[108:111]
	v_mfma_f32_16x16x32_bf16 v[104:107], v[144:147], v[218:221], v[104:107]
	v_mfma_f32_16x16x32_bf16 v[100:103], v[136:139], v[226:229], v[100:103]
	v_mfma_f32_16x16x32_bf16 v[96:99], v[144:147], v[226:229], v[96:99]
	s_setprio 0
	s_setprio 1
	v_mfma_f32_16x16x32_bf16 v[124:127], v[140:143], v[206:209], v[124:127]
	v_mfma_f32_16x16x32_bf16 v[120:123], v[148:151], v[206:209], v[120:123]
	v_mfma_f32_16x16x32_bf16 v[116:119], v[140:143], v[214:217], v[116:119]
	v_mfma_f32_16x16x32_bf16 v[112:115], v[148:151], v[214:217], v[112:115]
	v_mfma_f32_16x16x32_bf16 v[108:111], v[140:143], v[222:225], v[108:111]
	v_mfma_f32_16x16x32_bf16 v[104:107], v[148:151], v[222:225], v[104:107]
	v_mfma_f32_16x16x32_bf16 v[100:103], v[140:143], v[230:233], v[100:103]
	v_mfma_f32_16x16x32_bf16 v[96:99], v[148:151], v[230:233], v[96:99]
	s_setprio 0
	s_setprio 1
	v_mfma_f32_16x16x32_bf16 v[92:95], v[152:155], v[202:205], v[92:95]
	v_mfma_f32_16x16x32_bf16 v[88:91], v[186:189], v[202:205], v[88:91]
	v_mfma_f32_16x16x32_bf16 v[84:87], v[152:155], v[210:213], v[84:87]
	v_mfma_f32_16x16x32_bf16 v[80:83], v[186:189], v[210:213], v[80:83]
	v_mfma_f32_16x16x32_bf16 v[76:79], v[152:155], v[218:221], v[76:79]
	v_mfma_f32_16x16x32_bf16 v[72:75], v[186:189], v[218:221], v[72:75]
	v_mfma_f32_16x16x32_bf16 v[68:71], v[152:155], v[226:229], v[68:71]
	v_mfma_f32_16x16x32_bf16 v[64:67], v[186:189], v[226:229], v[64:67]
	s_setprio 0
	s_setprio 1
	v_mfma_f32_16x16x32_bf16 v[92:95], v[156:159], v[206:209], v[92:95]
	v_mfma_f32_16x16x32_bf16 v[88:91], v[198:201], v[206:209], v[88:91]
	v_mfma_f32_16x16x32_bf16 v[84:87], v[156:159], v[214:217], v[84:87]
	v_mfma_f32_16x16x32_bf16 v[80:83], v[198:201], v[214:217], v[80:83]
	v_mfma_f32_16x16x32_bf16 v[76:79], v[156:159], v[222:225], v[76:79]
	v_mfma_f32_16x16x32_bf16 v[72:75], v[198:201], v[222:225], v[72:75]
	v_mfma_f32_16x16x32_bf16 v[68:71], v[156:159], v[230:233], v[68:71]
	v_mfma_f32_16x16x32_bf16 v[64:67], v[198:201], v[230:233], v[64:67]
	s_setprio 0
	s_barrier
	s_add_i32 s37, 0, 0x18000
	s_add_i32 s41, 0, 0x1c000
	v_add_u32_e32 v148, s37, v194
	v_add_u32_e32 v197, s41, v194
	ds_read_b128 v[136:139], v148
	ds_read_b128 v[140:143], v148 offset:1024
	ds_read_b128 v[144:147], v148 offset:2048
	ds_read_b128 v[148:151], v148 offset:3072
	ds_read_b128 v[152:155], v197
	ds_read_b128 v[156:159], v197 offset:1024
	ds_read_b128 v[186:189], v197 offset:2048
	ds_read_b128 v[198:201], v197 offset:3072
	v_lshl_add_u64 v[190:191], v[190:191], 0, s[12:13]
	s_mov_b32 m0, s49
	v_lshl_add_u64 v[244:245], v[190:191], 0, v[162:163]
	ds_read_b128 v[202:205], v195 offset:32768
	ds_read_b128 v[206:209], v195 offset:33792
	ds_read_b128 v[210:213], v195 offset:34816
	ds_read_b128 v[214:217], v195 offset:35840
	ds_read_b128 v[218:221], v195 offset:36864
	ds_read_b128 v[222:225], v195 offset:37888
	ds_read_b128 v[226:229], v195 offset:38912
	ds_read_b128 v[230:233], v195 offset:39936
	global_load_lds_dwordx4 v[244:245], off
	v_lshl_add_u64 v[190:191], v[190:191], 0, v[164:165]
	s_mov_b32 m0, s50
	s_nop 0
	global_load_lds_dwordx4 v[190:191], off
	s_waitcnt vmcnt(8)
	s_waitcnt lgkmcnt(0)
	s_barrier
	s_setprio 1
	s_waitcnt lgkmcnt(0)
	v_mfma_f32_16x16x32_bf16 v[60:63], v[136:139], v[202:205], v[60:63]
	v_mfma_f32_16x16x32_bf16 v[56:59], v[144:147], v[202:205], v[56:59]
	v_mfma_f32_16x16x32_bf16 v[52:55], v[136:139], v[210:213], v[52:55]
	v_mfma_f32_16x16x32_bf16 v[48:51], v[144:147], v[210:213], v[48:51]
	v_mfma_f32_16x16x32_bf16 v[44:47], v[136:139], v[218:221], v[44:47]
	v_mfma_f32_16x16x32_bf16 v[40:43], v[144:147], v[218:221], v[40:43]
	v_mfma_f32_16x16x32_bf16 v[36:39], v[136:139], v[226:229], v[36:39]
	v_mfma_f32_16x16x32_bf16 v[32:35], v[144:147], v[226:229], v[32:35]
	s_setprio 0
	s_setprio 1
	v_mfma_f32_16x16x32_bf16 v[60:63], v[140:143], v[206:209], v[60:63]
	v_mfma_f32_16x16x32_bf16 v[56:59], v[148:151], v[206:209], v[56:59]
	v_mfma_f32_16x16x32_bf16 v[52:55], v[140:143], v[214:217], v[52:55]
	v_mfma_f32_16x16x32_bf16 v[48:51], v[148:151], v[214:217], v[48:51]
	v_mfma_f32_16x16x32_bf16 v[44:47], v[140:143], v[222:225], v[44:47]
	v_mfma_f32_16x16x32_bf16 v[40:43], v[148:151], v[222:225], v[40:43]
	v_mfma_f32_16x16x32_bf16 v[36:39], v[140:143], v[230:233], v[36:39]
	v_mfma_f32_16x16x32_bf16 v[32:35], v[148:151], v[230:233], v[32:35]
	s_setprio 0
	s_setprio 1
	v_mfma_f32_16x16x32_bf16 v[28:31], v[152:155], v[202:205], v[28:31]
	v_mfma_f32_16x16x32_bf16 v[24:27], v[186:189], v[202:205], v[24:27]
	v_mfma_f32_16x16x32_bf16 v[20:23], v[152:155], v[210:213], v[20:23]
	v_mfma_f32_16x16x32_bf16 v[16:19], v[186:189], v[210:213], v[16:19]
	v_mfma_f32_16x16x32_bf16 v[12:15], v[152:155], v[218:221], v[12:15]
	v_mfma_f32_16x16x32_bf16 v[8:11], v[186:189], v[218:221], v[8:11]
	v_mfma_f32_16x16x32_bf16 v[4:7], v[152:155], v[226:229], v[4:7]
	v_mfma_f32_16x16x32_bf16 v[0:3], v[186:189], v[226:229], v[0:3]
	s_setprio 0
	s_setprio 1
	v_mfma_f32_16x16x32_bf16 v[28:31], v[156:159], v[206:209], v[28:31]
	v_mfma_f32_16x16x32_bf16 v[24:27], v[198:201], v[206:209], v[24:27]
	v_mfma_f32_16x16x32_bf16 v[20:23], v[156:159], v[214:217], v[20:23]
	v_mfma_f32_16x16x32_bf16 v[16:19], v[198:201], v[214:217], v[16:19]
	v_mfma_f32_16x16x32_bf16 v[12:15], v[156:159], v[222:225], v[12:15]
	v_mfma_f32_16x16x32_bf16 v[8:11], v[198:201], v[222:225], v[8:11]
	v_mfma_f32_16x16x32_bf16 v[4:7], v[156:159], v[230:233], v[4:7]
	v_mfma_f32_16x16x32_bf16 v[0:3], v[198:201], v[230:233], v[0:3]
	s_setprio 0
	s_barrier
	s_add_i32 s37, s37, s3
	v_lshl_add_u64 v[190:191], v[236:237], 0, s[16:17]
	s_mov_b32 m0, s37
	ds_read_b128 v[202:205], v195 offset:49152
	ds_read_b128 v[206:209], v195 offset:50176
	ds_read_b128 v[210:213], v195 offset:51200
	ds_read_b128 v[214:217], v195 offset:52224
	ds_read_b128 v[218:221], v195 offset:53248
	ds_read_b128 v[222:225], v195 offset:54272
	ds_read_b128 v[226:229], v195 offset:55296
	ds_read_b128 v[230:233], v195 offset:56320
	global_load_lds_dwordx4 v[190:191], off
	v_lshl_add_u64 v[190:191], v[238:239], 0, s[16:17]
	s_add_i32 m0, s37, 0x2000
	s_add_i32 s37, s41, s3
	global_load_lds_dwordx4 v[190:191], off
	v_lshl_add_u64 v[190:191], v[234:235], 0, s[18:19]
	v_lshl_add_u64 v[234:235], v[190:191], 0, v[162:163]
	s_mov_b32 m0, s37
	v_lshl_add_u64 v[190:191], v[190:191], 0, v[164:165]
	global_load_lds_dwordx4 v[234:235], off
	s_add_i32 m0, s37, 0x2000
	s_nop 0
	global_load_lds_dwordx4 v[190:191], off
	v_lshl_add_u64 v[190:191], v[240:241], 0, s[16:17]
	s_mov_b32 m0, s52
	s_nop 0
	global_load_lds_dwordx4 v[190:191], off
	v_lshl_add_u64 v[190:191], v[242:243], 0, s[16:17]
	s_mov_b32 m0, s53
	s_nop 0
	global_load_lds_dwordx4 v[190:191], off
	s_waitcnt vmcnt(8)
	s_waitcnt lgkmcnt(0)
	s_barrier
	s_setprio 1
	s_waitcnt lgkmcnt(0)
	v_mfma_f32_16x16x32_bf16 v[124:127], v[136:139], v[202:205], v[124:127]
	v_mfma_f32_16x16x32_bf16 v[120:123], v[144:147], v[202:205], v[120:123]
	v_mfma_f32_16x16x32_bf16 v[116:119], v[136:139], v[210:213], v[116:119]
	v_mfma_f32_16x16x32_bf16 v[112:115], v[144:147], v[210:213], v[112:115]
	v_mfma_f32_16x16x32_bf16 v[108:111], v[136:139], v[218:221], v[108:111]
	v_mfma_f32_16x16x32_bf16 v[104:107], v[144:147], v[218:221], v[104:107]
	v_mfma_f32_16x16x32_bf16 v[100:103], v[136:139], v[226:229], v[100:103]
	v_mfma_f32_16x16x32_bf16 v[96:99], v[144:147], v[226:229], v[96:99]
	s_setprio 0
	s_setprio 1
	v_mfma_f32_16x16x32_bf16 v[124:127], v[140:143], v[206:209], v[124:127]
	v_mfma_f32_16x16x32_bf16 v[120:123], v[148:151], v[206:209], v[120:123]
	v_mfma_f32_16x16x32_bf16 v[116:119], v[140:143], v[214:217], v[116:119]
	v_mfma_f32_16x16x32_bf16 v[112:115], v[148:151], v[214:217], v[112:115]
	v_mfma_f32_16x16x32_bf16 v[108:111], v[140:143], v[222:225], v[108:111]
	v_mfma_f32_16x16x32_bf16 v[104:107], v[148:151], v[222:225], v[104:107]
	v_mfma_f32_16x16x32_bf16 v[100:103], v[140:143], v[230:233], v[100:103]
	v_mfma_f32_16x16x32_bf16 v[96:99], v[148:151], v[230:233], v[96:99]
	s_setprio 0
	s_setprio 1
	v_mfma_f32_16x16x32_bf16 v[92:95], v[152:155], v[202:205], v[92:95]
	v_mfma_f32_16x16x32_bf16 v[88:91], v[186:189], v[202:205], v[88:91]
	v_mfma_f32_16x16x32_bf16 v[84:87], v[152:155], v[210:213], v[84:87]
	v_mfma_f32_16x16x32_bf16 v[80:83], v[186:189], v[210:213], v[80:83]
	v_mfma_f32_16x16x32_bf16 v[76:79], v[152:155], v[218:221], v[76:79]
	v_mfma_f32_16x16x32_bf16 v[72:75], v[186:189], v[218:221], v[72:75]
	v_mfma_f32_16x16x32_bf16 v[68:71], v[152:155], v[226:229], v[68:71]
	v_mfma_f32_16x16x32_bf16 v[64:67], v[186:189], v[226:229], v[64:67]
	s_setprio 0
	s_setprio 1
	v_mfma_f32_16x16x32_bf16 v[92:95], v[156:159], v[206:209], v[92:95]
	v_mfma_f32_16x16x32_bf16 v[88:91], v[198:201], v[206:209], v[88:91]
	v_mfma_f32_16x16x32_bf16 v[84:87], v[156:159], v[214:217], v[84:87]
	v_mfma_f32_16x16x32_bf16 v[80:83], v[198:201], v[214:217], v[80:83]
	v_mfma_f32_16x16x32_bf16 v[76:79], v[156:159], v[222:225], v[76:79]
	v_mfma_f32_16x16x32_bf16 v[72:75], v[198:201], v[222:225], v[72:75]
	v_mfma_f32_16x16x32_bf16 v[68:71], v[156:159], v[230:233], v[68:71]
	v_mfma_f32_16x16x32_bf16 v[64:67], v[198:201], v[230:233], v[64:67]
	s_setprio 0
	s_barrier
	v_lshl_add_u64 v[132:133], v[132:133], 0, s[24:25]
	s_cmp_ge_i32 s35, s5
	v_lshl_add_u64 v[134:135], v[134:135], 0, s[24:25]
	s_cbranch_scc0 .LBB0_1383
